# K-loop load segments: LDS fragment reads issued first after each barrier, loop counter and exit compare moved ahead of the block-closing barrier
# baseline (speedup 1.0000x reference)
; #define PG8_STAGE(bufoff, gbase, voff) do { _Pragma("unroll") for (int _i = 0; _i < 2; ++_i) \
;         __builtin_amdgcn_global_load_lds((const unsigned*)((const char*)(gbase) + (voff)[_i]), (PG8_LAS unsigned*)(lds + (bufoff) + ldsw + _i * 8192), 16, 0, 0); } while (0)
; #define PG8_LDA(dst, b, h) do { _Pragma("unroll") for (int m = 0; m < 4; ++m) _Pragma("unroll") for (int k = 0; k < 2; ++k) dst[m][k] = *(const PG8_LAS bf16x8*)(lds + PG8_SA(b, h) + aoff + m * 2048 + k * 1024); } while (0)
; #define PG8_LDB(dst, b, h) do { _Pragma("unroll") for (int n = 0; n < 2; ++n) _Pragma("unroll") for (int k = 0; k < 2; ++k) dst[n][k] = *(const PG8_LAS bf16x8*)(lds + PG8_SB(b, h) + boff + n * 2048 + k * 1024); } while (0)
; #define PG8_MMA(ai, bj, At, Bt) do { __builtin_amdgcn_s_setprio(1); _Pragma("unroll") for (int m = 0; m < 4; ++m) _Pragma("unroll") for (int n = 0; n < 2; ++n) _Pragma("unroll") for (int k = 0; k < 2; ++k) \
;         acc[ai][bj][m][n] = __builtin_amdgcn_mfma_f32_16x16x32_bf16(Bt[n][k], At[m][k], acc[ai][bj][m][n], 0, 0, 0); __builtin_amdgcn_s_setprio(0); } while (0)
; #define PG8_WAIT_V(n) asm volatile("s_waitcnt vmcnt(" #n ")" ::: "memory")
; #define PG8_WAIT_VN(n) asm volatile("s_waitcnt vmcnt(%0)" :: "n"(n) : "memory")
; #define PG8_WAIT_L(n) asm volatile("s_waitcnt lgkmcnt(" #n ")" ::: "memory")
; #define PG8_BAR __builtin_amdgcn_s_barrier()
; #define PG8_SCHED __builtin_amdgcn_sched_barrier(0)
; template <class Epi, class Sched, bool ALIGN_EPI = false, bool SP2 = false>
; __device__ __forceinline__ void gemm_phase(PG8_LAS unsigned char* lds, const Gemm g, const Sched& S, const Epi& E, const int wave_id) {
;     ...
;             PG8_WAIT_VN(8 + Epi::NS); if (strict) PG8_WAIT_V(8); PG8_WAIT_L(0); PG8_BAR; PG8_MMA(1, 0, At, B0); PG8_MMA(1, 1, At, B1); PG8_BAR; PG8_SCHED;
;             PG8_LDB(B0, 1, 0); PG8_LDB(B1, 1, 1); PG8_SCHED; PG8_LDA(At, 1, 0); PG8_STAGE(PG8_SA(0, 1), a2 + hstep, voffA);
;             PG8_WAIT_V(8); PG8_WAIT_L(0); PG8_BAR; PG8_MMA(0, 0, At, B0); PG8_MMA(0, 1, At, B1); PG8_BAR; PG8_SCHED;
.LBB0_157:
	s_waitcnt lgkmcnt(0)
	s_barrier
	s_setprio 1
	s_waitcnt lgkmcnt(0)
	v_mfma_f32_16x16x32_bf16 v[62:65], v[146:149], v[186:189], v[62:65]
	v_mfma_f32_16x16x32_bf16 v[58:61], v[154:157], v[186:189], v[58:61]
	v_mfma_f32_16x16x32_bf16 v[54:57], v[146:149], v[178:181], v[54:57]
	v_mfma_f32_16x16x32_bf16 v[50:53], v[154:157], v[178:181], v[50:53]
	v_mfma_f32_16x16x32_bf16 v[30:33], v[146:149], v[170:173], v[30:33]
	v_mfma_f32_16x16x32_bf16 v[26:29], v[154:157], v[170:173], v[26:29]
	v_mfma_f32_16x16x32_bf16 v[22:25], v[146:149], v[162:165], v[22:25]
	v_mfma_f32_16x16x32_bf16 v[18:21], v[154:157], v[162:165], v[18:21]
	v_mfma_f32_16x16x32_bf16 v[62:65], v[150:153], v[190:193], v[62:65]
	v_mfma_f32_16x16x32_bf16 v[58:61], v[158:161], v[190:193], v[58:61]
	v_mfma_f32_16x16x32_bf16 v[54:57], v[150:153], v[182:185], v[54:57]
	v_mfma_f32_16x16x32_bf16 v[50:53], v[158:161], v[182:185], v[50:53]
	v_mfma_f32_16x16x32_bf16 v[30:33], v[150:153], v[174:177], v[30:33]
	v_mfma_f32_16x16x32_bf16 v[26:29], v[158:161], v[174:177], v[26:29]
	v_mfma_f32_16x16x32_bf16 v[22:25], v[150:153], v[166:169], v[22:25]
	v_mfma_f32_16x16x32_bf16 v[18:21], v[158:161], v[166:169], v[18:21]
	s_setprio 0
	s_setprio 1
	v_mfma_f32_16x16x32_bf16 v[46:49], v[130:133], v[186:189], v[46:49]
	v_mfma_f32_16x16x32_bf16 v[42:45], v[138:141], v[186:189], v[42:45]
	v_mfma_f32_16x16x32_bf16 v[38:41], v[130:133], v[178:181], v[38:41]
	v_mfma_f32_16x16x32_bf16 v[34:37], v[138:141], v[178:181], v[34:37]
	v_mfma_f32_16x16x32_bf16 v[14:17], v[130:133], v[170:173], v[14:17]
	v_mfma_f32_16x16x32_bf16 v[10:13], v[138:141], v[170:173], v[10:13]
	v_mfma_f32_16x16x32_bf16 v[6:9], v[130:133], v[162:165], v[6:9]
	v_mfma_f32_16x16x32_bf16 v[2:5], v[138:141], v[162:165], v[2:5]
	v_mfma_f32_16x16x32_bf16 v[46:49], v[134:137], v[190:193], v[46:49]
	v_mfma_f32_16x16x32_bf16 v[42:45], v[142:145], v[190:193], v[42:45]
	v_mfma_f32_16x16x32_bf16 v[38:41], v[134:137], v[182:185], v[38:41]
	v_mfma_f32_16x16x32_bf16 v[34:37], v[142:145], v[182:185], v[34:37]
	v_mfma_f32_16x16x32_bf16 v[14:17], v[134:137], v[174:177], v[14:17]
	v_mfma_f32_16x16x32_bf16 v[10:13], v[142:145], v[174:177], v[10:13]
	v_mfma_f32_16x16x32_bf16 v[6:9], v[134:137], v[166:169], v[6:9]
	v_mfma_f32_16x16x32_bf16 v[2:5], v[142:145], v[166:169], v[2:5]
	s_setprio 0
	s_barrier
	ds_read_b128 v[162:165], v249 offset:32768
	ds_read_b128 v[166:169], v249 offset:33792
	ds_read_b128 v[170:173], v249 offset:34816
	ds_read_b128 v[174:177], v249 offset:35840
	ds_read_b128 v[178:181], v249 offset:36864
	ds_read_b128 v[182:185], v249 offset:37888
	ds_read_b128 v[186:189], v249 offset:38912
	ds_read_b128 v[190:193], v249 offset:39936
	s_add_i32 s28, 0, 0x18000
	s_add_i32 s29, 0, 0x1c000
	v_add_u32_e32 v142, s28, v246
	v_add_u32_e32 v158, s29, v246
	ds_read_b128 v[130:133], v142
	ds_read_b128 v[134:137], v142 offset:1024
	ds_read_b128 v[138:141], v142 offset:2048
	ds_read_b128 v[142:145], v142 offset:3072
	ds_read_b128 v[146:149], v158
	ds_read_b128 v[150:153], v158 offset:1024
	ds_read_b128 v[154:157], v158 offset:2048
	ds_read_b128 v[158:161], v158 offset:3072
	s_add_u32 s26, s26, 0x40000
	s_addc_u32 s27, s27, 0
	s_mov_b32 m0, s52
	v_lshl_add_u64 v[194:195], s[26:27], 0, v[210:211]
	global_load_lds_dwordx4 v[194:195], off
	v_lshl_add_u64 v[194:195], s[26:27], 0, v[214:215]
	s_mov_b32 m0, s54
	s_nop 0
	global_load_lds_dwordx4 v[194:195], off
	s_waitcnt vmcnt(18)
	s_cmp_eq_u32 s100, 0
	s_cbranch_scc1 .Lthird_wait_relaxed_6
	s_waitcnt vmcnt(8)
; #define PG8_STAGE(bufoff, gbase, voff) do { _Pragma("unroll") for (int _i = 0; _i < 2; ++_i) \
;         __builtin_amdgcn_global_load_lds((const unsigned*)((const char*)(gbase) + (voff)[_i]), (PG8_LAS unsigned*)(lds + (bufoff) + ldsw + _i * 8192), 16, 0, 0); } while (0)
; #define PG8_LDA(dst, b, h) do { _Pragma("unroll") for (int m = 0; m < 4; ++m) _Pragma("unroll") for (int k = 0; k < 2; ++k) dst[m][k] = *(const PG8_LAS bf16x8*)(lds + PG8_SA(b, h) + aoff + m * 2048 + k * 1024); } while (0)
; #define PG8_LDB(dst, b, h) do { _Pragma("unroll") for (int n = 0; n < 2; ++n) _Pragma("unroll") for (int k = 0; k < 2; ++k) dst[n][k] = *(const PG8_LAS bf16x8*)(lds + PG8_SB(b, h) + boff + n * 2048 + k * 1024); } while (0)
; #define PG8_MMA(ai, bj, At, Bt) do { __builtin_amdgcn_s_setprio(1); _Pragma("unroll") for (int m = 0; m < 4; ++m) _Pragma("unroll") for (int n = 0; n < 2; ++n) _Pragma("unroll") for (int k = 0; k < 2; ++k) \
;         acc[ai][bj][m][n] = __builtin_amdgcn_mfma_f32_16x16x32_bf16(Bt[n][k], At[m][k], acc[ai][bj][m][n], 0, 0, 0); __builtin_amdgcn_s_setprio(0); } while (0)
; #define PG8_WAIT_V(n) asm volatile("s_waitcnt vmcnt(" #n ")" ::: "memory")
; #define PG8_WAIT_L(n) asm volatile("s_waitcnt lgkmcnt(" #n ")" ::: "memory")
; #define PG8_BAR __builtin_amdgcn_s_barrier()
; #define PG8_SCHED __builtin_amdgcn_sched_barrier(0)
; template <class Epi, class Sched, bool ALIGN_EPI = false, bool SP2 = false>
; __device__ __forceinline__ void gemm_phase(PG8_LAS unsigned char* lds, const Gemm g, const Sched& S, const Epi& E, const int wave_id) {
;     ...
;         for (int t = 0; t < nt; t += 2) {
;     ...
;             PG8_LDB(B0, 1, 0); PG8_LDB(B1, 1, 1); PG8_SCHED; PG8_LDA(At, 1, 0); PG8_STAGE(PG8_SA(0, 1), a2 + hstep, voffA);
;             PG8_WAIT_V(8); PG8_WAIT_L(0); PG8_BAR; PG8_MMA(0, 0, At, B0); PG8_MMA(0, 1, At, B1); PG8_BAR; PG8_SCHED;
;             PG8_LDA(At, 1, 1); PG8_STAGE(PG8_SB(1, 0), b3, voffB); PG8_STAGE(PG8_SB(1, 1), b3 + hstep, voffB); PG8_STAGE(PG8_SA(1, 0), a3, voffA);
;             PG8_WAIT_V(8); PG8_WAIT_L(0); PG8_BAR; PG8_MMA(1, 0, At, B0); PG8_MMA(1, 1, At, B1); PG8_BAR; PG8_SCHED;
.Lthird_wait_relaxed_6:
	s_waitcnt lgkmcnt(0)
	s_barrier
	s_setprio 1
	s_waitcnt lgkmcnt(0)
	v_mfma_f32_16x16x32_bf16 v[126:129], v[130:133], v[162:165], v[126:129]
	v_mfma_f32_16x16x32_bf16 v[122:125], v[138:141], v[162:165], v[122:125]
	v_mfma_f32_16x16x32_bf16 v[118:121], v[130:133], v[170:173], v[118:121]
	v_mfma_f32_16x16x32_bf16 v[114:117], v[138:141], v[170:173], v[114:117]
	v_mfma_f32_16x16x32_bf16 v[94:97], v[130:133], v[178:181], v[94:97]
	v_mfma_f32_16x16x32_bf16 v[90:93], v[138:141], v[178:181], v[90:93]
	v_mfma_f32_16x16x32_bf16 v[86:89], v[130:133], v[186:189], v[86:89]
	v_mfma_f32_16x16x32_bf16 v[82:85], v[138:141], v[186:189], v[82:85]
	v_mfma_f32_16x16x32_bf16 v[126:129], v[134:137], v[166:169], v[126:129]
	v_mfma_f32_16x16x32_bf16 v[122:125], v[142:145], v[166:169], v[122:125]
	v_mfma_f32_16x16x32_bf16 v[118:121], v[134:137], v[174:177], v[118:121]
	v_mfma_f32_16x16x32_bf16 v[114:117], v[142:145], v[174:177], v[114:117]
	v_mfma_f32_16x16x32_bf16 v[94:97], v[134:137], v[182:185], v[94:97]
	v_mfma_f32_16x16x32_bf16 v[90:93], v[142:145], v[182:185], v[90:93]
	v_mfma_f32_16x16x32_bf16 v[86:89], v[134:137], v[190:193], v[86:89]
	v_mfma_f32_16x16x32_bf16 v[82:85], v[142:145], v[190:193], v[82:85]
	s_setprio 0
	s_setprio 1
	v_mfma_f32_16x16x32_bf16 v[110:113], v[146:149], v[162:165], v[110:113]
	v_mfma_f32_16x16x32_bf16 v[106:109], v[154:157], v[162:165], v[106:109]
	v_mfma_f32_16x16x32_bf16 v[102:105], v[146:149], v[170:173], v[102:105]
	v_mfma_f32_16x16x32_bf16 v[98:101], v[154:157], v[170:173], v[98:101]
	v_mfma_f32_16x16x32_bf16 v[78:81], v[146:149], v[178:181], v[78:81]
	v_mfma_f32_16x16x32_bf16 v[74:77], v[154:157], v[178:181], v[74:77]
	v_mfma_f32_16x16x32_bf16 v[70:73], v[146:149], v[186:189], v[70:73]
	v_mfma_f32_16x16x32_bf16 v[66:69], v[154:157], v[186:189], v[66:69]
	v_mfma_f32_16x16x32_bf16 v[110:113], v[150:153], v[166:169], v[110:113]
	v_mfma_f32_16x16x32_bf16 v[106:109], v[158:161], v[166:169], v[106:109]
	v_mfma_f32_16x16x32_bf16 v[102:105], v[150:153], v[174:177], v[102:105]
	v_mfma_f32_16x16x32_bf16 v[98:101], v[158:161], v[174:177], v[98:101]
	v_mfma_f32_16x16x32_bf16 v[78:81], v[150:153], v[182:185], v[78:81]
	v_mfma_f32_16x16x32_bf16 v[74:77], v[158:161], v[182:185], v[74:77]
	v_mfma_f32_16x16x32_bf16 v[70:73], v[150:153], v[190:193], v[70:73]
	v_mfma_f32_16x16x32_bf16 v[66:69], v[158:161], v[190:193], v[66:69]
	s_setprio 0
	s_barrier
	ds_read_b128 v[162:165], v249 offset:49152
	ds_read_b128 v[166:169], v249 offset:50176
	ds_read_b128 v[170:173], v249 offset:51200
	ds_read_b128 v[174:177], v249 offset:52224
	ds_read_b128 v[178:181], v249 offset:53248
	ds_read_b128 v[182:185], v249 offset:54272
	ds_read_b128 v[186:189], v249 offset:55296
	ds_read_b128 v[190:193], v249 offset:56320
	s_add_i32 s26, s28, s40
	v_lshl_add_u64 v[194:195], v[232:233], 0, s[64:65]
	s_mov_b32 m0, s26
	s_nop 0
	global_load_lds_dwordx4 v[194:195], off
	s_add_i32 m0, s26, 0x2000
	s_add_u32 s24, s24, 0x40080
	v_lshl_add_u64 v[194:195], v[230:231], 0, s[64:65]
	s_addc_u32 s25, s25, 0
	s_add_i32 s26, s29, s40
	global_load_lds_dwordx4 v[194:195], off
	v_lshl_add_u64 v[194:195], s[24:25], 0, v[212:213]
	s_mov_b32 m0, s26
	s_nop 0
	global_load_lds_dwordx4 v[194:195], off
	v_lshl_add_u64 v[194:195], s[24:25], 0, v[216:217]
	s_add_i32 m0, s26, 0x2000
	s_nop 0
	global_load_lds_dwordx4 v[194:195], off
	v_lshl_add_u64 v[194:195], v[226:227], 0, s[64:65]
	s_mov_b32 m0, s57
	s_nop 0
	global_load_lds_dwordx4 v[194:195], off
	v_lshl_add_u64 v[194:195], v[228:229], 0, s[64:65]
	s_mov_b32 m0, s62
	s_nop 0
	global_load_lds_dwordx4 v[194:195], off
	s_waitcnt vmcnt(8)
	s_waitcnt lgkmcnt(0)
	s_barrier
	s_setprio 1
	s_waitcnt lgkmcnt(0)
	v_mfma_f32_16x16x32_bf16 v[62:65], v[130:133], v[162:165], v[62:65]
	v_mfma_f32_16x16x32_bf16 v[58:61], v[138:141], v[162:165], v[58:61]
	v_mfma_f32_16x16x32_bf16 v[54:57], v[130:133], v[170:173], v[54:57]
	v_mfma_f32_16x16x32_bf16 v[50:53], v[138:141], v[170:173], v[50:53]
	v_mfma_f32_16x16x32_bf16 v[30:33], v[130:133], v[178:181], v[30:33]
	v_mfma_f32_16x16x32_bf16 v[26:29], v[138:141], v[178:181], v[26:29]
	v_mfma_f32_16x16x32_bf16 v[22:25], v[130:133], v[186:189], v[22:25]
	v_mfma_f32_16x16x32_bf16 v[18:21], v[138:141], v[186:189], v[18:21]
	v_mfma_f32_16x16x32_bf16 v[62:65], v[134:137], v[166:169], v[62:65]
	v_mfma_f32_16x16x32_bf16 v[58:61], v[142:145], v[166:169], v[58:61]
	v_mfma_f32_16x16x32_bf16 v[54:57], v[134:137], v[174:177], v[54:57]
	v_mfma_f32_16x16x32_bf16 v[50:53], v[142:145], v[174:177], v[50:53]
	v_mfma_f32_16x16x32_bf16 v[30:33], v[134:137], v[182:185], v[30:33]
	v_mfma_f32_16x16x32_bf16 v[26:29], v[142:145], v[182:185], v[26:29]
	v_mfma_f32_16x16x32_bf16 v[22:25], v[134:137], v[190:193], v[22:25]
	v_mfma_f32_16x16x32_bf16 v[18:21], v[142:145], v[190:193], v[18:21]
	s_setprio 0
	s_setprio 1
	v_mfma_f32_16x16x32_bf16 v[46:49], v[146:149], v[162:165], v[46:49]
	v_mfma_f32_16x16x32_bf16 v[42:45], v[154:157], v[162:165], v[42:45]
	v_mfma_f32_16x16x32_bf16 v[38:41], v[146:149], v[170:173], v[38:41]
	v_mfma_f32_16x16x32_bf16 v[34:37], v[154:157], v[170:173], v[34:37]
	v_mfma_f32_16x16x32_bf16 v[14:17], v[146:149], v[178:181], v[14:17]
	v_mfma_f32_16x16x32_bf16 v[10:13], v[154:157], v[178:181], v[10:13]
	v_mfma_f32_16x16x32_bf16 v[6:9], v[146:149], v[186:189], v[6:9]
	v_mfma_f32_16x16x32_bf16 v[2:5], v[154:157], v[186:189], v[2:5]
	v_mfma_f32_16x16x32_bf16 v[46:49], v[150:153], v[166:169], v[46:49]
	v_mfma_f32_16x16x32_bf16 v[42:45], v[158:161], v[166:169], v[42:45]
	v_mfma_f32_16x16x32_bf16 v[38:41], v[150:153], v[174:177], v[38:41]
	v_mfma_f32_16x16x32_bf16 v[34:37], v[158:161], v[174:177], v[34:37]
	v_mfma_f32_16x16x32_bf16 v[14:17], v[150:153], v[182:185], v[14:17]
	v_mfma_f32_16x16x32_bf16 v[10:13], v[158:161], v[182:185], v[10:13]
	v_mfma_f32_16x16x32_bf16 v[6:9], v[150:153], v[190:193], v[6:9]
	v_mfma_f32_16x16x32_bf16 v[2:5], v[158:161], v[190:193], v[2:5]
	s_setprio 0
	s_add_i32 s76, s76, 2
	s_add_u32 s22, s22, 0x100
	s_addc_u32 s23, s23, 0
	s_cmp_gt_u32 s76, 13
	s_barrier
	s_cbranch_scc1 .LBB0_162

; #define PG8_STAGE(bufoff, gbase, voff) do { _Pragma("unroll") for (int _i = 0; _i < 2; ++_i) \
;         __builtin_amdgcn_global_load_lds((const unsigned*)((const char*)(gbase) + (voff)[_i]), (PG8_LAS unsigned*)(lds + (bufoff) + ldsw + _i * 8192), 16, 0, 0); } while (0)
; #define PG8_LDA(dst, b, h) do { _Pragma("unroll") for (int m = 0; m < 4; ++m) _Pragma("unroll") for (int k = 0; k < 2; ++k) dst[m][k] = *(const PG8_LAS bf16x8*)(lds + PG8_SA(b, h) + aoff + m * 2048 + k * 1024); } while (0)
; #define PG8_LDB(dst, b, h) do { _Pragma("unroll") for (int n = 0; n < 2; ++n) _Pragma("unroll") for (int k = 0; k < 2; ++k) dst[n][k] = *(const PG8_LAS bf16x8*)(lds + PG8_SB(b, h) + boff + n * 2048 + k * 1024); } while (0)
; #define PG8_MMA(ai, bj, At, Bt) do { __builtin_amdgcn_s_setprio(1); _Pragma("unroll") for (int m = 0; m < 4; ++m) _Pragma("unroll") for (int n = 0; n < 2; ++n) _Pragma("unroll") for (int k = 0; k < 2; ++k) \
;         acc[ai][bj][m][n] = __builtin_amdgcn_mfma_f32_16x16x32_bf16(Bt[n][k], At[m][k], acc[ai][bj][m][n], 0, 0, 0); __builtin_amdgcn_s_setprio(0); } while (0)
; #define PG8_WAIT_V(n) asm volatile("s_waitcnt vmcnt(" #n ")" ::: "memory")
; #define PG8_WAIT_VN(n) asm volatile("s_waitcnt vmcnt(%0)" :: "n"(n) : "memory")
; template <class Epi, class Sched, bool ALIGN_EPI = false, bool SP2 = false>
; __device__ __forceinline__ void gemm_phase(PG8_LAS unsigned char* lds, const Gemm g, const Sched& S, const Epi& E, const int wave_id) {
;     ...
;             const bool last = (t == nt - 2);
;             const char* a1 = cA + (size_t)(t + 1) * kstep;
;             const char* a2 = last ? nA : cA + (size_t)(t + 2) * kstep; const char* b2 = last ? nB : cB + (size_t)(t + 2) * kstep;
;             const char* a3 = a2 + kstep; const char* b3 = b2 + kstep;
;     ...
;             PG8_LDB(B0, 0, 0); PG8_LDB(B1, 0, 1); PG8_SCHED; PG8_LDA(At, 0, 0); PG8_STAGE(PG8_SA(1, 1), a1 + hstep, voffA);
;             PG8_WAIT_VN(8 + Epi::NS); if (strict) PG8_WAIT_V(8); PG8_WAIT_L(0); PG8_BAR; PG8_MMA(0, 0, At, B0); PG8_MMA(0, 1, At, B1); PG8_BAR; PG8_SCHED;
;             PG8_LDA(At, 0, 1); PG8_STAGE(PG8_SB(0, 0), b2, voffB); PG8_STAGE(PG8_SB(0, 1), b2 + hstep, voffB); PG8_STAGE(PG8_SA(0, 0), a2, voffA);
;             PG8_WAIT_VN(8 + Epi::NS); if (strict) PG8_WAIT_V(8); PG8_WAIT_L(0); PG8_BAR; PG8_MMA(1, 0, At, B0); PG8_MMA(1, 1, At, B1); PG8_BAR; PG8_SCHED;
.LBB0_160:
	s_add_u32 s24, s20, s22
	s_addc_u32 s25, s21, s23
	s_add_u32 s24, s24, 0x100
	s_addc_u32 s25, s25, 0
	s_add_u32 s53, s74, s22
	s_addc_u32 s78, s75, s23
	s_waitcnt lgkmcnt(0)
	s_cmpk_eq_i32 s22, 0x700
	s_cselect_b32 s27, s13, s25
	s_cselect_b32 s26, s68, s24
	s_cselect_b32 s25, s11, s78
	s_cselect_b32 s24, s69, s53
	s_barrier
	s_setprio 1
	s_waitcnt lgkmcnt(0)
	v_mfma_f32_16x16x32_bf16 v[126:129], v[146:149], v[186:189], v[126:129]
	v_mfma_f32_16x16x32_bf16 v[122:125], v[154:157], v[186:189], v[122:125]
	v_mfma_f32_16x16x32_bf16 v[118:121], v[146:149], v[178:181], v[118:121]
	v_mfma_f32_16x16x32_bf16 v[114:117], v[154:157], v[178:181], v[114:117]
	v_mfma_f32_16x16x32_bf16 v[94:97], v[146:149], v[170:173], v[94:97]
	v_mfma_f32_16x16x32_bf16 v[90:93], v[154:157], v[170:173], v[90:93]
	v_mfma_f32_16x16x32_bf16 v[86:89], v[146:149], v[162:165], v[86:89]
	v_mfma_f32_16x16x32_bf16 v[82:85], v[154:157], v[162:165], v[82:85]
	v_mfma_f32_16x16x32_bf16 v[126:129], v[150:153], v[190:193], v[126:129]
	v_mfma_f32_16x16x32_bf16 v[122:125], v[158:161], v[190:193], v[122:125]
	v_mfma_f32_16x16x32_bf16 v[118:121], v[150:153], v[182:185], v[118:121]
	v_mfma_f32_16x16x32_bf16 v[114:117], v[158:161], v[182:185], v[114:117]
	v_mfma_f32_16x16x32_bf16 v[94:97], v[150:153], v[174:177], v[94:97]
	v_mfma_f32_16x16x32_bf16 v[90:93], v[158:161], v[174:177], v[90:93]
	v_mfma_f32_16x16x32_bf16 v[86:89], v[150:153], v[166:169], v[86:89]
	v_mfma_f32_16x16x32_bf16 v[82:85], v[158:161], v[166:169], v[82:85]
	s_setprio 0
	s_setprio 1
	v_mfma_f32_16x16x32_bf16 v[110:113], v[130:133], v[186:189], v[110:113]
	v_mfma_f32_16x16x32_bf16 v[106:109], v[138:141], v[186:189], v[106:109]
	v_mfma_f32_16x16x32_bf16 v[102:105], v[130:133], v[178:181], v[102:105]
	v_mfma_f32_16x16x32_bf16 v[98:101], v[138:141], v[178:181], v[98:101]
	v_mfma_f32_16x16x32_bf16 v[78:81], v[130:133], v[170:173], v[78:81]
	v_mfma_f32_16x16x32_bf16 v[74:77], v[138:141], v[170:173], v[74:77]
	v_mfma_f32_16x16x32_bf16 v[70:73], v[130:133], v[162:165], v[70:73]
	v_mfma_f32_16x16x32_bf16 v[66:69], v[138:141], v[162:165], v[66:69]
	v_mfma_f32_16x16x32_bf16 v[110:113], v[134:137], v[190:193], v[110:113]
	v_mfma_f32_16x16x32_bf16 v[106:109], v[142:145], v[190:193], v[106:109]
	v_mfma_f32_16x16x32_bf16 v[102:105], v[134:137], v[182:185], v[102:105]
	v_mfma_f32_16x16x32_bf16 v[98:101], v[142:145], v[182:185], v[98:101]
	v_mfma_f32_16x16x32_bf16 v[78:81], v[134:137], v[174:177], v[78:81]
	v_mfma_f32_16x16x32_bf16 v[74:77], v[142:145], v[174:177], v[74:77]
	v_mfma_f32_16x16x32_bf16 v[70:73], v[134:137], v[166:169], v[70:73]
	v_mfma_f32_16x16x32_bf16 v[66:69], v[142:145], v[166:169], v[66:69]
	s_setprio 0
	s_barrier
	ds_read_b128 v[186:189], v249 offset:16384
	ds_read_b128 v[190:193], v249 offset:17408
	ds_read_b128 v[178:181], v249 offset:18432
	ds_read_b128 v[182:185], v249 offset:19456
	ds_read_b128 v[170:173], v249 offset:20480
	ds_read_b128 v[174:177], v249 offset:21504
	ds_read_b128 v[162:165], v249 offset:22528
	ds_read_b128 v[166:169], v249 offset:23552
	s_mov_b32 m0, s42
	v_lshl_add_u64 v[232:233], s[24:25], 0, v[212:213]
	s_add_u32 s90, s24, 0x40000
	global_load_lds_dwordx4 v[232:233], off
	v_lshl_add_u64 v[230:231], s[24:25], 0, v[216:217]
	s_mov_b32 m0, s43
	s_addc_u32 s91, s25, 0
	global_load_lds_dwordx4 v[230:231], off
	v_lshl_add_u64 v[194:195], s[90:91], 0, v[212:213]
	s_mov_b32 m0, s49
	v_lshl_add_u64 v[226:227], s[26:27], 0, v[210:211]
	global_load_lds_dwordx4 v[194:195], off
	v_lshl_add_u64 v[194:195], s[90:91], 0, v[216:217]
	s_mov_b32 m0, s50
	v_lshl_add_u64 v[228:229], s[26:27], 0, v[214:215]
	global_load_lds_dwordx4 v[194:195], off
	s_mov_b32 m0, s41
	s_andn2_b64 vcc, exec, s[28:29]
	global_load_lds_dwordx4 v[226:227], off
	s_mov_b32 m0, s51
	s_nop 0
	global_load_lds_dwordx4 v[228:229], off
	s_waitcnt vmcnt(16)
	s_cbranch_vccnz .LBB0_157
	s_waitcnt vmcnt(8)
	s_branch .LBB0_157

; #define PG8_STAGE(bufoff, gbase, voff) do { _Pragma("unroll") for (int _i = 0; _i < 2; ++_i) \
;         __builtin_amdgcn_global_load_lds((const unsigned*)((const char*)(gbase) + (voff)[_i]), (PG8_LAS unsigned*)(lds + (bufoff) + ldsw + _i * 8192), 16, 0, 0); } while (0)
; #define PG8_LDA(dst, b, h) do { _Pragma("unroll") for (int m = 0; m < 4; ++m) _Pragma("unroll") for (int k = 0; k < 2; ++k) dst[m][k] = *(const PG8_LAS bf16x8*)(lds + PG8_SA(b, h) + aoff + m * 2048 + k * 1024); } while (0)
; #define PG8_LDB(dst, b, h) do { _Pragma("unroll") for (int n = 0; n < 2; ++n) _Pragma("unroll") for (int k = 0; k < 2; ++k) dst[n][k] = *(const PG8_LAS bf16x8*)(lds + PG8_SB(b, h) + boff + n * 2048 + k * 1024); } while (0)
; #define PG8_MMA(ai, bj, At, Bt) do { __builtin_amdgcn_s_setprio(1); _Pragma("unroll") for (int m = 0; m < 4; ++m) _Pragma("unroll") for (int n = 0; n < 2; ++n) _Pragma("unroll") for (int k = 0; k < 2; ++k) \
;         acc[ai][bj][m][n] = __builtin_amdgcn_mfma_f32_16x16x32_bf16(Bt[n][k], At[m][k], acc[ai][bj][m][n], 0, 0, 0); __builtin_amdgcn_s_setprio(0); } while (0)
; #define PG8_WAIT_V(n) asm volatile("s_waitcnt vmcnt(" #n ")" ::: "memory")
; #define PG8_WAIT_VN(n) asm volatile("s_waitcnt vmcnt(%0)" :: "n"(n) : "memory")
; #define PG8_WAIT_L(n) asm volatile("s_waitcnt lgkmcnt(" #n ")" ::: "memory")
; #define PG8_BAR __builtin_amdgcn_s_barrier()
; #define PG8_SCHED __builtin_amdgcn_sched_barrier(0)
; template <class Epi, class Sched, bool ALIGN_EPI = false, bool SP2 = false>
; __device__ __forceinline__ void gemm_phase(PG8_LAS unsigned char* lds, const Gemm g, const Sched& S, const Epi& E, const int wave_id) {
;     ...
;             PG8_WAIT_VN(8 + Epi::NS); if (strict) PG8_WAIT_V(8); PG8_WAIT_L(0); PG8_BAR; PG8_MMA(1, 0, At, B0); PG8_MMA(1, 1, At, B1); PG8_BAR; PG8_SCHED;
;             PG8_LDB(B0, 1, 0); PG8_LDB(B1, 1, 1); PG8_SCHED; PG8_LDA(At, 1, 0); PG8_STAGE(PG8_SA(0, 1), a2 + hstep, voffA);
.LBB0_235:
	s_waitcnt lgkmcnt(0)
	s_barrier
	s_setprio 1
	s_waitcnt lgkmcnt(0)
	v_mfma_f32_16x16x32_bf16 v[62:65], v[146:149], v[186:189], v[62:65]
	v_mfma_f32_16x16x32_bf16 v[58:61], v[154:157], v[186:189], v[58:61]
	v_mfma_f32_16x16x32_bf16 v[46:49], v[146:149], v[178:181], v[46:49]
	v_mfma_f32_16x16x32_bf16 v[42:45], v[154:157], v[178:181], v[42:45]
	v_mfma_f32_16x16x32_bf16 v[30:33], v[146:149], v[170:173], v[30:33]
	v_mfma_f32_16x16x32_bf16 v[26:29], v[154:157], v[170:173], v[26:29]
	v_mfma_f32_16x16x32_bf16 v[14:17], v[146:149], v[162:165], v[14:17]
	v_mfma_f32_16x16x32_bf16 v[10:13], v[154:157], v[162:165], v[10:13]
	v_mfma_f32_16x16x32_bf16 v[62:65], v[150:153], v[190:193], v[62:65]
	v_mfma_f32_16x16x32_bf16 v[58:61], v[158:161], v[190:193], v[58:61]
	v_mfma_f32_16x16x32_bf16 v[46:49], v[150:153], v[182:185], v[46:49]
	v_mfma_f32_16x16x32_bf16 v[42:45], v[158:161], v[182:185], v[42:45]
	v_mfma_f32_16x16x32_bf16 v[30:33], v[150:153], v[174:177], v[30:33]
	v_mfma_f32_16x16x32_bf16 v[26:29], v[158:161], v[174:177], v[26:29]
	v_mfma_f32_16x16x32_bf16 v[14:17], v[150:153], v[166:169], v[14:17]
	v_mfma_f32_16x16x32_bf16 v[10:13], v[158:161], v[166:169], v[10:13]
	s_setprio 0
	s_setprio 1
	v_mfma_f32_16x16x32_bf16 v[54:57], v[130:133], v[186:189], v[54:57]
	v_mfma_f32_16x16x32_bf16 v[50:53], v[138:141], v[186:189], v[50:53]
	v_mfma_f32_16x16x32_bf16 v[38:41], v[130:133], v[178:181], v[38:41]
	v_mfma_f32_16x16x32_bf16 v[34:37], v[138:141], v[178:181], v[34:37]
	v_mfma_f32_16x16x32_bf16 v[22:25], v[130:133], v[170:173], v[22:25]
	v_mfma_f32_16x16x32_bf16 v[18:21], v[138:141], v[170:173], v[18:21]
	v_mfma_f32_16x16x32_bf16 v[6:9], v[130:133], v[162:165], v[6:9]
	v_mfma_f32_16x16x32_bf16 v[2:5], v[138:141], v[162:165], v[2:5]
	v_mfma_f32_16x16x32_bf16 v[54:57], v[134:137], v[190:193], v[54:57]
	v_mfma_f32_16x16x32_bf16 v[50:53], v[142:145], v[190:193], v[50:53]
	v_mfma_f32_16x16x32_bf16 v[38:41], v[134:137], v[182:185], v[38:41]
	v_mfma_f32_16x16x32_bf16 v[34:37], v[142:145], v[182:185], v[34:37]
	v_mfma_f32_16x16x32_bf16 v[22:25], v[134:137], v[174:177], v[22:25]
	v_mfma_f32_16x16x32_bf16 v[18:21], v[142:145], v[174:177], v[18:21]
	v_mfma_f32_16x16x32_bf16 v[6:9], v[134:137], v[166:169], v[6:9]
	v_mfma_f32_16x16x32_bf16 v[2:5], v[142:145], v[166:169], v[2:5]
	s_setprio 0
	s_barrier
	ds_read_b128 v[162:165], v247 offset:32768
	ds_read_b128 v[166:169], v247 offset:33792
	ds_read_b128 v[170:173], v247 offset:34816
	ds_read_b128 v[174:177], v247 offset:35840
	ds_read_b128 v[178:181], v247 offset:36864
	ds_read_b128 v[182:185], v247 offset:37888
	ds_read_b128 v[186:189], v247 offset:38912
	ds_read_b128 v[190:193], v247 offset:39936
	s_add_i32 s20, 0, 0x18000
	s_add_i32 s21, 0, 0x1c000
	v_add_u32_e32 v142, s20, v246
	v_add_u32_e32 v158, s21, v246
	ds_read_b128 v[130:133], v142
	ds_read_b128 v[134:137], v142 offset:1024
	ds_read_b128 v[138:141], v142 offset:2048
	ds_read_b128 v[142:145], v142 offset:3072
	ds_read_b128 v[146:149], v158
	ds_read_b128 v[150:153], v158 offset:1024
	ds_read_b128 v[154:157], v158 offset:2048
	ds_read_b128 v[158:161], v158 offset:3072
	s_add_u32 s18, s18, 0xb0000
	s_addc_u32 s19, s19, 0
	s_mov_b32 m0, s39
	v_lshl_add_u64 v[194:195], s[18:19], 0, v[210:211]
	global_load_lds_dwordx4 v[194:195], off
	v_lshl_add_u64 v[194:195], s[18:19], 0, v[214:215]
	s_mov_b32 m0, s40
	s_nop 0
	global_load_lds_dwordx4 v[194:195], off
	s_waitcnt vmcnt(26)
	s_cmp_eq_u32 s100, 0
	s_cbranch_scc1 .Lthird_wait_relaxed_5
	s_waitcnt vmcnt(8)
; #define PG8_STAGE(bufoff, gbase, voff) do { _Pragma("unroll") for (int _i = 0; _i < 2; ++_i) \
;         __builtin_amdgcn_global_load_lds((const unsigned*)((const char*)(gbase) + (voff)[_i]), (PG8_LAS unsigned*)(lds + (bufoff) + ldsw + _i * 8192), 16, 0, 0); } while (0)
; #define PG8_LDA(dst, b, h) do { _Pragma("unroll") for (int m = 0; m < 4; ++m) _Pragma("unroll") for (int k = 0; k < 2; ++k) dst[m][k] = *(const PG8_LAS bf16x8*)(lds + PG8_SA(b, h) + aoff + m * 2048 + k * 1024); } while (0)
; #define PG8_LDB(dst, b, h) do { _Pragma("unroll") for (int n = 0; n < 2; ++n) _Pragma("unroll") for (int k = 0; k < 2; ++k) dst[n][k] = *(const PG8_LAS bf16x8*)(lds + PG8_SB(b, h) + boff + n * 2048 + k * 1024); } while (0)
; #define PG8_MMA(ai, bj, At, Bt) do { __builtin_amdgcn_s_setprio(1); _Pragma("unroll") for (int m = 0; m < 4; ++m) _Pragma("unroll") for (int n = 0; n < 2; ++n) _Pragma("unroll") for (int k = 0; k < 2; ++k) \
;         acc[ai][bj][m][n] = __builtin_amdgcn_mfma_f32_16x16x32_bf16(Bt[n][k], At[m][k], acc[ai][bj][m][n], 0, 0, 0); __builtin_amdgcn_s_setprio(0); } while (0)
; #define PG8_WAIT_V(n) asm volatile("s_waitcnt vmcnt(" #n ")" ::: "memory")
; #define PG8_WAIT_L(n) asm volatile("s_waitcnt lgkmcnt(" #n ")" ::: "memory")
; #define PG8_BAR __builtin_amdgcn_s_barrier()
; #define PG8_SCHED __builtin_amdgcn_sched_barrier(0)
; template <class Epi, class Sched, bool ALIGN_EPI = false, bool SP2 = false>
; __device__ __forceinline__ void gemm_phase(PG8_LAS unsigned char* lds, const Gemm g, const Sched& S, const Epi& E, const int wave_id) {
;     ...
;         for (int t = 0; t < nt; t += 2) {
;     ...
;             PG8_LDB(B0, 1, 0); PG8_LDB(B1, 1, 1); PG8_SCHED; PG8_LDA(At, 1, 0); PG8_STAGE(PG8_SA(0, 1), a2 + hstep, voffA);
;             PG8_WAIT_V(8); PG8_WAIT_L(0); PG8_BAR; PG8_MMA(0, 0, At, B0); PG8_MMA(0, 1, At, B1); PG8_BAR; PG8_SCHED;
;             PG8_LDA(At, 1, 1); PG8_STAGE(PG8_SB(1, 0), b3, voffB); PG8_STAGE(PG8_SB(1, 1), b3 + hstep, voffB); PG8_STAGE(PG8_SA(1, 0), a3, voffA);
;             PG8_WAIT_V(8); PG8_WAIT_L(0); PG8_BAR; PG8_MMA(1, 0, At, B0); PG8_MMA(1, 1, At, B1); PG8_BAR; PG8_SCHED;
.Lthird_wait_relaxed_5:
	s_waitcnt lgkmcnt(0)
	s_barrier
	s_setprio 1
	s_waitcnt lgkmcnt(0)
	v_mfma_f32_16x16x32_bf16 v[126:129], v[130:133], v[162:165], v[126:129]
	v_mfma_f32_16x16x32_bf16 v[122:125], v[138:141], v[162:165], v[122:125]
	v_mfma_f32_16x16x32_bf16 v[110:113], v[130:133], v[170:173], v[110:113]
	v_mfma_f32_16x16x32_bf16 v[106:109], v[138:141], v[170:173], v[106:109]
	v_mfma_f32_16x16x32_bf16 v[94:97], v[130:133], v[178:181], v[94:97]
	v_mfma_f32_16x16x32_bf16 v[90:93], v[138:141], v[178:181], v[90:93]
	v_mfma_f32_16x16x32_bf16 v[78:81], v[130:133], v[186:189], v[78:81]
	v_mfma_f32_16x16x32_bf16 v[74:77], v[138:141], v[186:189], v[74:77]
	v_mfma_f32_16x16x32_bf16 v[126:129], v[134:137], v[166:169], v[126:129]
	v_mfma_f32_16x16x32_bf16 v[122:125], v[142:145], v[166:169], v[122:125]
	v_mfma_f32_16x16x32_bf16 v[110:113], v[134:137], v[174:177], v[110:113]
	v_mfma_f32_16x16x32_bf16 v[106:109], v[142:145], v[174:177], v[106:109]
	v_mfma_f32_16x16x32_bf16 v[94:97], v[134:137], v[182:185], v[94:97]
	v_mfma_f32_16x16x32_bf16 v[90:93], v[142:145], v[182:185], v[90:93]
	v_mfma_f32_16x16x32_bf16 v[78:81], v[134:137], v[190:193], v[78:81]
	v_mfma_f32_16x16x32_bf16 v[74:77], v[142:145], v[190:193], v[74:77]
	s_setprio 0
	s_setprio 1
	v_mfma_f32_16x16x32_bf16 v[118:121], v[146:149], v[162:165], v[118:121]
	v_mfma_f32_16x16x32_bf16 v[114:117], v[154:157], v[162:165], v[114:117]
	v_mfma_f32_16x16x32_bf16 v[102:105], v[146:149], v[170:173], v[102:105]
	v_mfma_f32_16x16x32_bf16 v[98:101], v[154:157], v[170:173], v[98:101]
	v_mfma_f32_16x16x32_bf16 v[86:89], v[146:149], v[178:181], v[86:89]
	v_mfma_f32_16x16x32_bf16 v[82:85], v[154:157], v[178:181], v[82:85]
	v_mfma_f32_16x16x32_bf16 v[70:73], v[146:149], v[186:189], v[70:73]
	v_mfma_f32_16x16x32_bf16 v[66:69], v[154:157], v[186:189], v[66:69]
	v_mfma_f32_16x16x32_bf16 v[118:121], v[150:153], v[166:169], v[118:121]
	v_mfma_f32_16x16x32_bf16 v[114:117], v[158:161], v[166:169], v[114:117]
	v_mfma_f32_16x16x32_bf16 v[102:105], v[150:153], v[174:177], v[102:105]
	v_mfma_f32_16x16x32_bf16 v[98:101], v[158:161], v[174:177], v[98:101]
	v_mfma_f32_16x16x32_bf16 v[86:89], v[150:153], v[182:185], v[86:89]
	v_mfma_f32_16x16x32_bf16 v[82:85], v[158:161], v[182:185], v[82:85]
	v_mfma_f32_16x16x32_bf16 v[70:73], v[150:153], v[190:193], v[70:73]
	v_mfma_f32_16x16x32_bf16 v[66:69], v[158:161], v[190:193], v[66:69]
	s_setprio 0
	s_barrier
	ds_read_b128 v[162:165], v247 offset:49152
	ds_read_b128 v[166:169], v247 offset:50176
	ds_read_b128 v[170:173], v247 offset:51200
	ds_read_b128 v[174:177], v247 offset:52224
	ds_read_b128 v[178:181], v247 offset:53248
	ds_read_b128 v[182:185], v247 offset:54272
	ds_read_b128 v[186:189], v247 offset:55296
	ds_read_b128 v[190:193], v247 offset:56320
	s_add_i32 s18, s20, s30
	v_lshl_add_u64 v[194:195], v[232:233], 0, s[64:65]
	s_mov_b32 m0, s18
	s_nop 0
	global_load_lds_dwordx4 v[194:195], off
	s_add_i32 m0, s18, 0x2000
	s_add_u32 s16, s16, 0xb0080
	v_lshl_add_u64 v[194:195], v[230:231], 0, s[64:65]
	s_addc_u32 s17, s17, 0
	s_add_i32 s18, s21, s30
	global_load_lds_dwordx4 v[194:195], off
	v_lshl_add_u64 v[194:195], s[16:17], 0, v[212:213]
	s_mov_b32 m0, s18
	s_nop 0
	global_load_lds_dwordx4 v[194:195], off
	v_lshl_add_u64 v[194:195], s[16:17], 0, v[216:217]
	s_add_i32 m0, s18, 0x2000
	s_nop 0
	global_load_lds_dwordx4 v[194:195], off
	v_lshl_add_u64 v[194:195], v[226:227], 0, s[64:65]
	s_mov_b32 m0, s42
	s_nop 0
	global_load_lds_dwordx4 v[194:195], off
	v_lshl_add_u64 v[194:195], v[228:229], 0, s[64:65]
	s_mov_b32 m0, s43
	s_nop 0
	global_load_lds_dwordx4 v[194:195], off
	s_waitcnt vmcnt(8)
	s_waitcnt lgkmcnt(0)
	s_barrier
	s_setprio 1
	s_waitcnt lgkmcnt(0)
	v_mfma_f32_16x16x32_bf16 v[62:65], v[130:133], v[162:165], v[62:65]
	v_mfma_f32_16x16x32_bf16 v[58:61], v[138:141], v[162:165], v[58:61]
	v_mfma_f32_16x16x32_bf16 v[46:49], v[130:133], v[170:173], v[46:49]
	v_mfma_f32_16x16x32_bf16 v[42:45], v[138:141], v[170:173], v[42:45]
	v_mfma_f32_16x16x32_bf16 v[30:33], v[130:133], v[178:181], v[30:33]
	v_mfma_f32_16x16x32_bf16 v[26:29], v[138:141], v[178:181], v[26:29]
	v_mfma_f32_16x16x32_bf16 v[14:17], v[130:133], v[186:189], v[14:17]
	v_mfma_f32_16x16x32_bf16 v[10:13], v[138:141], v[186:189], v[10:13]
	v_mfma_f32_16x16x32_bf16 v[62:65], v[134:137], v[166:169], v[62:65]
	v_mfma_f32_16x16x32_bf16 v[58:61], v[142:145], v[166:169], v[58:61]
	v_mfma_f32_16x16x32_bf16 v[46:49], v[134:137], v[174:177], v[46:49]
	v_mfma_f32_16x16x32_bf16 v[42:45], v[142:145], v[174:177], v[42:45]
	v_mfma_f32_16x16x32_bf16 v[30:33], v[134:137], v[182:185], v[30:33]
	v_mfma_f32_16x16x32_bf16 v[26:29], v[142:145], v[182:185], v[26:29]
	v_mfma_f32_16x16x32_bf16 v[14:17], v[134:137], v[190:193], v[14:17]
	v_mfma_f32_16x16x32_bf16 v[10:13], v[142:145], v[190:193], v[10:13]
	s_setprio 0
	s_setprio 1
	v_mfma_f32_16x16x32_bf16 v[54:57], v[146:149], v[162:165], v[54:57]
	v_mfma_f32_16x16x32_bf16 v[50:53], v[154:157], v[162:165], v[50:53]
	v_mfma_f32_16x16x32_bf16 v[38:41], v[146:149], v[170:173], v[38:41]
	v_mfma_f32_16x16x32_bf16 v[34:37], v[154:157], v[170:173], v[34:37]
	v_mfma_f32_16x16x32_bf16 v[22:25], v[146:149], v[178:181], v[22:25]
	v_mfma_f32_16x16x32_bf16 v[18:21], v[154:157], v[178:181], v[18:21]
	v_mfma_f32_16x16x32_bf16 v[6:9], v[146:149], v[186:189], v[6:9]
	v_mfma_f32_16x16x32_bf16 v[2:5], v[154:157], v[186:189], v[2:5]
	v_mfma_f32_16x16x32_bf16 v[54:57], v[150:153], v[166:169], v[54:57]
	v_mfma_f32_16x16x32_bf16 v[50:53], v[158:161], v[166:169], v[50:53]
	v_mfma_f32_16x16x32_bf16 v[38:41], v[150:153], v[174:177], v[38:41]
	v_mfma_f32_16x16x32_bf16 v[34:37], v[158:161], v[174:177], v[34:37]
	v_mfma_f32_16x16x32_bf16 v[22:25], v[150:153], v[182:185], v[22:25]
	v_mfma_f32_16x16x32_bf16 v[18:21], v[158:161], v[182:185], v[18:21]
	v_mfma_f32_16x16x32_bf16 v[6:9], v[150:153], v[190:193], v[6:9]
	v_mfma_f32_16x16x32_bf16 v[2:5], v[158:161], v[190:193], v[2:5]
	s_setprio 0
	s_add_i32 s63, s63, 2
	s_add_u32 s14, s14, 0x100
	s_addc_u32 s15, s15, 0
	s_cmp_gt_u32 s63, 41
	s_barrier
	s_cbranch_scc1 .LBB0_240

; #define PG8_STAGE(bufoff, gbase, voff) do { _Pragma("unroll") for (int _i = 0; _i < 2; ++_i) \
;         __builtin_amdgcn_global_load_lds((const unsigned*)((const char*)(gbase) + (voff)[_i]), (PG8_LAS unsigned*)(lds + (bufoff) + ldsw + _i * 8192), 16, 0, 0); } while (0)
; #define PG8_LDA(dst, b, h) do { _Pragma("unroll") for (int m = 0; m < 4; ++m) _Pragma("unroll") for (int k = 0; k < 2; ++k) dst[m][k] = *(const PG8_LAS bf16x8*)(lds + PG8_SA(b, h) + aoff + m * 2048 + k * 1024); } while (0)
; #define PG8_LDB(dst, b, h) do { _Pragma("unroll") for (int n = 0; n < 2; ++n) _Pragma("unroll") for (int k = 0; k < 2; ++k) dst[n][k] = *(const PG8_LAS bf16x8*)(lds + PG8_SB(b, h) + boff + n * 2048 + k * 1024); } while (0)
; #define PG8_MMA(ai, bj, At, Bt) do { __builtin_amdgcn_s_setprio(1); _Pragma("unroll") for (int m = 0; m < 4; ++m) _Pragma("unroll") for (int n = 0; n < 2; ++n) _Pragma("unroll") for (int k = 0; k < 2; ++k) \
;         acc[ai][bj][m][n] = __builtin_amdgcn_mfma_f32_16x16x32_bf16(Bt[n][k], At[m][k], acc[ai][bj][m][n], 0, 0, 0); __builtin_amdgcn_s_setprio(0); } while (0)
; #define PG8_WAIT_V(n) asm volatile("s_waitcnt vmcnt(" #n ")" ::: "memory")
; #define PG8_WAIT_VN(n) asm volatile("s_waitcnt vmcnt(%0)" :: "n"(n) : "memory")
; template <class Epi, class Sched, bool ALIGN_EPI = false, bool SP2 = false>
; __device__ __forceinline__ void gemm_phase(PG8_LAS unsigned char* lds, const Gemm g, const Sched& S, const Epi& E, const int wave_id) {
;     ...
;             const bool last = (t == nt - 2);
;             const char* a1 = cA + (size_t)(t + 1) * kstep;
;             const char* a2 = last ? nA : cA + (size_t)(t + 2) * kstep; const char* b2 = last ? nB : cB + (size_t)(t + 2) * kstep;
;             const char* a3 = a2 + kstep; const char* b3 = b2 + kstep;
;     ...
;             PG8_LDB(B0, 0, 0); PG8_LDB(B1, 0, 1); PG8_SCHED; PG8_LDA(At, 0, 0); PG8_STAGE(PG8_SA(1, 1), a1 + hstep, voffA);
;             PG8_WAIT_VN(8 + Epi::NS); if (strict) PG8_WAIT_V(8); PG8_WAIT_L(0); PG8_BAR; PG8_MMA(0, 0, At, B0); PG8_MMA(0, 1, At, B1); PG8_BAR; PG8_SCHED;
;             PG8_LDA(At, 0, 1); PG8_STAGE(PG8_SB(0, 0), b2, voffB); PG8_STAGE(PG8_SB(0, 1), b2 + hstep, voffB); PG8_STAGE(PG8_SA(0, 0), a2, voffA);
;             PG8_WAIT_VN(8 + Epi::NS); if (strict) PG8_WAIT_V(8); PG8_WAIT_L(0); PG8_BAR; PG8_MMA(1, 0, At, B0); PG8_MMA(1, 1, At, B1); PG8_BAR; PG8_SCHED;
.LBB0_238:
	s_add_u32 s16, s12, s14
	s_addc_u32 s17, s13, s15
	s_add_u32 s16, s16, 0x100
	s_addc_u32 s17, s17, 0
	s_add_u32 s53, s57, s14
	s_addc_u32 s67, s62, s15
	s_waitcnt lgkmcnt(0)
	s_cmpk_eq_i32 s14, 0x1500
	s_cselect_b32 s19, s7, s17
	s_cselect_b32 s18, s6, s16
	s_cselect_b32 s17, s11, s67
	s_cselect_b32 s16, s10, s53
	s_barrier
	s_setprio 1
	s_waitcnt lgkmcnt(0)
	v_mfma_f32_16x16x32_bf16 v[126:129], v[146:149], v[186:189], v[126:129]
	v_mfma_f32_16x16x32_bf16 v[122:125], v[154:157], v[186:189], v[122:125]
	v_mfma_f32_16x16x32_bf16 v[110:113], v[146:149], v[178:181], v[110:113]
	v_mfma_f32_16x16x32_bf16 v[106:109], v[154:157], v[178:181], v[106:109]
	v_mfma_f32_16x16x32_bf16 v[94:97], v[146:149], v[170:173], v[94:97]
	v_mfma_f32_16x16x32_bf16 v[90:93], v[154:157], v[170:173], v[90:93]
	v_mfma_f32_16x16x32_bf16 v[78:81], v[146:149], v[162:165], v[78:81]
	v_mfma_f32_16x16x32_bf16 v[74:77], v[154:157], v[162:165], v[74:77]
	v_mfma_f32_16x16x32_bf16 v[126:129], v[150:153], v[190:193], v[126:129]
	v_mfma_f32_16x16x32_bf16 v[122:125], v[158:161], v[190:193], v[122:125]
	v_mfma_f32_16x16x32_bf16 v[110:113], v[150:153], v[182:185], v[110:113]
	v_mfma_f32_16x16x32_bf16 v[106:109], v[158:161], v[182:185], v[106:109]
	v_mfma_f32_16x16x32_bf16 v[94:97], v[150:153], v[174:177], v[94:97]
	v_mfma_f32_16x16x32_bf16 v[90:93], v[158:161], v[174:177], v[90:93]
	v_mfma_f32_16x16x32_bf16 v[78:81], v[150:153], v[166:169], v[78:81]
	v_mfma_f32_16x16x32_bf16 v[74:77], v[158:161], v[166:169], v[74:77]
	s_setprio 0
	s_setprio 1
	v_mfma_f32_16x16x32_bf16 v[118:121], v[130:133], v[186:189], v[118:121]
	v_mfma_f32_16x16x32_bf16 v[114:117], v[138:141], v[186:189], v[114:117]
	v_mfma_f32_16x16x32_bf16 v[102:105], v[130:133], v[178:181], v[102:105]
	v_mfma_f32_16x16x32_bf16 v[98:101], v[138:141], v[178:181], v[98:101]
	v_mfma_f32_16x16x32_bf16 v[86:89], v[130:133], v[170:173], v[86:89]
	v_mfma_f32_16x16x32_bf16 v[82:85], v[138:141], v[170:173], v[82:85]
	v_mfma_f32_16x16x32_bf16 v[70:73], v[130:133], v[162:165], v[70:73]
	v_mfma_f32_16x16x32_bf16 v[66:69], v[138:141], v[162:165], v[66:69]
	v_mfma_f32_16x16x32_bf16 v[118:121], v[134:137], v[190:193], v[118:121]
	v_mfma_f32_16x16x32_bf16 v[114:117], v[142:145], v[190:193], v[114:117]
	v_mfma_f32_16x16x32_bf16 v[102:105], v[134:137], v[182:185], v[102:105]
	v_mfma_f32_16x16x32_bf16 v[98:101], v[142:145], v[182:185], v[98:101]
	v_mfma_f32_16x16x32_bf16 v[86:89], v[134:137], v[174:177], v[86:89]
	v_mfma_f32_16x16x32_bf16 v[82:85], v[142:145], v[174:177], v[82:85]
	v_mfma_f32_16x16x32_bf16 v[70:73], v[134:137], v[166:169], v[70:73]
	v_mfma_f32_16x16x32_bf16 v[66:69], v[142:145], v[166:169], v[66:69]
	s_setprio 0
	s_barrier
	ds_read_b128 v[186:189], v247 offset:16384
	ds_read_b128 v[190:193], v247 offset:17408
	ds_read_b128 v[178:181], v247 offset:18432
	ds_read_b128 v[182:185], v247 offset:19456
	ds_read_b128 v[170:173], v247 offset:20480
	ds_read_b128 v[174:177], v247 offset:21504
	ds_read_b128 v[162:165], v247 offset:22528
	ds_read_b128 v[166:169], v247 offset:23552
	s_mov_b32 m0, s34
	v_lshl_add_u64 v[232:233], s[16:17], 0, v[212:213]
	s_add_u32 s68, s16, 0xb0000
	global_load_lds_dwordx4 v[232:233], off
	v_lshl_add_u64 v[230:231], s[16:17], 0, v[216:217]
	s_mov_b32 m0, s35
	s_addc_u32 s69, s17, 0
	global_load_lds_dwordx4 v[230:231], off
	v_lshl_add_u64 v[194:195], s[68:69], 0, v[212:213]
	s_mov_b32 m0, s36
	v_lshl_add_u64 v[226:227], s[18:19], 0, v[210:211]
	global_load_lds_dwordx4 v[194:195], off
	v_lshl_add_u64 v[194:195], s[68:69], 0, v[216:217]
	s_mov_b32 m0, s37
	v_lshl_add_u64 v[228:229], s[18:19], 0, v[214:215]
	global_load_lds_dwordx4 v[194:195], off
	s_mov_b32 m0, s31
	s_andn2_b64 vcc, exec, s[20:21]
	global_load_lds_dwordx4 v[226:227], off
	s_mov_b32 m0, s38
	s_nop 0
	global_load_lds_dwordx4 v[228:229], off
	s_waitcnt vmcnt(24)
	s_cbranch_vccnz .LBB0_235
	s_waitcnt vmcnt(8)
	s_branch .LBB0_235

; #define PG8_STAGE(bufoff, gbase, voff) do { _Pragma("unroll") for (int _i = 0; _i < 2; ++_i) \
;         __builtin_amdgcn_global_load_lds((const unsigned*)((const char*)(gbase) + (voff)[_i]), (PG8_LAS unsigned*)(lds + (bufoff) + ldsw + _i * 8192), 16, 0, 0); } while (0)
; #define PG8_LDA(dst, b, h) do { _Pragma("unroll") for (int m = 0; m < 4; ++m) _Pragma("unroll") for (int k = 0; k < 2; ++k) dst[m][k] = *(const PG8_LAS bf16x8*)(lds + PG8_SA(b, h) + aoff + m * 2048 + k * 1024); } while (0)
; #define PG8_LDB(dst, b, h) do { _Pragma("unroll") for (int n = 0; n < 2; ++n) _Pragma("unroll") for (int k = 0; k < 2; ++k) dst[n][k] = *(const PG8_LAS bf16x8*)(lds + PG8_SB(b, h) + boff + n * 2048 + k * 1024); } while (0)
; #define PG8_MMA(ai, bj, At, Bt) do { __builtin_amdgcn_s_setprio(1); _Pragma("unroll") for (int m = 0; m < 4; ++m) _Pragma("unroll") for (int n = 0; n < 2; ++n) _Pragma("unroll") for (int k = 0; k < 2; ++k) \
;         acc[ai][bj][m][n] = __builtin_amdgcn_mfma_f32_16x16x32_bf16(Bt[n][k], At[m][k], acc[ai][bj][m][n], 0, 0, 0); __builtin_amdgcn_s_setprio(0); } while (0)
; #define PG8_WAIT_V(n) asm volatile("s_waitcnt vmcnt(" #n ")" ::: "memory")
; #define PG8_WAIT_L(n) asm volatile("s_waitcnt lgkmcnt(" #n ")" ::: "memory")
; #define PG8_BAR __builtin_amdgcn_s_barrier()
; #define PG8_SCHED __builtin_amdgcn_sched_barrier(0)
; template <class Epi, class Sched, bool ALIGN_EPI = false, bool SP2 = false>
; __device__ __forceinline__ void gemm_phase(PG8_LAS unsigned char* lds, const Gemm g, const Sched& S, const Epi& E, const int wave_id) {
;     ...
;             PG8_LDB(B0, 1, 0); PG8_LDB(B1, 1, 1); PG8_SCHED; PG8_LDA(At, 1, 0); PG8_STAGE(PG8_SA(0, 1), a2 + hstep, voffA);
;             PG8_WAIT_V(8); PG8_WAIT_L(0); PG8_BAR; PG8_MMA(0, 0, At, B0); PG8_MMA(0, 1, At, B1); PG8_BAR; PG8_SCHED;
.LBB0_304:
	s_waitcnt lgkmcnt(0)
	s_barrier
	s_setprio 1
	s_waitcnt lgkmcnt(0)
	v_mfma_f32_16x16x32_bf16 v[62:65], v[146:149], v[186:189], v[62:65]
	v_mfma_f32_16x16x32_bf16 v[58:61], v[154:157], v[186:189], v[58:61]
	v_mfma_f32_16x16x32_bf16 v[54:57], v[146:149], v[178:181], v[54:57]
	v_mfma_f32_16x16x32_bf16 v[50:53], v[154:157], v[178:181], v[50:53]
	v_mfma_f32_16x16x32_bf16 v[42:45], v[146:149], v[170:173], v[42:45]
	v_mfma_f32_16x16x32_bf16 v[34:37], v[154:157], v[170:173], v[34:37]
	v_mfma_f32_16x16x32_bf16 v[26:29], v[146:149], v[162:165], v[26:29]
	v_mfma_f32_16x16x32_bf16 v[18:21], v[154:157], v[162:165], v[18:21]
	v_mfma_f32_16x16x32_bf16 v[62:65], v[150:153], v[190:193], v[62:65]
	v_mfma_f32_16x16x32_bf16 v[58:61], v[158:161], v[190:193], v[58:61]
	v_mfma_f32_16x16x32_bf16 v[54:57], v[150:153], v[182:185], v[54:57]
	v_mfma_f32_16x16x32_bf16 v[50:53], v[158:161], v[182:185], v[50:53]
	v_mfma_f32_16x16x32_bf16 v[42:45], v[150:153], v[174:177], v[42:45]
	v_mfma_f32_16x16x32_bf16 v[34:37], v[158:161], v[174:177], v[34:37]
	v_mfma_f32_16x16x32_bf16 v[26:29], v[150:153], v[166:169], v[26:29]
	v_mfma_f32_16x16x32_bf16 v[18:21], v[158:161], v[166:169], v[18:21]
	s_setprio 0
	s_setprio 1
	v_mfma_f32_16x16x32_bf16 v[46:49], v[130:133], v[186:189], v[46:49]
	v_mfma_f32_16x16x32_bf16 v[38:41], v[138:141], v[186:189], v[38:41]
	v_mfma_f32_16x16x32_bf16 v[30:33], v[130:133], v[178:181], v[30:33]
	v_mfma_f32_16x16x32_bf16 v[22:25], v[138:141], v[178:181], v[22:25]
	v_mfma_f32_16x16x32_bf16 v[14:17], v[130:133], v[170:173], v[14:17]
	v_mfma_f32_16x16x32_bf16 v[10:13], v[138:141], v[170:173], v[10:13]
	v_mfma_f32_16x16x32_bf16 v[6:9], v[130:133], v[162:165], v[6:9]
	v_mfma_f32_16x16x32_bf16 v[2:5], v[138:141], v[162:165], v[2:5]
	v_mfma_f32_16x16x32_bf16 v[46:49], v[134:137], v[190:193], v[46:49]
	v_mfma_f32_16x16x32_bf16 v[38:41], v[142:145], v[190:193], v[38:41]
	v_mfma_f32_16x16x32_bf16 v[30:33], v[134:137], v[182:185], v[30:33]
	v_mfma_f32_16x16x32_bf16 v[22:25], v[142:145], v[182:185], v[22:25]
	v_mfma_f32_16x16x32_bf16 v[14:17], v[134:137], v[174:177], v[14:17]
	v_mfma_f32_16x16x32_bf16 v[10:13], v[142:145], v[174:177], v[10:13]
	v_mfma_f32_16x16x32_bf16 v[6:9], v[134:137], v[166:169], v[6:9]
	v_mfma_f32_16x16x32_bf16 v[2:5], v[142:145], v[166:169], v[2:5]
	s_setprio 0
	s_barrier
	ds_read_b128 v[162:165], v232 offset:32768
	ds_read_b128 v[166:169], v232 offset:33792
	ds_read_b128 v[170:173], v232 offset:34816
	ds_read_b128 v[174:177], v232 offset:35840
	ds_read_b128 v[178:181], v232 offset:36864
	ds_read_b128 v[182:185], v232 offset:37888
	ds_read_b128 v[186:189], v232 offset:38912
	ds_read_b128 v[190:193], v232 offset:39936
	s_add_i32 s16, 0, 0x18000
	s_add_i32 s17, 0, 0x1c000
	v_add_u32_e32 v142, s16, v231
	v_add_u32_e32 v158, s17, v231
	ds_read_b128 v[130:133], v142
	ds_read_b128 v[134:137], v142 offset:1024
	ds_read_b128 v[138:141], v142 offset:2048
	ds_read_b128 v[142:145], v142 offset:3072
	ds_read_b128 v[146:149], v158
	ds_read_b128 v[150:153], v158 offset:1024
	ds_read_b128 v[154:157], v158 offset:2048
	ds_read_b128 v[158:161], v158 offset:3072
	s_add_u32 s14, s14, 0xb0000
	s_addc_u32 s15, s15, 0
	s_mov_b32 m0, s29
	v_lshl_add_u64 v[194:195], s[14:15], 0, v[216:217]
	global_load_lds_dwordx4 v[194:195], off
	v_lshl_add_u64 v[194:195], s[14:15], 0, v[212:213]
	s_mov_b32 m0, s30
	s_nop 0
	global_load_lds_dwordx4 v[194:195], off
	s_waitcnt vmcnt(8)
	s_waitcnt lgkmcnt(0)
	s_barrier
	s_setprio 1
	s_waitcnt lgkmcnt(0)
	v_mfma_f32_16x16x32_bf16 v[126:129], v[130:133], v[162:165], v[126:129]
	v_mfma_f32_16x16x32_bf16 v[122:125], v[138:141], v[162:165], v[122:125]
	v_mfma_f32_16x16x32_bf16 v[118:121], v[130:133], v[170:173], v[118:121]
	v_mfma_f32_16x16x32_bf16 v[114:117], v[138:141], v[170:173], v[114:117]
	v_mfma_f32_16x16x32_bf16 v[110:113], v[130:133], v[178:181], v[110:113]
	v_mfma_f32_16x16x32_bf16 v[102:105], v[138:141], v[178:181], v[102:105]
	v_mfma_f32_16x16x32_bf16 v[94:97], v[130:133], v[186:189], v[94:97]
	v_mfma_f32_16x16x32_bf16 v[86:89], v[138:141], v[186:189], v[86:89]
	v_mfma_f32_16x16x32_bf16 v[126:129], v[134:137], v[166:169], v[126:129]
	v_mfma_f32_16x16x32_bf16 v[122:125], v[142:145], v[166:169], v[122:125]
	v_mfma_f32_16x16x32_bf16 v[118:121], v[134:137], v[174:177], v[118:121]
	v_mfma_f32_16x16x32_bf16 v[114:117], v[142:145], v[174:177], v[114:117]
	v_mfma_f32_16x16x32_bf16 v[110:113], v[134:137], v[182:185], v[110:113]
	v_mfma_f32_16x16x32_bf16 v[102:105], v[142:145], v[182:185], v[102:105]
	v_mfma_f32_16x16x32_bf16 v[94:97], v[134:137], v[190:193], v[94:97]
	v_mfma_f32_16x16x32_bf16 v[86:89], v[142:145], v[190:193], v[86:89]
	s_setprio 0
	s_setprio 1
	v_mfma_f32_16x16x32_bf16 v[106:109], v[146:149], v[162:165], v[106:109]
	v_mfma_f32_16x16x32_bf16 v[98:101], v[154:157], v[162:165], v[98:101]
	v_mfma_f32_16x16x32_bf16 v[90:93], v[146:149], v[170:173], v[90:93]
	v_mfma_f32_16x16x32_bf16 v[82:85], v[154:157], v[170:173], v[82:85]
	v_mfma_f32_16x16x32_bf16 v[78:81], v[146:149], v[178:181], v[78:81]
	v_mfma_f32_16x16x32_bf16 v[74:77], v[154:157], v[178:181], v[74:77]
	v_mfma_f32_16x16x32_bf16 v[70:73], v[146:149], v[186:189], v[70:73]
	v_mfma_f32_16x16x32_bf16 v[66:69], v[154:157], v[186:189], v[66:69]
	v_mfma_f32_16x16x32_bf16 v[106:109], v[150:153], v[166:169], v[106:109]
	v_mfma_f32_16x16x32_bf16 v[98:101], v[158:161], v[166:169], v[98:101]
	v_mfma_f32_16x16x32_bf16 v[90:93], v[150:153], v[174:177], v[90:93]
	v_mfma_f32_16x16x32_bf16 v[82:85], v[158:161], v[174:177], v[82:85]
	v_mfma_f32_16x16x32_bf16 v[78:81], v[150:153], v[182:185], v[78:81]
	v_mfma_f32_16x16x32_bf16 v[74:77], v[158:161], v[182:185], v[74:77]
	v_mfma_f32_16x16x32_bf16 v[70:73], v[150:153], v[190:193], v[70:73]
	v_mfma_f32_16x16x32_bf16 v[66:69], v[158:161], v[190:193], v[66:69]
	s_setprio 0
	s_barrier
; #define PG8_STAGE(bufoff, gbase, voff) do { _Pragma("unroll") for (int _i = 0; _i < 2; ++_i) \
;         __builtin_amdgcn_global_load_lds((const unsigned*)((const char*)(gbase) + (voff)[_i]), (PG8_LAS unsigned*)(lds + (bufoff) + ldsw + _i * 8192), 16, 0, 0); } while (0)
; #define PG8_LDA(dst, b, h) do { _Pragma("unroll") for (int m = 0; m < 4; ++m) _Pragma("unroll") for (int k = 0; k < 2; ++k) dst[m][k] = *(const PG8_LAS bf16x8*)(lds + PG8_SA(b, h) + aoff + m * 2048 + k * 1024); } while (0)
; #define PG8_MMA(ai, bj, At, Bt) do { __builtin_amdgcn_s_setprio(1); _Pragma("unroll") for (int m = 0; m < 4; ++m) _Pragma("unroll") for (int n = 0; n < 2; ++n) _Pragma("unroll") for (int k = 0; k < 2; ++k) \
;         acc[ai][bj][m][n] = __builtin_amdgcn_mfma_f32_16x16x32_bf16(Bt[n][k], At[m][k], acc[ai][bj][m][n], 0, 0, 0); __builtin_amdgcn_s_setprio(0); } while (0)
; #define PG8_WAIT_V(n) asm volatile("s_waitcnt vmcnt(" #n ")" ::: "memory")
; #define PG8_WAIT_L(n) asm volatile("s_waitcnt lgkmcnt(" #n ")" ::: "memory")
; #define PG8_BAR __builtin_amdgcn_s_barrier()
; #define PG8_SCHED __builtin_amdgcn_sched_barrier(0)
; template <class Epi, class Sched, bool ALIGN_EPI = false, bool SP2 = false>
; __device__ __forceinline__ void gemm_phase(PG8_LAS unsigned char* lds, const Gemm g, const Sched& S, const Epi& E, const int wave_id) {
;     ...
;         for (int t = 0; t < nt; t += 2) {
;     ...
;             PG8_LDA(At, 1, 1); PG8_STAGE(PG8_SB(1, 0), b3, voffB); PG8_STAGE(PG8_SB(1, 1), b3 + hstep, voffB); PG8_STAGE(PG8_SA(1, 0), a3, voffA);
;             PG8_WAIT_V(8); PG8_WAIT_L(0); PG8_BAR; PG8_MMA(1, 0, At, B0); PG8_MMA(1, 1, At, B1); PG8_BAR; PG8_SCHED;
	ds_read_b128 v[162:165], v232 offset:49152
	ds_read_b128 v[166:169], v232 offset:50176
	ds_read_b128 v[170:173], v232 offset:51200
	ds_read_b128 v[174:177], v232 offset:52224
	ds_read_b128 v[178:181], v232 offset:53248
	ds_read_b128 v[182:185], v232 offset:54272
	ds_read_b128 v[186:189], v232 offset:55296
	ds_read_b128 v[190:193], v232 offset:56320
	s_add_i32 s14, s16, s21
	v_lshl_add_u64 v[194:195], v[228:229], 0, s[64:65]
	s_mov_b32 m0, s14
	s_nop 0
	global_load_lds_dwordx4 v[194:195], off
	s_add_i32 m0, s14, 0x2000
	s_add_u32 s12, s12, 0xb0080
	v_lshl_add_u64 v[194:195], v[226:227], 0, s[64:65]
	s_addc_u32 s13, s13, 0
	s_add_i32 s14, s17, s21
	global_load_lds_dwordx4 v[194:195], off
	v_lshl_add_u64 v[194:195], s[12:13], 0, v[214:215]
	s_mov_b32 m0, s14
	s_nop 0
	global_load_lds_dwordx4 v[194:195], off
	v_lshl_add_u64 v[194:195], s[12:13], 0, v[210:211]
	s_add_i32 m0, s14, 0x2000
	s_nop 0
	global_load_lds_dwordx4 v[194:195], off
	v_lshl_add_u64 v[194:195], v[222:223], 0, s[64:65]
	s_mov_b32 m0, s31
	s_nop 0
	global_load_lds_dwordx4 v[194:195], off
	v_lshl_add_u64 v[194:195], v[224:225], 0, s[64:65]
	s_mov_b32 m0, s34
	s_nop 0
	global_load_lds_dwordx4 v[194:195], off
	s_waitcnt vmcnt(8)
	s_waitcnt lgkmcnt(0)
	s_barrier
	s_setprio 1
	s_waitcnt lgkmcnt(0)
	v_mfma_f32_16x16x32_bf16 v[62:65], v[130:133], v[162:165], v[62:65]
	v_mfma_f32_16x16x32_bf16 v[58:61], v[138:141], v[162:165], v[58:61]
	v_mfma_f32_16x16x32_bf16 v[54:57], v[130:133], v[170:173], v[54:57]
	v_mfma_f32_16x16x32_bf16 v[50:53], v[138:141], v[170:173], v[50:53]
	v_mfma_f32_16x16x32_bf16 v[42:45], v[130:133], v[178:181], v[42:45]
	v_mfma_f32_16x16x32_bf16 v[34:37], v[138:141], v[178:181], v[34:37]
	v_mfma_f32_16x16x32_bf16 v[26:29], v[130:133], v[186:189], v[26:29]
	v_mfma_f32_16x16x32_bf16 v[18:21], v[138:141], v[186:189], v[18:21]
	v_mfma_f32_16x16x32_bf16 v[62:65], v[134:137], v[166:169], v[62:65]
	v_mfma_f32_16x16x32_bf16 v[58:61], v[142:145], v[166:169], v[58:61]
	v_mfma_f32_16x16x32_bf16 v[54:57], v[134:137], v[174:177], v[54:57]
	v_mfma_f32_16x16x32_bf16 v[50:53], v[142:145], v[174:177], v[50:53]
	v_mfma_f32_16x16x32_bf16 v[42:45], v[134:137], v[182:185], v[42:45]
	v_mfma_f32_16x16x32_bf16 v[34:37], v[142:145], v[182:185], v[34:37]
	v_mfma_f32_16x16x32_bf16 v[26:29], v[134:137], v[190:193], v[26:29]
	v_mfma_f32_16x16x32_bf16 v[18:21], v[142:145], v[190:193], v[18:21]
	s_setprio 0
	s_setprio 1
	v_mfma_f32_16x16x32_bf16 v[46:49], v[146:149], v[162:165], v[46:49]
	v_mfma_f32_16x16x32_bf16 v[38:41], v[154:157], v[162:165], v[38:41]
	v_mfma_f32_16x16x32_bf16 v[30:33], v[146:149], v[170:173], v[30:33]
	v_mfma_f32_16x16x32_bf16 v[22:25], v[154:157], v[170:173], v[22:25]
	v_mfma_f32_16x16x32_bf16 v[14:17], v[146:149], v[178:181], v[14:17]
	v_mfma_f32_16x16x32_bf16 v[10:13], v[154:157], v[178:181], v[10:13]
	v_mfma_f32_16x16x32_bf16 v[6:9], v[146:149], v[186:189], v[6:9]
	v_mfma_f32_16x16x32_bf16 v[2:5], v[154:157], v[186:189], v[2:5]
	v_mfma_f32_16x16x32_bf16 v[46:49], v[150:153], v[166:169], v[46:49]
	v_mfma_f32_16x16x32_bf16 v[38:41], v[158:161], v[166:169], v[38:41]
	v_mfma_f32_16x16x32_bf16 v[30:33], v[150:153], v[174:177], v[30:33]
	v_mfma_f32_16x16x32_bf16 v[22:25], v[158:161], v[174:177], v[22:25]
	v_mfma_f32_16x16x32_bf16 v[14:17], v[150:153], v[182:185], v[14:17]
	v_mfma_f32_16x16x32_bf16 v[10:13], v[158:161], v[182:185], v[10:13]
	v_mfma_f32_16x16x32_bf16 v[6:9], v[150:153], v[190:193], v[6:9]
	v_mfma_f32_16x16x32_bf16 v[2:5], v[158:161], v[190:193], v[2:5]
	s_setprio 0
	s_barrier
	s_add_u32 s10, s10, 0x100
	s_addc_u32 s11, s11, 0
	s_cmp_gt_u32 s39, 19
	v_readlane_b32 s40, v254, 55
	s_cbranch_scc1 .LBB0_309

; #define PG8_STAGE(bufoff, gbase, voff) do { _Pragma("unroll") for (int _i = 0; _i < 2; ++_i) \
;         __builtin_amdgcn_global_load_lds((const unsigned*)((const char*)(gbase) + (voff)[_i]), (PG8_LAS unsigned*)(lds + (bufoff) + ldsw + _i * 8192), 16, 0, 0); } while (0)
; #define PG8_LDA(dst, b, h) do { _Pragma("unroll") for (int m = 0; m < 4; ++m) _Pragma("unroll") for (int k = 0; k < 2; ++k) dst[m][k] = *(const PG8_LAS bf16x8*)(lds + PG8_SA(b, h) + aoff + m * 2048 + k * 1024); } while (0)
; #define PG8_LDB(dst, b, h) do { _Pragma("unroll") for (int n = 0; n < 2; ++n) _Pragma("unroll") for (int k = 0; k < 2; ++k) dst[n][k] = *(const PG8_LAS bf16x8*)(lds + PG8_SB(b, h) + boff + n * 2048 + k * 1024); } while (0)
; #define PG8_MMA(ai, bj, At, Bt) do { __builtin_amdgcn_s_setprio(1); _Pragma("unroll") for (int m = 0; m < 4; ++m) _Pragma("unroll") for (int n = 0; n < 2; ++n) _Pragma("unroll") for (int k = 0; k < 2; ++k) \
;         acc[ai][bj][m][n] = __builtin_amdgcn_mfma_f32_16x16x32_bf16(Bt[n][k], At[m][k], acc[ai][bj][m][n], 0, 0, 0); __builtin_amdgcn_s_setprio(0); } while (0)
; #define PG8_WAIT_V(n) asm volatile("s_waitcnt vmcnt(" #n ")" ::: "memory")
; #define PG8_WAIT_VN(n) asm volatile("s_waitcnt vmcnt(%0)" :: "n"(n) : "memory")
; template <class Epi, class Sched, bool ALIGN_EPI = false, bool SP2 = false>
; __device__ __forceinline__ void gemm_phase(PG8_LAS unsigned char* lds, const Gemm g, const Sched& S, const Epi& E, const int wave_id) {
;     ...
;             const bool last = (t == nt - 2);
;             const char* a1 = cA + (size_t)(t + 1) * kstep;
;             const char* a2 = last ? nA : cA + (size_t)(t + 2) * kstep; const char* b2 = last ? nB : cB + (size_t)(t + 2) * kstep;
;             const char* a3 = a2 + kstep; const char* b3 = b2 + kstep;
;     ...
;             PG8_LDB(B0, 0, 0); PG8_LDB(B1, 0, 1); PG8_SCHED; PG8_LDA(At, 0, 0); PG8_STAGE(PG8_SA(1, 1), a1 + hstep, voffA);
;             PG8_WAIT_VN(8 + Epi::NS); if (strict) PG8_WAIT_V(8); PG8_WAIT_L(0); PG8_BAR; PG8_MMA(0, 0, At, B0); PG8_MMA(0, 1, At, B1); PG8_BAR; PG8_SCHED;
;             PG8_LDA(At, 0, 1); PG8_STAGE(PG8_SB(0, 0), b2, voffB); PG8_STAGE(PG8_SB(0, 1), b2 + hstep, voffB); PG8_STAGE(PG8_SA(0, 0), a2, voffA);
;             PG8_WAIT_VN(8 + Epi::NS); if (strict) PG8_WAIT_V(8); PG8_WAIT_L(0); PG8_BAR; PG8_MMA(1, 0, At, B0); PG8_MMA(1, 1, At, B1); PG8_BAR; PG8_SCHED;
.LBB0_307:
	s_add_u32 s12, s37, s10
	s_addc_u32 s13, s38, s11
	s_add_u32 s12, s12, 0x26300100
	s_addc_u32 s13, s13, 0
	s_add_u32 s40, s35, s10
	s_addc_u32 s41, s36, s11
	s_waitcnt lgkmcnt(0)
	s_cmpk_eq_i32 s10, 0xa00
	s_cselect_b32 s15, s9, s13
	s_cselect_b32 s14, s8, s12
	s_cselect_b32 s13, s7, s41
	s_cselect_b32 s12, s6, s40
	s_barrier
	s_setprio 1
	s_waitcnt lgkmcnt(0)
	v_mfma_f32_16x16x32_bf16 v[126:129], v[146:149], v[186:189], v[126:129]
	v_mfma_f32_16x16x32_bf16 v[122:125], v[154:157], v[186:189], v[122:125]
	v_mfma_f32_16x16x32_bf16 v[118:121], v[146:149], v[178:181], v[118:121]
	v_mfma_f32_16x16x32_bf16 v[114:117], v[154:157], v[178:181], v[114:117]
	v_mfma_f32_16x16x32_bf16 v[110:113], v[146:149], v[170:173], v[110:113]
	v_mfma_f32_16x16x32_bf16 v[102:105], v[154:157], v[170:173], v[102:105]
	v_mfma_f32_16x16x32_bf16 v[94:97], v[146:149], v[162:165], v[94:97]
	v_mfma_f32_16x16x32_bf16 v[86:89], v[154:157], v[162:165], v[86:89]
	v_mfma_f32_16x16x32_bf16 v[126:129], v[150:153], v[190:193], v[126:129]
	v_mfma_f32_16x16x32_bf16 v[122:125], v[158:161], v[190:193], v[122:125]
	v_mfma_f32_16x16x32_bf16 v[118:121], v[150:153], v[182:185], v[118:121]
	v_mfma_f32_16x16x32_bf16 v[114:117], v[158:161], v[182:185], v[114:117]
	v_mfma_f32_16x16x32_bf16 v[110:113], v[150:153], v[174:177], v[110:113]
	v_mfma_f32_16x16x32_bf16 v[102:105], v[158:161], v[174:177], v[102:105]
	v_mfma_f32_16x16x32_bf16 v[94:97], v[150:153], v[166:169], v[94:97]
	v_mfma_f32_16x16x32_bf16 v[86:89], v[158:161], v[166:169], v[86:89]
	s_setprio 0
	s_setprio 1
	v_mfma_f32_16x16x32_bf16 v[106:109], v[130:133], v[186:189], v[106:109]
	v_mfma_f32_16x16x32_bf16 v[98:101], v[138:141], v[186:189], v[98:101]
	v_mfma_f32_16x16x32_bf16 v[90:93], v[130:133], v[178:181], v[90:93]
	v_mfma_f32_16x16x32_bf16 v[82:85], v[138:141], v[178:181], v[82:85]
	v_mfma_f32_16x16x32_bf16 v[78:81], v[130:133], v[170:173], v[78:81]
	v_mfma_f32_16x16x32_bf16 v[74:77], v[138:141], v[170:173], v[74:77]
	v_mfma_f32_16x16x32_bf16 v[70:73], v[130:133], v[162:165], v[70:73]
	v_mfma_f32_16x16x32_bf16 v[66:69], v[138:141], v[162:165], v[66:69]
	v_mfma_f32_16x16x32_bf16 v[106:109], v[134:137], v[190:193], v[106:109]
	v_mfma_f32_16x16x32_bf16 v[98:101], v[142:145], v[190:193], v[98:101]
	v_mfma_f32_16x16x32_bf16 v[90:93], v[134:137], v[182:185], v[90:93]
	v_mfma_f32_16x16x32_bf16 v[82:85], v[142:145], v[182:185], v[82:85]
	v_mfma_f32_16x16x32_bf16 v[78:81], v[134:137], v[174:177], v[78:81]
	v_mfma_f32_16x16x32_bf16 v[74:77], v[142:145], v[174:177], v[74:77]
	v_mfma_f32_16x16x32_bf16 v[70:73], v[134:137], v[166:169], v[70:73]
	v_mfma_f32_16x16x32_bf16 v[66:69], v[142:145], v[166:169], v[66:69]
	s_setprio 0
	s_barrier
	ds_read_b128 v[186:189], v232 offset:16384
	ds_read_b128 v[190:193], v232 offset:17408
	ds_read_b128 v[178:181], v232 offset:18432
	ds_read_b128 v[182:185], v232 offset:19456
	ds_read_b128 v[170:173], v232 offset:20480
	ds_read_b128 v[174:177], v232 offset:21504
	ds_read_b128 v[162:165], v232 offset:22528
	ds_read_b128 v[166:169], v232 offset:23552
	s_mov_b32 m0, s23
	v_lshl_add_u64 v[228:229], s[12:13], 0, v[214:215]
	s_add_u32 s40, s12, 0xb0000
	global_load_lds_dwordx4 v[228:229], off
	v_lshl_add_u64 v[226:227], s[12:13], 0, v[210:211]
	s_mov_b32 m0, s24
	s_addc_u32 s41, s13, 0
	global_load_lds_dwordx4 v[226:227], off
	v_lshl_add_u64 v[194:195], s[40:41], 0, v[214:215]
	s_mov_b32 m0, s25
	v_lshl_add_u64 v[222:223], s[14:15], 0, v[216:217]
	global_load_lds_dwordx4 v[194:195], off
	v_lshl_add_u64 v[194:195], s[40:41], 0, v[210:211]
	s_mov_b32 m0, s26
	v_lshl_add_u64 v[224:225], s[14:15], 0, v[212:213]
	global_load_lds_dwordx4 v[194:195], off
	s_mov_b32 m0, s22
	s_andn2_b64 vcc, exec, s[16:17]
	global_load_lds_dwordx4 v[222:223], off
	s_mov_b32 m0, s28
	s_nop 0
	global_load_lds_dwordx4 v[224:225], off
	s_waitcnt vmcnt(24)
	s_cbranch_vccnz .LBB0_304
	s_waitcnt vmcnt(8)
	s_branch .LBB0_304

; #define PG8_STAGE(bufoff, gbase, voff) do { _Pragma("unroll") for (int _i = 0; _i < 2; ++_i) \
;         __builtin_amdgcn_global_load_lds((const unsigned*)((const char*)(gbase) + (voff)[_i]), (PG8_LAS unsigned*)(lds + (bufoff) + ldsw + _i * 8192), 16, 0, 0); } while (0)
; #define PG8_LDA(dst, b, h) do { _Pragma("unroll") for (int m = 0; m < 4; ++m) _Pragma("unroll") for (int k = 0; k < 2; ++k) dst[m][k] = *(const PG8_LAS bf16x8*)(lds + PG8_SA(b, h) + aoff + m * 2048 + k * 1024); } while (0)
; #define PG8_LDB(dst, b, h) do { _Pragma("unroll") for (int n = 0; n < 2; ++n) _Pragma("unroll") for (int k = 0; k < 2; ++k) dst[n][k] = *(const PG8_LAS bf16x8*)(lds + PG8_SB(b, h) + boff + n * 2048 + k * 1024); } while (0)
; #define PG8_MMA(ai, bj, At, Bt) do { __builtin_amdgcn_s_setprio(1); _Pragma("unroll") for (int m = 0; m < 4; ++m) _Pragma("unroll") for (int n = 0; n < 2; ++n) _Pragma("unroll") for (int k = 0; k < 2; ++k) \
;         acc[ai][bj][m][n] = __builtin_amdgcn_mfma_f32_16x16x32_bf16(Bt[n][k], At[m][k], acc[ai][bj][m][n], 0, 0, 0); __builtin_amdgcn_s_setprio(0); } while (0)
; #define PG8_WAIT_V(n) asm volatile("s_waitcnt vmcnt(" #n ")" ::: "memory")
; #define PG8_WAIT_VN(n) asm volatile("s_waitcnt vmcnt(%0)" :: "n"(n) : "memory")
; #define PG8_WAIT_L(n) asm volatile("s_waitcnt lgkmcnt(" #n ")" ::: "memory")
; #define PG8_BAR __builtin_amdgcn_s_barrier()
; #define PG8_SCHED __builtin_amdgcn_sched_barrier(0)
; template <class Epi, class Sched, bool ALIGN_EPI = false, bool SP2 = false>
; __device__ __forceinline__ void gemm_phase(PG8_LAS unsigned char* lds, const Gemm g, const Sched& S, const Epi& E, const int wave_id) {
;     ...
;             PG8_WAIT_VN(8 + Epi::NS); if (strict) PG8_WAIT_V(8); PG8_WAIT_L(0); PG8_BAR; PG8_MMA(1, 0, At, B0); PG8_MMA(1, 1, At, B1); PG8_BAR; PG8_SCHED;
;             PG8_LDB(B0, 1, 0); PG8_LDB(B1, 1, 1); PG8_SCHED; PG8_LDA(At, 1, 0); PG8_STAGE(PG8_SA(0, 1), a2 + hstep, voffA);
.LBB0_420:
	s_waitcnt lgkmcnt(0)
	s_barrier
	s_setprio 1
	s_waitcnt lgkmcnt(0)
	v_mfma_f32_16x16x32_bf16 v[62:65], v[146:149], v[186:189], v[62:65]
	v_mfma_f32_16x16x32_bf16 v[58:61], v[154:157], v[186:189], v[58:61]
	v_mfma_f32_16x16x32_bf16 v[46:49], v[146:149], v[178:181], v[46:49]
	v_mfma_f32_16x16x32_bf16 v[42:45], v[154:157], v[178:181], v[42:45]
	v_mfma_f32_16x16x32_bf16 v[30:33], v[146:149], v[170:173], v[30:33]
	v_mfma_f32_16x16x32_bf16 v[26:29], v[154:157], v[170:173], v[26:29]
	v_mfma_f32_16x16x32_bf16 v[14:17], v[146:149], v[162:165], v[14:17]
	v_mfma_f32_16x16x32_bf16 v[10:13], v[154:157], v[162:165], v[10:13]
	v_mfma_f32_16x16x32_bf16 v[62:65], v[150:153], v[190:193], v[62:65]
	v_mfma_f32_16x16x32_bf16 v[58:61], v[158:161], v[190:193], v[58:61]
	v_mfma_f32_16x16x32_bf16 v[46:49], v[150:153], v[182:185], v[46:49]
	v_mfma_f32_16x16x32_bf16 v[42:45], v[158:161], v[182:185], v[42:45]
	v_mfma_f32_16x16x32_bf16 v[30:33], v[150:153], v[174:177], v[30:33]
	v_mfma_f32_16x16x32_bf16 v[26:29], v[158:161], v[174:177], v[26:29]
	v_mfma_f32_16x16x32_bf16 v[14:17], v[150:153], v[166:169], v[14:17]
	v_mfma_f32_16x16x32_bf16 v[10:13], v[158:161], v[166:169], v[10:13]
	s_setprio 0
	s_setprio 1
	v_mfma_f32_16x16x32_bf16 v[54:57], v[130:133], v[186:189], v[54:57]
	v_mfma_f32_16x16x32_bf16 v[50:53], v[138:141], v[186:189], v[50:53]
	v_mfma_f32_16x16x32_bf16 v[38:41], v[130:133], v[178:181], v[38:41]
	v_mfma_f32_16x16x32_bf16 v[34:37], v[138:141], v[178:181], v[34:37]
	v_mfma_f32_16x16x32_bf16 v[22:25], v[130:133], v[170:173], v[22:25]
	v_mfma_f32_16x16x32_bf16 v[18:21], v[138:141], v[170:173], v[18:21]
	v_mfma_f32_16x16x32_bf16 v[6:9], v[130:133], v[162:165], v[6:9]
	v_mfma_f32_16x16x32_bf16 v[2:5], v[138:141], v[162:165], v[2:5]
	v_mfma_f32_16x16x32_bf16 v[54:57], v[134:137], v[190:193], v[54:57]
	v_mfma_f32_16x16x32_bf16 v[50:53], v[142:145], v[190:193], v[50:53]
	v_mfma_f32_16x16x32_bf16 v[38:41], v[134:137], v[182:185], v[38:41]
	v_mfma_f32_16x16x32_bf16 v[34:37], v[142:145], v[182:185], v[34:37]
	v_mfma_f32_16x16x32_bf16 v[22:25], v[134:137], v[174:177], v[22:25]
	v_mfma_f32_16x16x32_bf16 v[18:21], v[142:145], v[174:177], v[18:21]
	v_mfma_f32_16x16x32_bf16 v[6:9], v[134:137], v[166:169], v[6:9]
	v_mfma_f32_16x16x32_bf16 v[2:5], v[142:145], v[166:169], v[2:5]
	s_setprio 0
	s_barrier
	ds_read_b128 v[162:165], v247 offset:32768
	ds_read_b128 v[166:169], v247 offset:33792
	ds_read_b128 v[170:173], v247 offset:34816
	ds_read_b128 v[174:177], v247 offset:35840
	ds_read_b128 v[178:181], v247 offset:36864
	ds_read_b128 v[182:185], v247 offset:37888
	ds_read_b128 v[186:189], v247 offset:38912
	ds_read_b128 v[190:193], v247 offset:39936
	s_add_i32 s34, 0, 0x18000
	s_add_i32 s35, 0, 0x1c000
	v_add_u32_e32 v142, s34, v246
	v_add_u32_e32 v158, s35, v246
	ds_read_b128 v[130:133], v142
	ds_read_b128 v[134:137], v142 offset:1024
	ds_read_b128 v[138:141], v142 offset:2048
	ds_read_b128 v[142:145], v142 offset:3072
	ds_read_b128 v[146:149], v158
	ds_read_b128 v[150:153], v158 offset:1024
	ds_read_b128 v[154:157], v158 offset:2048
	ds_read_b128 v[158:161], v158 offset:3072
	s_add_u32 s14, s14, 0x40000
	s_addc_u32 s15, s15, 0
	s_mov_b32 m0, s3
	v_lshl_add_u64 v[194:195], s[14:15], 0, v[210:211]
	global_load_lds_dwordx4 v[194:195], off
	v_lshl_add_u64 v[194:195], s[14:15], 0, v[214:215]
	s_mov_b32 m0, s4
	s_nop 0
	global_load_lds_dwordx4 v[194:195], off
	s_waitcnt vmcnt(26)
	s_cmp_eq_u32 s100, 0
	s_cbranch_scc1 .Lthird_wait_relaxed_4
	s_waitcnt vmcnt(8)
; #define PG8_STAGE(bufoff, gbase, voff) do { _Pragma("unroll") for (int _i = 0; _i < 2; ++_i) \
;         __builtin_amdgcn_global_load_lds((const unsigned*)((const char*)(gbase) + (voff)[_i]), (PG8_LAS unsigned*)(lds + (bufoff) + ldsw + _i * 8192), 16, 0, 0); } while (0)
; #define PG8_LDA(dst, b, h) do { _Pragma("unroll") for (int m = 0; m < 4; ++m) _Pragma("unroll") for (int k = 0; k < 2; ++k) dst[m][k] = *(const PG8_LAS bf16x8*)(lds + PG8_SA(b, h) + aoff + m * 2048 + k * 1024); } while (0)
; #define PG8_LDB(dst, b, h) do { _Pragma("unroll") for (int n = 0; n < 2; ++n) _Pragma("unroll") for (int k = 0; k < 2; ++k) dst[n][k] = *(const PG8_LAS bf16x8*)(lds + PG8_SB(b, h) + boff + n * 2048 + k * 1024); } while (0)
; #define PG8_MMA(ai, bj, At, Bt) do { __builtin_amdgcn_s_setprio(1); _Pragma("unroll") for (int m = 0; m < 4; ++m) _Pragma("unroll") for (int n = 0; n < 2; ++n) _Pragma("unroll") for (int k = 0; k < 2; ++k) \
;         acc[ai][bj][m][n] = __builtin_amdgcn_mfma_f32_16x16x32_bf16(Bt[n][k], At[m][k], acc[ai][bj][m][n], 0, 0, 0); __builtin_amdgcn_s_setprio(0); } while (0)
; #define PG8_WAIT_V(n) asm volatile("s_waitcnt vmcnt(" #n ")" ::: "memory")
; #define PG8_WAIT_L(n) asm volatile("s_waitcnt lgkmcnt(" #n ")" ::: "memory")
; #define PG8_BAR __builtin_amdgcn_s_barrier()
; #define PG8_SCHED __builtin_amdgcn_sched_barrier(0)
; template <class Epi, class Sched, bool ALIGN_EPI = false, bool SP2 = false>
; __device__ __forceinline__ void gemm_phase(PG8_LAS unsigned char* lds, const Gemm g, const Sched& S, const Epi& E, const int wave_id) {
;     ...
;         for (int t = 0; t < nt; t += 2) {
;     ...
;             PG8_LDB(B0, 1, 0); PG8_LDB(B1, 1, 1); PG8_SCHED; PG8_LDA(At, 1, 0); PG8_STAGE(PG8_SA(0, 1), a2 + hstep, voffA);
;             PG8_WAIT_V(8); PG8_WAIT_L(0); PG8_BAR; PG8_MMA(0, 0, At, B0); PG8_MMA(0, 1, At, B1); PG8_BAR; PG8_SCHED;
;             PG8_LDA(At, 1, 1); PG8_STAGE(PG8_SB(1, 0), b3, voffB); PG8_STAGE(PG8_SB(1, 1), b3 + hstep, voffB); PG8_STAGE(PG8_SA(1, 0), a3, voffA);
;             PG8_WAIT_V(8); PG8_WAIT_L(0); PG8_BAR; PG8_MMA(1, 0, At, B0); PG8_MMA(1, 1, At, B1); PG8_BAR; PG8_SCHED;
.Lthird_wait_relaxed_4:
	s_waitcnt lgkmcnt(0)
	s_barrier
	s_setprio 1
	s_waitcnt lgkmcnt(0)
	v_mfma_f32_16x16x32_bf16 v[126:129], v[130:133], v[162:165], v[126:129]
	v_mfma_f32_16x16x32_bf16 v[122:125], v[138:141], v[162:165], v[122:125]
	v_mfma_f32_16x16x32_bf16 v[110:113], v[130:133], v[170:173], v[110:113]
	v_mfma_f32_16x16x32_bf16 v[106:109], v[138:141], v[170:173], v[106:109]
	v_mfma_f32_16x16x32_bf16 v[94:97], v[130:133], v[178:181], v[94:97]
	v_mfma_f32_16x16x32_bf16 v[90:93], v[138:141], v[178:181], v[90:93]
	v_mfma_f32_16x16x32_bf16 v[78:81], v[130:133], v[186:189], v[78:81]
	v_mfma_f32_16x16x32_bf16 v[74:77], v[138:141], v[186:189], v[74:77]
	v_mfma_f32_16x16x32_bf16 v[126:129], v[134:137], v[166:169], v[126:129]
	v_mfma_f32_16x16x32_bf16 v[122:125], v[142:145], v[166:169], v[122:125]
	v_mfma_f32_16x16x32_bf16 v[110:113], v[134:137], v[174:177], v[110:113]
	v_mfma_f32_16x16x32_bf16 v[106:109], v[142:145], v[174:177], v[106:109]
	v_mfma_f32_16x16x32_bf16 v[94:97], v[134:137], v[182:185], v[94:97]
	v_mfma_f32_16x16x32_bf16 v[90:93], v[142:145], v[182:185], v[90:93]
	v_mfma_f32_16x16x32_bf16 v[78:81], v[134:137], v[190:193], v[78:81]
	v_mfma_f32_16x16x32_bf16 v[74:77], v[142:145], v[190:193], v[74:77]
	s_setprio 0
	s_setprio 1
	v_mfma_f32_16x16x32_bf16 v[118:121], v[146:149], v[162:165], v[118:121]
	v_mfma_f32_16x16x32_bf16 v[114:117], v[154:157], v[162:165], v[114:117]
	v_mfma_f32_16x16x32_bf16 v[102:105], v[146:149], v[170:173], v[102:105]
	v_mfma_f32_16x16x32_bf16 v[98:101], v[154:157], v[170:173], v[98:101]
	v_mfma_f32_16x16x32_bf16 v[86:89], v[146:149], v[178:181], v[86:89]
	v_mfma_f32_16x16x32_bf16 v[82:85], v[154:157], v[178:181], v[82:85]
	v_mfma_f32_16x16x32_bf16 v[70:73], v[146:149], v[186:189], v[70:73]
	v_mfma_f32_16x16x32_bf16 v[66:69], v[154:157], v[186:189], v[66:69]
	v_mfma_f32_16x16x32_bf16 v[118:121], v[150:153], v[166:169], v[118:121]
	v_mfma_f32_16x16x32_bf16 v[114:117], v[158:161], v[166:169], v[114:117]
	v_mfma_f32_16x16x32_bf16 v[102:105], v[150:153], v[174:177], v[102:105]
	v_mfma_f32_16x16x32_bf16 v[98:101], v[158:161], v[174:177], v[98:101]
	v_mfma_f32_16x16x32_bf16 v[86:89], v[150:153], v[182:185], v[86:89]
	v_mfma_f32_16x16x32_bf16 v[82:85], v[158:161], v[182:185], v[82:85]
	v_mfma_f32_16x16x32_bf16 v[70:73], v[150:153], v[190:193], v[70:73]
	v_mfma_f32_16x16x32_bf16 v[66:69], v[158:161], v[190:193], v[66:69]
	s_setprio 0
	s_barrier
	ds_read_b128 v[162:165], v247 offset:49152
	ds_read_b128 v[166:169], v247 offset:50176
	ds_read_b128 v[170:173], v247 offset:51200
	ds_read_b128 v[174:177], v247 offset:52224
	ds_read_b128 v[178:181], v247 offset:53248
	ds_read_b128 v[182:185], v247 offset:54272
	ds_read_b128 v[186:189], v247 offset:55296
	ds_read_b128 v[190:193], v247 offset:56320
	s_add_i32 s14, s34, s90
	v_lshl_add_u64 v[194:195], v[232:233], 0, s[64:65]
	s_mov_b32 m0, s14
	s_nop 0
	global_load_lds_dwordx4 v[194:195], off
	s_add_i32 m0, s14, 0x2000
	s_add_u32 s12, s12, 0x40080
	v_lshl_add_u64 v[194:195], v[230:231], 0, s[64:65]
	s_addc_u32 s13, s13, 0
	s_add_i32 s14, s35, s90
	global_load_lds_dwordx4 v[194:195], off
	v_lshl_add_u64 v[194:195], s[12:13], 0, v[212:213]
	s_mov_b32 m0, s14
	s_nop 0
	global_load_lds_dwordx4 v[194:195], off
	v_lshl_add_u64 v[194:195], s[12:13], 0, v[216:217]
	s_add_i32 m0, s14, 0x2000
	s_nop 0
	global_load_lds_dwordx4 v[194:195], off
	v_lshl_add_u64 v[194:195], v[226:227], 0, s[64:65]
	s_mov_b32 m0, s63
	s_nop 0
	global_load_lds_dwordx4 v[194:195], off
	v_lshl_add_u64 v[194:195], v[228:229], 0, s[64:65]
	s_mov_b32 m0, s68
	s_nop 0
	global_load_lds_dwordx4 v[194:195], off
	s_waitcnt vmcnt(8)
	s_waitcnt lgkmcnt(0)
	s_barrier
	s_setprio 1
	s_waitcnt lgkmcnt(0)
	v_mfma_f32_16x16x32_bf16 v[62:65], v[130:133], v[162:165], v[62:65]
	v_mfma_f32_16x16x32_bf16 v[58:61], v[138:141], v[162:165], v[58:61]
	v_mfma_f32_16x16x32_bf16 v[46:49], v[130:133], v[170:173], v[46:49]
	v_mfma_f32_16x16x32_bf16 v[42:45], v[138:141], v[170:173], v[42:45]
	v_mfma_f32_16x16x32_bf16 v[30:33], v[130:133], v[178:181], v[30:33]
	v_mfma_f32_16x16x32_bf16 v[26:29], v[138:141], v[178:181], v[26:29]
	v_mfma_f32_16x16x32_bf16 v[14:17], v[130:133], v[186:189], v[14:17]
	v_mfma_f32_16x16x32_bf16 v[10:13], v[138:141], v[186:189], v[10:13]
	v_mfma_f32_16x16x32_bf16 v[62:65], v[134:137], v[166:169], v[62:65]
	v_mfma_f32_16x16x32_bf16 v[58:61], v[142:145], v[166:169], v[58:61]
	v_mfma_f32_16x16x32_bf16 v[46:49], v[134:137], v[174:177], v[46:49]
	v_mfma_f32_16x16x32_bf16 v[42:45], v[142:145], v[174:177], v[42:45]
	v_mfma_f32_16x16x32_bf16 v[30:33], v[134:137], v[182:185], v[30:33]
	v_mfma_f32_16x16x32_bf16 v[26:29], v[142:145], v[182:185], v[26:29]
	v_mfma_f32_16x16x32_bf16 v[14:17], v[134:137], v[190:193], v[14:17]
	v_mfma_f32_16x16x32_bf16 v[10:13], v[142:145], v[190:193], v[10:13]
	s_setprio 0
	s_setprio 1
	v_mfma_f32_16x16x32_bf16 v[54:57], v[146:149], v[162:165], v[54:57]
	v_mfma_f32_16x16x32_bf16 v[50:53], v[154:157], v[162:165], v[50:53]
	v_mfma_f32_16x16x32_bf16 v[38:41], v[146:149], v[170:173], v[38:41]
	v_mfma_f32_16x16x32_bf16 v[34:37], v[154:157], v[170:173], v[34:37]
	v_mfma_f32_16x16x32_bf16 v[22:25], v[146:149], v[178:181], v[22:25]
	v_mfma_f32_16x16x32_bf16 v[18:21], v[154:157], v[178:181], v[18:21]
	v_mfma_f32_16x16x32_bf16 v[6:9], v[146:149], v[186:189], v[6:9]
	v_mfma_f32_16x16x32_bf16 v[2:5], v[154:157], v[186:189], v[2:5]
	v_mfma_f32_16x16x32_bf16 v[54:57], v[150:153], v[166:169], v[54:57]
	v_mfma_f32_16x16x32_bf16 v[50:53], v[158:161], v[166:169], v[50:53]
	v_mfma_f32_16x16x32_bf16 v[38:41], v[150:153], v[174:177], v[38:41]
	v_mfma_f32_16x16x32_bf16 v[34:37], v[158:161], v[174:177], v[34:37]
	v_mfma_f32_16x16x32_bf16 v[22:25], v[150:153], v[182:185], v[22:25]
	v_mfma_f32_16x16x32_bf16 v[18:21], v[158:161], v[182:185], v[18:21]
	v_mfma_f32_16x16x32_bf16 v[6:9], v[150:153], v[190:193], v[6:9]
	v_mfma_f32_16x16x32_bf16 v[2:5], v[158:161], v[190:193], v[2:5]
	s_setprio 0
	s_add_i32 s40, s40, 2
	s_add_u32 s10, s10, 0x100
	s_addc_u32 s11, s11, 0
	s_cmp_gt_u32 s40, 13
	s_barrier
	s_cbranch_scc1 .LBB0_425

; #define PG8_STAGE(bufoff, gbase, voff) do { _Pragma("unroll") for (int _i = 0; _i < 2; ++_i) \
;         __builtin_amdgcn_global_load_lds((const unsigned*)((const char*)(gbase) + (voff)[_i]), (PG8_LAS unsigned*)(lds + (bufoff) + ldsw + _i * 8192), 16, 0, 0); } while (0)
; #define PG8_LDA(dst, b, h) do { _Pragma("unroll") for (int m = 0; m < 4; ++m) _Pragma("unroll") for (int k = 0; k < 2; ++k) dst[m][k] = *(const PG8_LAS bf16x8*)(lds + PG8_SA(b, h) + aoff + m * 2048 + k * 1024); } while (0)
; #define PG8_LDB(dst, b, h) do { _Pragma("unroll") for (int n = 0; n < 2; ++n) _Pragma("unroll") for (int k = 0; k < 2; ++k) dst[n][k] = *(const PG8_LAS bf16x8*)(lds + PG8_SB(b, h) + boff + n * 2048 + k * 1024); } while (0)
; #define PG8_MMA(ai, bj, At, Bt) do { __builtin_amdgcn_s_setprio(1); _Pragma("unroll") for (int m = 0; m < 4; ++m) _Pragma("unroll") for (int n = 0; n < 2; ++n) _Pragma("unroll") for (int k = 0; k < 2; ++k) \
;         acc[ai][bj][m][n] = __builtin_amdgcn_mfma_f32_16x16x32_bf16(Bt[n][k], At[m][k], acc[ai][bj][m][n], 0, 0, 0); __builtin_amdgcn_s_setprio(0); } while (0)
; #define PG8_WAIT_V(n) asm volatile("s_waitcnt vmcnt(" #n ")" ::: "memory")
; #define PG8_WAIT_VN(n) asm volatile("s_waitcnt vmcnt(%0)" :: "n"(n) : "memory")
; template <class Epi, class Sched, bool ALIGN_EPI = false, bool SP2 = false>
; __device__ __forceinline__ void gemm_phase(PG8_LAS unsigned char* lds, const Gemm g, const Sched& S, const Epi& E, const int wave_id) {
;     ...
;             const bool last = (t == nt - 2);
;             const char* a1 = cA + (size_t)(t + 1) * kstep;
;             const char* a2 = last ? nA : cA + (size_t)(t + 2) * kstep; const char* b2 = last ? nB : cB + (size_t)(t + 2) * kstep;
;             const char* a3 = a2 + kstep; const char* b3 = b2 + kstep;
;     ...
;             PG8_LDB(B0, 0, 0); PG8_LDB(B1, 0, 1); PG8_SCHED; PG8_LDA(At, 0, 0); PG8_STAGE(PG8_SA(1, 1), a1 + hstep, voffA);
;             PG8_WAIT_VN(8 + Epi::NS); if (strict) PG8_WAIT_V(8); PG8_WAIT_L(0); PG8_BAR; PG8_MMA(0, 0, At, B0); PG8_MMA(0, 1, At, B1); PG8_BAR; PG8_SCHED;
;             PG8_LDA(At, 0, 1); PG8_STAGE(PG8_SB(0, 0), b2, voffB); PG8_STAGE(PG8_SB(0, 1), b2 + hstep, voffB); PG8_STAGE(PG8_SA(0, 0), a2, voffA);
;             PG8_WAIT_VN(8 + Epi::NS); if (strict) PG8_WAIT_V(8); PG8_WAIT_L(0); PG8_BAR; PG8_MMA(1, 0, At, B0); PG8_MMA(1, 1, At, B1); PG8_BAR; PG8_SCHED;
.LBB0_423:
	s_add_u32 s12, s8, s10
	s_addc_u32 s13, s9, s11
	s_add_u32 s12, s12, 0x100
	s_addc_u32 s13, s13, 0
	s_add_u32 s41, s36, s10
	s_addc_u32 s42, s37, s11
	s_waitcnt lgkmcnt(0)
	s_cmpk_eq_i32 s10, 0x700
	s_cselect_b32 s15, s23, s13
	s_cselect_b32 s14, s29, s12
	s_cselect_b32 s13, s21, s42
	s_cselect_b32 s12, s31, s41
	s_barrier
	s_setprio 1
	s_waitcnt lgkmcnt(0)
	v_mfma_f32_16x16x32_bf16 v[126:129], v[146:149], v[186:189], v[126:129]
	v_mfma_f32_16x16x32_bf16 v[122:125], v[154:157], v[186:189], v[122:125]
	v_mfma_f32_16x16x32_bf16 v[110:113], v[146:149], v[178:181], v[110:113]
	v_mfma_f32_16x16x32_bf16 v[106:109], v[154:157], v[178:181], v[106:109]
	v_mfma_f32_16x16x32_bf16 v[94:97], v[146:149], v[170:173], v[94:97]
	v_mfma_f32_16x16x32_bf16 v[90:93], v[154:157], v[170:173], v[90:93]
	v_mfma_f32_16x16x32_bf16 v[78:81], v[146:149], v[162:165], v[78:81]
	v_mfma_f32_16x16x32_bf16 v[74:77], v[154:157], v[162:165], v[74:77]
	v_mfma_f32_16x16x32_bf16 v[126:129], v[150:153], v[190:193], v[126:129]
	v_mfma_f32_16x16x32_bf16 v[122:125], v[158:161], v[190:193], v[122:125]
	v_mfma_f32_16x16x32_bf16 v[110:113], v[150:153], v[182:185], v[110:113]
	v_mfma_f32_16x16x32_bf16 v[106:109], v[158:161], v[182:185], v[106:109]
	v_mfma_f32_16x16x32_bf16 v[94:97], v[150:153], v[174:177], v[94:97]
	v_mfma_f32_16x16x32_bf16 v[90:93], v[158:161], v[174:177], v[90:93]
	v_mfma_f32_16x16x32_bf16 v[78:81], v[150:153], v[166:169], v[78:81]
	v_mfma_f32_16x16x32_bf16 v[74:77], v[158:161], v[166:169], v[74:77]
	s_setprio 0
	s_setprio 1
	v_mfma_f32_16x16x32_bf16 v[118:121], v[130:133], v[186:189], v[118:121]
	v_mfma_f32_16x16x32_bf16 v[114:117], v[138:141], v[186:189], v[114:117]
	v_mfma_f32_16x16x32_bf16 v[102:105], v[130:133], v[178:181], v[102:105]
	v_mfma_f32_16x16x32_bf16 v[98:101], v[138:141], v[178:181], v[98:101]
	v_mfma_f32_16x16x32_bf16 v[86:89], v[130:133], v[170:173], v[86:89]
	v_mfma_f32_16x16x32_bf16 v[82:85], v[138:141], v[170:173], v[82:85]
	v_mfma_f32_16x16x32_bf16 v[70:73], v[130:133], v[162:165], v[70:73]
	v_mfma_f32_16x16x32_bf16 v[66:69], v[138:141], v[162:165], v[66:69]
	v_mfma_f32_16x16x32_bf16 v[118:121], v[134:137], v[190:193], v[118:121]
	v_mfma_f32_16x16x32_bf16 v[114:117], v[142:145], v[190:193], v[114:117]
	v_mfma_f32_16x16x32_bf16 v[102:105], v[134:137], v[182:185], v[102:105]
	v_mfma_f32_16x16x32_bf16 v[98:101], v[142:145], v[182:185], v[98:101]
	v_mfma_f32_16x16x32_bf16 v[86:89], v[134:137], v[174:177], v[86:89]
	v_mfma_f32_16x16x32_bf16 v[82:85], v[142:145], v[174:177], v[82:85]
	v_mfma_f32_16x16x32_bf16 v[70:73], v[134:137], v[166:169], v[70:73]
	v_mfma_f32_16x16x32_bf16 v[66:69], v[142:145], v[166:169], v[66:69]
	s_setprio 0
	s_barrier
	ds_read_b128 v[186:189], v247 offset:16384
	ds_read_b128 v[190:193], v247 offset:17408
	ds_read_b128 v[178:181], v247 offset:18432
	ds_read_b128 v[182:185], v247 offset:19456
	ds_read_b128 v[170:173], v247 offset:20480
	ds_read_b128 v[174:177], v247 offset:21504
	ds_read_b128 v[162:165], v247 offset:22528
	ds_read_b128 v[166:169], v247 offset:23552
	s_mov_b32 m0, s94
	v_lshl_add_u64 v[232:233], s[12:13], 0, v[212:213]
	s_add_u32 s42, s12, 0x40000
	global_load_lds_dwordx4 v[232:233], off
	v_lshl_add_u64 v[230:231], s[12:13], 0, v[216:217]
	s_mov_b32 m0, s95
	s_addc_u32 s43, s13, 0
	global_load_lds_dwordx4 v[230:231], off
	v_lshl_add_u64 v[194:195], s[42:43], 0, v[212:213]
	s_mov_b32 m0, s38
	v_lshl_add_u64 v[226:227], s[14:15], 0, v[210:211]
	global_load_lds_dwordx4 v[194:195], off
	v_lshl_add_u64 v[194:195], s[42:43], 0, v[216:217]
	s_mov_b32 m0, s39
	v_lshl_add_u64 v[228:229], s[14:15], 0, v[214:215]
	global_load_lds_dwordx4 v[194:195], off
	s_mov_b32 m0, s91
	s_andn2_b64 vcc, exec, s[34:35]
	global_load_lds_dwordx4 v[226:227], off
	s_mov_b32 m0, s2
	s_nop 0
	global_load_lds_dwordx4 v[228:229], off
	s_waitcnt vmcnt(24)
	s_cbranch_vccnz .LBB0_420
	s_waitcnt vmcnt(8)
	s_branch .LBB0_420

; #define PG8_STAGE(bufoff, gbase, voff) do { _Pragma("unroll") for (int _i = 0; _i < 2; ++_i) \
;         __builtin_amdgcn_global_load_lds((const unsigned*)((const char*)(gbase) + (voff)[_i]), (PG8_LAS unsigned*)(lds + (bufoff) + ldsw + _i * 8192), 16, 0, 0); } while (0)
; #define PG8_LDA(dst, b, h) do { _Pragma("unroll") for (int m = 0; m < 4; ++m) _Pragma("unroll") for (int k = 0; k < 2; ++k) dst[m][k] = *(const PG8_LAS bf16x8*)(lds + PG8_SA(b, h) + aoff + m * 2048 + k * 1024); } while (0)
; #define PG8_LDB(dst, b, h) do { _Pragma("unroll") for (int n = 0; n < 2; ++n) _Pragma("unroll") for (int k = 0; k < 2; ++k) dst[n][k] = *(const PG8_LAS bf16x8*)(lds + PG8_SB(b, h) + boff + n * 2048 + k * 1024); } while (0)
; #define PG8_MMA(ai, bj, At, Bt) do { __builtin_amdgcn_s_setprio(1); _Pragma("unroll") for (int m = 0; m < 4; ++m) _Pragma("unroll") for (int n = 0; n < 2; ++n) _Pragma("unroll") for (int k = 0; k < 2; ++k) \
;         acc[ai][bj][m][n] = __builtin_amdgcn_mfma_f32_16x16x32_bf16(Bt[n][k], At[m][k], acc[ai][bj][m][n], 0, 0, 0); __builtin_amdgcn_s_setprio(0); } while (0)
; #define PG8_WAIT_V(n) asm volatile("s_waitcnt vmcnt(" #n ")" ::: "memory")
; #define PG8_WAIT_L(n) asm volatile("s_waitcnt lgkmcnt(" #n ")" ::: "memory")
; #define PG8_BAR __builtin_amdgcn_s_barrier()
; #define PG8_SCHED __builtin_amdgcn_sched_barrier(0)
; template <class Epi, class Sched, bool ALIGN_EPI = false, bool SP2 = false>
; __device__ __forceinline__ void gemm_phase(PG8_LAS unsigned char* lds, const Gemm g, const Sched& S, const Epi& E, const int wave_id) {
;     ...
;             PG8_LDB(B0, 1, 0); PG8_LDB(B1, 1, 1); PG8_SCHED; PG8_LDA(At, 1, 0); PG8_STAGE(PG8_SA(0, 1), a2 + hstep, voffA);
;             PG8_WAIT_V(8); PG8_WAIT_L(0); PG8_BAR; PG8_MMA(0, 0, At, B0); PG8_MMA(0, 1, At, B1); PG8_BAR; PG8_SCHED;
.LBB0_1504:
	s_waitcnt lgkmcnt(0)
	s_barrier
	s_setprio 1
	s_waitcnt lgkmcnt(0)
	v_mfma_f32_16x16x32_bf16 v[62:65], v[146:149], v[186:189], v[62:65]
	v_mfma_f32_16x16x32_bf16 v[58:61], v[154:157], v[186:189], v[58:61]
	v_mfma_f32_16x16x32_bf16 v[46:49], v[146:149], v[178:181], v[46:49]
	v_mfma_f32_16x16x32_bf16 v[42:45], v[154:157], v[178:181], v[42:45]
	v_mfma_f32_16x16x32_bf16 v[30:33], v[146:149], v[170:173], v[30:33]
	v_mfma_f32_16x16x32_bf16 v[26:29], v[154:157], v[170:173], v[26:29]
	v_mfma_f32_16x16x32_bf16 v[14:17], v[146:149], v[162:165], v[14:17]
	v_mfma_f32_16x16x32_bf16 v[10:13], v[154:157], v[162:165], v[10:13]
	v_mfma_f32_16x16x32_bf16 v[62:65], v[150:153], v[190:193], v[62:65]
	v_mfma_f32_16x16x32_bf16 v[58:61], v[158:161], v[190:193], v[58:61]
	v_mfma_f32_16x16x32_bf16 v[46:49], v[150:153], v[182:185], v[46:49]
	v_mfma_f32_16x16x32_bf16 v[42:45], v[158:161], v[182:185], v[42:45]
	v_mfma_f32_16x16x32_bf16 v[30:33], v[150:153], v[174:177], v[30:33]
	v_mfma_f32_16x16x32_bf16 v[26:29], v[158:161], v[174:177], v[26:29]
	v_mfma_f32_16x16x32_bf16 v[14:17], v[150:153], v[166:169], v[14:17]
	v_mfma_f32_16x16x32_bf16 v[10:13], v[158:161], v[166:169], v[10:13]
	s_setprio 0
	s_setprio 1
	v_mfma_f32_16x16x32_bf16 v[54:57], v[130:133], v[186:189], v[54:57]
	v_mfma_f32_16x16x32_bf16 v[50:53], v[138:141], v[186:189], v[50:53]
	v_mfma_f32_16x16x32_bf16 v[38:41], v[130:133], v[178:181], v[38:41]
	v_mfma_f32_16x16x32_bf16 v[34:37], v[138:141], v[178:181], v[34:37]
	v_mfma_f32_16x16x32_bf16 v[22:25], v[130:133], v[170:173], v[22:25]
	v_mfma_f32_16x16x32_bf16 v[18:21], v[138:141], v[170:173], v[18:21]
	v_mfma_f32_16x16x32_bf16 v[6:9], v[130:133], v[162:165], v[6:9]
	v_mfma_f32_16x16x32_bf16 v[2:5], v[138:141], v[162:165], v[2:5]
	v_mfma_f32_16x16x32_bf16 v[54:57], v[134:137], v[190:193], v[54:57]
	v_mfma_f32_16x16x32_bf16 v[50:53], v[142:145], v[190:193], v[50:53]
	v_mfma_f32_16x16x32_bf16 v[38:41], v[134:137], v[182:185], v[38:41]
	v_mfma_f32_16x16x32_bf16 v[34:37], v[142:145], v[182:185], v[34:37]
	v_mfma_f32_16x16x32_bf16 v[22:25], v[134:137], v[174:177], v[22:25]
	v_mfma_f32_16x16x32_bf16 v[18:21], v[142:145], v[174:177], v[18:21]
	v_mfma_f32_16x16x32_bf16 v[6:9], v[134:137], v[166:169], v[6:9]
	v_mfma_f32_16x16x32_bf16 v[2:5], v[142:145], v[166:169], v[2:5]
	s_setprio 0
	s_barrier
	ds_read_b128 v[162:165], v232 offset:32768
	ds_read_b128 v[166:169], v232 offset:33792
	ds_read_b128 v[170:173], v232 offset:34816
	ds_read_b128 v[174:177], v232 offset:35840
	ds_read_b128 v[178:181], v232 offset:36864
	ds_read_b128 v[182:185], v232 offset:37888
	ds_read_b128 v[186:189], v232 offset:38912
	ds_read_b128 v[190:193], v232 offset:39936
	s_add_i32 s20, 0, 0x18000
	s_add_i32 s21, 0, 0x1c000
	v_add_u32_e32 v142, s20, v1
	v_add_u32_e32 v158, s21, v1
	ds_read_b128 v[130:133], v142
	ds_read_b128 v[134:137], v142 offset:1024
	ds_read_b128 v[138:141], v142 offset:2048
	ds_read_b128 v[142:145], v142 offset:3072
	ds_read_b128 v[146:149], v158
	ds_read_b128 v[150:153], v158 offset:1024
	ds_read_b128 v[154:157], v158 offset:2048
	ds_read_b128 v[158:161], v158 offset:3072
	s_add_u32 s18, s18, 0x40000
	s_addc_u32 s19, s19, 0
	s_mov_b32 m0, s35
	v_lshl_add_u64 v[194:195], s[18:19], 0, v[216:217]
	global_load_lds_dwordx4 v[194:195], off
	v_lshl_add_u64 v[194:195], s[18:19], 0, v[212:213]
	s_mov_b32 m0, s36
	s_nop 0
	global_load_lds_dwordx4 v[194:195], off
	s_waitcnt vmcnt(8)
	s_waitcnt lgkmcnt(0)
	s_barrier
	s_setprio 1
	s_waitcnt lgkmcnt(0)
	v_mfma_f32_16x16x32_bf16 v[126:129], v[130:133], v[162:165], v[126:129]
	v_mfma_f32_16x16x32_bf16 v[122:125], v[138:141], v[162:165], v[122:125]
	v_mfma_f32_16x16x32_bf16 v[110:113], v[130:133], v[170:173], v[110:113]
	v_mfma_f32_16x16x32_bf16 v[106:109], v[138:141], v[170:173], v[106:109]
	v_mfma_f32_16x16x32_bf16 v[94:97], v[130:133], v[178:181], v[94:97]
	v_mfma_f32_16x16x32_bf16 v[90:93], v[138:141], v[178:181], v[90:93]
	v_mfma_f32_16x16x32_bf16 v[78:81], v[130:133], v[186:189], v[78:81]
	v_mfma_f32_16x16x32_bf16 v[74:77], v[138:141], v[186:189], v[74:77]
	v_mfma_f32_16x16x32_bf16 v[126:129], v[134:137], v[166:169], v[126:129]
	v_mfma_f32_16x16x32_bf16 v[122:125], v[142:145], v[166:169], v[122:125]
	v_mfma_f32_16x16x32_bf16 v[110:113], v[134:137], v[174:177], v[110:113]
	v_mfma_f32_16x16x32_bf16 v[106:109], v[142:145], v[174:177], v[106:109]
	v_mfma_f32_16x16x32_bf16 v[94:97], v[134:137], v[182:185], v[94:97]
	v_mfma_f32_16x16x32_bf16 v[90:93], v[142:145], v[182:185], v[90:93]
	v_mfma_f32_16x16x32_bf16 v[78:81], v[134:137], v[190:193], v[78:81]
	v_mfma_f32_16x16x32_bf16 v[74:77], v[142:145], v[190:193], v[74:77]
	s_setprio 0
	s_setprio 1
	v_mfma_f32_16x16x32_bf16 v[118:121], v[146:149], v[162:165], v[118:121]
	v_mfma_f32_16x16x32_bf16 v[114:117], v[154:157], v[162:165], v[114:117]
	v_mfma_f32_16x16x32_bf16 v[102:105], v[146:149], v[170:173], v[102:105]
	v_mfma_f32_16x16x32_bf16 v[98:101], v[154:157], v[170:173], v[98:101]
	v_mfma_f32_16x16x32_bf16 v[86:89], v[146:149], v[178:181], v[86:89]
	v_mfma_f32_16x16x32_bf16 v[82:85], v[154:157], v[178:181], v[82:85]
	v_mfma_f32_16x16x32_bf16 v[70:73], v[146:149], v[186:189], v[70:73]
	v_mfma_f32_16x16x32_bf16 v[66:69], v[154:157], v[186:189], v[66:69]
	v_mfma_f32_16x16x32_bf16 v[118:121], v[150:153], v[166:169], v[118:121]
	v_mfma_f32_16x16x32_bf16 v[114:117], v[158:161], v[166:169], v[114:117]
	v_mfma_f32_16x16x32_bf16 v[102:105], v[150:153], v[174:177], v[102:105]
	v_mfma_f32_16x16x32_bf16 v[98:101], v[158:161], v[174:177], v[98:101]
	v_mfma_f32_16x16x32_bf16 v[86:89], v[150:153], v[182:185], v[86:89]
	v_mfma_f32_16x16x32_bf16 v[82:85], v[158:161], v[182:185], v[82:85]
	v_mfma_f32_16x16x32_bf16 v[70:73], v[150:153], v[190:193], v[70:73]
	v_mfma_f32_16x16x32_bf16 v[66:69], v[158:161], v[190:193], v[66:69]
	s_setprio 0
	s_barrier
; #define PG8_STAGE(bufoff, gbase, voff) do { _Pragma("unroll") for (int _i = 0; _i < 2; ++_i) \
;         __builtin_amdgcn_global_load_lds((const unsigned*)((const char*)(gbase) + (voff)[_i]), (PG8_LAS unsigned*)(lds + (bufoff) + ldsw + _i * 8192), 16, 0, 0); } while (0)
; #define PG8_LDA(dst, b, h) do { _Pragma("unroll") for (int m = 0; m < 4; ++m) _Pragma("unroll") for (int k = 0; k < 2; ++k) dst[m][k] = *(const PG8_LAS bf16x8*)(lds + PG8_SA(b, h) + aoff + m * 2048 + k * 1024); } while (0)
; #define PG8_MMA(ai, bj, At, Bt) do { __builtin_amdgcn_s_setprio(1); _Pragma("unroll") for (int m = 0; m < 4; ++m) _Pragma("unroll") for (int n = 0; n < 2; ++n) _Pragma("unroll") for (int k = 0; k < 2; ++k) \
;         acc[ai][bj][m][n] = __builtin_amdgcn_mfma_f32_16x16x32_bf16(Bt[n][k], At[m][k], acc[ai][bj][m][n], 0, 0, 0); __builtin_amdgcn_s_setprio(0); } while (0)
; #define PG8_WAIT_V(n) asm volatile("s_waitcnt vmcnt(" #n ")" ::: "memory")
; #define PG8_WAIT_L(n) asm volatile("s_waitcnt lgkmcnt(" #n ")" ::: "memory")
; #define PG8_BAR __builtin_amdgcn_s_barrier()
; #define PG8_SCHED __builtin_amdgcn_sched_barrier(0)
; template <class Epi, class Sched, bool ALIGN_EPI = false, bool SP2 = false>
; __device__ __forceinline__ void gemm_phase(PG8_LAS unsigned char* lds, const Gemm g, const Sched& S, const Epi& E, const int wave_id) {
;     ...
;         for (int t = 0; t < nt; t += 2) {
;     ...
;             PG8_LDA(At, 1, 1); PG8_STAGE(PG8_SB(1, 0), b3, voffB); PG8_STAGE(PG8_SB(1, 1), b3 + hstep, voffB); PG8_STAGE(PG8_SA(1, 0), a3, voffA);
;             PG8_WAIT_V(8); PG8_WAIT_L(0); PG8_BAR; PG8_MMA(1, 0, At, B0); PG8_MMA(1, 1, At, B1); PG8_BAR; PG8_SCHED;
	ds_read_b128 v[162:165], v232 offset:49152
	ds_read_b128 v[166:169], v232 offset:50176
	ds_read_b128 v[170:173], v232 offset:51200
	ds_read_b128 v[174:177], v232 offset:52224
	ds_read_b128 v[178:181], v232 offset:53248
	ds_read_b128 v[182:185], v232 offset:54272
	ds_read_b128 v[186:189], v232 offset:55296
	ds_read_b128 v[190:193], v232 offset:56320
	s_add_i32 s18, s20, s24
	v_lshl_add_u64 v[194:195], v[228:229], 0, s[64:65]
	s_mov_b32 m0, s18
	s_nop 0
	global_load_lds_dwordx4 v[194:195], off
	s_add_i32 m0, s18, 0x2000
	s_add_u32 s16, s16, 0x40080
	v_lshl_add_u64 v[194:195], v[226:227], 0, s[64:65]
	s_addc_u32 s17, s17, 0
	s_add_i32 s18, s21, s24
	global_load_lds_dwordx4 v[194:195], off
	v_lshl_add_u64 v[194:195], s[16:17], 0, v[214:215]
	s_mov_b32 m0, s18
	s_nop 0
	global_load_lds_dwordx4 v[194:195], off
	v_lshl_add_u64 v[194:195], s[16:17], 0, v[210:211]
	s_add_i32 m0, s18, 0x2000
	s_nop 0
	global_load_lds_dwordx4 v[194:195], off
	v_lshl_add_u64 v[194:195], v[222:223], 0, s[64:65]
	s_mov_b32 m0, s37
	s_nop 0
	global_load_lds_dwordx4 v[194:195], off
	v_lshl_add_u64 v[194:195], v[224:225], 0, s[64:65]
	s_mov_b32 m0, s38
	s_nop 0
	global_load_lds_dwordx4 v[194:195], off
	s_waitcnt vmcnt(8)
	s_waitcnt lgkmcnt(0)
	s_barrier
	s_setprio 1
	s_waitcnt lgkmcnt(0)
	v_mfma_f32_16x16x32_bf16 v[62:65], v[130:133], v[162:165], v[62:65]
	v_mfma_f32_16x16x32_bf16 v[58:61], v[138:141], v[162:165], v[58:61]
	v_mfma_f32_16x16x32_bf16 v[46:49], v[130:133], v[170:173], v[46:49]
	v_mfma_f32_16x16x32_bf16 v[42:45], v[138:141], v[170:173], v[42:45]
	v_mfma_f32_16x16x32_bf16 v[30:33], v[130:133], v[178:181], v[30:33]
	v_mfma_f32_16x16x32_bf16 v[26:29], v[138:141], v[178:181], v[26:29]
	v_mfma_f32_16x16x32_bf16 v[14:17], v[130:133], v[186:189], v[14:17]
	v_mfma_f32_16x16x32_bf16 v[10:13], v[138:141], v[186:189], v[10:13]
	v_mfma_f32_16x16x32_bf16 v[62:65], v[134:137], v[166:169], v[62:65]
	v_mfma_f32_16x16x32_bf16 v[58:61], v[142:145], v[166:169], v[58:61]
	v_mfma_f32_16x16x32_bf16 v[46:49], v[134:137], v[174:177], v[46:49]
	v_mfma_f32_16x16x32_bf16 v[42:45], v[142:145], v[174:177], v[42:45]
	v_mfma_f32_16x16x32_bf16 v[30:33], v[134:137], v[182:185], v[30:33]
	v_mfma_f32_16x16x32_bf16 v[26:29], v[142:145], v[182:185], v[26:29]
	v_mfma_f32_16x16x32_bf16 v[14:17], v[134:137], v[190:193], v[14:17]
	v_mfma_f32_16x16x32_bf16 v[10:13], v[142:145], v[190:193], v[10:13]
	s_setprio 0
	s_setprio 1
	v_mfma_f32_16x16x32_bf16 v[54:57], v[146:149], v[162:165], v[54:57]
	v_mfma_f32_16x16x32_bf16 v[50:53], v[154:157], v[162:165], v[50:53]
	v_mfma_f32_16x16x32_bf16 v[38:41], v[146:149], v[170:173], v[38:41]
	v_mfma_f32_16x16x32_bf16 v[34:37], v[154:157], v[170:173], v[34:37]
	v_mfma_f32_16x16x32_bf16 v[22:25], v[146:149], v[178:181], v[22:25]
	v_mfma_f32_16x16x32_bf16 v[18:21], v[154:157], v[178:181], v[18:21]
	v_mfma_f32_16x16x32_bf16 v[6:9], v[146:149], v[186:189], v[6:9]
	v_mfma_f32_16x16x32_bf16 v[2:5], v[154:157], v[186:189], v[2:5]
	v_mfma_f32_16x16x32_bf16 v[54:57], v[150:153], v[166:169], v[54:57]
	v_mfma_f32_16x16x32_bf16 v[50:53], v[158:161], v[166:169], v[50:53]
	v_mfma_f32_16x16x32_bf16 v[38:41], v[150:153], v[174:177], v[38:41]
	v_mfma_f32_16x16x32_bf16 v[34:37], v[158:161], v[174:177], v[34:37]
	v_mfma_f32_16x16x32_bf16 v[22:25], v[150:153], v[182:185], v[22:25]
	v_mfma_f32_16x16x32_bf16 v[18:21], v[158:161], v[182:185], v[18:21]
	v_mfma_f32_16x16x32_bf16 v[6:9], v[150:153], v[190:193], v[6:9]
	v_mfma_f32_16x16x32_bf16 v[2:5], v[158:161], v[190:193], v[2:5]
	s_setprio 0
	s_barrier
	s_add_u32 s12, s12, 0x100
	s_addc_u32 s13, s13, 0
	s_cmp_gt_u32 s43, 13
	s_cbranch_scc1 .LBB0_1526

; #define PG8_STAGE(bufoff, gbase, voff) do { _Pragma("unroll") for (int _i = 0; _i < 2; ++_i) \
;         __builtin_amdgcn_global_load_lds((const unsigned*)((const char*)(gbase) + (voff)[_i]), (PG8_LAS unsigned*)(lds + (bufoff) + ldsw + _i * 8192), 16, 0, 0); } while (0)
; #define PG8_LDA(dst, b, h) do { _Pragma("unroll") for (int m = 0; m < 4; ++m) _Pragma("unroll") for (int k = 0; k < 2; ++k) dst[m][k] = *(const PG8_LAS bf16x8*)(lds + PG8_SA(b, h) + aoff + m * 2048 + k * 1024); } while (0)
; #define PG8_LDB(dst, b, h) do { _Pragma("unroll") for (int n = 0; n < 2; ++n) _Pragma("unroll") for (int k = 0; k < 2; ++k) dst[n][k] = *(const PG8_LAS bf16x8*)(lds + PG8_SB(b, h) + boff + n * 2048 + k * 1024); } while (0)
; #define PG8_MMA(ai, bj, At, Bt) do { __builtin_amdgcn_s_setprio(1); _Pragma("unroll") for (int m = 0; m < 4; ++m) _Pragma("unroll") for (int n = 0; n < 2; ++n) _Pragma("unroll") for (int k = 0; k < 2; ++k) \
;         acc[ai][bj][m][n] = __builtin_amdgcn_mfma_f32_16x16x32_bf16(Bt[n][k], At[m][k], acc[ai][bj][m][n], 0, 0, 0); __builtin_amdgcn_s_setprio(0); } while (0)
; #define PG8_WAIT_V(n) asm volatile("s_waitcnt vmcnt(" #n ")" ::: "memory")
; #define PG8_WAIT_VN(n) asm volatile("s_waitcnt vmcnt(%0)" :: "n"(n) : "memory")
; template <class Epi, class Sched, bool ALIGN_EPI = false, bool SP2 = false>
; __device__ __forceinline__ void gemm_phase(PG8_LAS unsigned char* lds, const Gemm g, const Sched& S, const Epi& E, const int wave_id) {
;     ...
;             const bool last = (t == nt - 2);
;             const char* a1 = cA + (size_t)(t + 1) * kstep;
;             const char* a2 = last ? nA : cA + (size_t)(t + 2) * kstep; const char* b2 = last ? nB : cB + (size_t)(t + 2) * kstep;
;             const char* a3 = a2 + kstep; const char* b3 = b2 + kstep;
;     ...
;             PG8_LDB(B0, 0, 0); PG8_LDB(B1, 0, 1); PG8_SCHED; PG8_LDA(At, 0, 0); PG8_STAGE(PG8_SA(1, 1), a1 + hstep, voffA);
;             PG8_WAIT_VN(8 + Epi::NS); if (strict) PG8_WAIT_V(8); PG8_WAIT_L(0); PG8_BAR; PG8_MMA(0, 0, At, B0); PG8_MMA(0, 1, At, B1); PG8_BAR; PG8_SCHED;
;             PG8_LDA(At, 0, 1); PG8_STAGE(PG8_SB(0, 0), b2, voffB); PG8_STAGE(PG8_SB(0, 1), b2 + hstep, voffB); PG8_STAGE(PG8_SA(0, 0), a2, voffA);
;             PG8_WAIT_VN(8 + Epi::NS); if (strict) PG8_WAIT_V(8); PG8_WAIT_L(0); PG8_BAR; PG8_MMA(1, 0, At, B0); PG8_MMA(1, 1, At, B1); PG8_BAR; PG8_SCHED;
.LBB0_1507:
	s_add_u32 s16, s41, s12
	s_addc_u32 s17, s42, s13
	s_add_u32 s16, s16, 0x8f2c0100
	s_addc_u32 s17, s17, 0
	s_add_u32 s49, s39, s12
	s_addc_u32 s50, s40, s13
	s_waitcnt lgkmcnt(0)
	s_cmpk_eq_i32 s12, 0x700
	s_cselect_b32 s19, s11, s17
	s_cselect_b32 s18, s10, s16
	s_cselect_b32 s17, s9, s50
	s_cselect_b32 s16, s8, s49
	s_barrier
	s_setprio 1
	s_waitcnt lgkmcnt(0)
	v_mfma_f32_16x16x32_bf16 v[126:129], v[146:149], v[186:189], v[126:129]
	v_mfma_f32_16x16x32_bf16 v[122:125], v[154:157], v[186:189], v[122:125]
	v_mfma_f32_16x16x32_bf16 v[110:113], v[146:149], v[178:181], v[110:113]
	v_mfma_f32_16x16x32_bf16 v[106:109], v[154:157], v[178:181], v[106:109]
	v_mfma_f32_16x16x32_bf16 v[94:97], v[146:149], v[170:173], v[94:97]
	v_mfma_f32_16x16x32_bf16 v[90:93], v[154:157], v[170:173], v[90:93]
	v_mfma_f32_16x16x32_bf16 v[78:81], v[146:149], v[162:165], v[78:81]
	v_mfma_f32_16x16x32_bf16 v[74:77], v[154:157], v[162:165], v[74:77]
	v_mfma_f32_16x16x32_bf16 v[126:129], v[150:153], v[190:193], v[126:129]
	v_mfma_f32_16x16x32_bf16 v[122:125], v[158:161], v[190:193], v[122:125]
	v_mfma_f32_16x16x32_bf16 v[110:113], v[150:153], v[182:185], v[110:113]
	v_mfma_f32_16x16x32_bf16 v[106:109], v[158:161], v[182:185], v[106:109]
	v_mfma_f32_16x16x32_bf16 v[94:97], v[150:153], v[174:177], v[94:97]
	v_mfma_f32_16x16x32_bf16 v[90:93], v[158:161], v[174:177], v[90:93]
	v_mfma_f32_16x16x32_bf16 v[78:81], v[150:153], v[166:169], v[78:81]
	v_mfma_f32_16x16x32_bf16 v[74:77], v[158:161], v[166:169], v[74:77]
	s_setprio 0
	s_setprio 1
	v_mfma_f32_16x16x32_bf16 v[118:121], v[130:133], v[186:189], v[118:121]
	v_mfma_f32_16x16x32_bf16 v[114:117], v[138:141], v[186:189], v[114:117]
	v_mfma_f32_16x16x32_bf16 v[102:105], v[130:133], v[178:181], v[102:105]
	v_mfma_f32_16x16x32_bf16 v[98:101], v[138:141], v[178:181], v[98:101]
	v_mfma_f32_16x16x32_bf16 v[86:89], v[130:133], v[170:173], v[86:89]
	v_mfma_f32_16x16x32_bf16 v[82:85], v[138:141], v[170:173], v[82:85]
	v_mfma_f32_16x16x32_bf16 v[70:73], v[130:133], v[162:165], v[70:73]
	v_mfma_f32_16x16x32_bf16 v[66:69], v[138:141], v[162:165], v[66:69]
	v_mfma_f32_16x16x32_bf16 v[118:121], v[134:137], v[190:193], v[118:121]
	v_mfma_f32_16x16x32_bf16 v[114:117], v[142:145], v[190:193], v[114:117]
	v_mfma_f32_16x16x32_bf16 v[102:105], v[134:137], v[182:185], v[102:105]
	v_mfma_f32_16x16x32_bf16 v[98:101], v[142:145], v[182:185], v[98:101]
	v_mfma_f32_16x16x32_bf16 v[86:89], v[134:137], v[174:177], v[86:89]
	v_mfma_f32_16x16x32_bf16 v[82:85], v[142:145], v[174:177], v[82:85]
	v_mfma_f32_16x16x32_bf16 v[70:73], v[134:137], v[166:169], v[70:73]
	v_mfma_f32_16x16x32_bf16 v[66:69], v[142:145], v[166:169], v[66:69]
	s_setprio 0
	s_barrier
	ds_read_b128 v[186:189], v232 offset:16384
	ds_read_b128 v[190:193], v232 offset:17408
	ds_read_b128 v[178:181], v232 offset:18432
	ds_read_b128 v[182:185], v232 offset:19456
	ds_read_b128 v[170:173], v232 offset:20480
	ds_read_b128 v[174:177], v232 offset:21504
	ds_read_b128 v[162:165], v232 offset:22528
	ds_read_b128 v[166:169], v232 offset:23552
	s_mov_b32 m0, s26
	v_lshl_add_u64 v[228:229], s[16:17], 0, v[214:215]
	s_add_u32 s50, s16, 0x40000
	global_load_lds_dwordx4 v[228:229], off
	v_lshl_add_u64 v[226:227], s[16:17], 0, v[210:211]
	s_mov_b32 m0, s27
	s_addc_u32 s51, s17, 0
	global_load_lds_dwordx4 v[226:227], off
	v_lshl_add_u64 v[194:195], s[50:51], 0, v[214:215]
	s_mov_b32 m0, s29
	v_lshl_add_u64 v[222:223], s[18:19], 0, v[216:217]
	global_load_lds_dwordx4 v[194:195], off
	v_lshl_add_u64 v[194:195], s[50:51], 0, v[210:211]
	s_mov_b32 m0, s30
	v_lshl_add_u64 v[224:225], s[18:19], 0, v[212:213]
	global_load_lds_dwordx4 v[194:195], off
	s_mov_b32 m0, s25
	s_andn2_b64 vcc, exec, s[20:21]
	global_load_lds_dwordx4 v[222:223], off
	s_mov_b32 m0, s34
	s_nop 0
	global_load_lds_dwordx4 v[224:225], off
	s_waitcnt vmcnt(24)
	s_cbranch_vccnz .LBB0_1504
	s_waitcnt vmcnt(8)
	s_branch .LBB0_1504

; #define PG8_STAGE(bufoff, gbase, voff) do { _Pragma("unroll") for (int _i = 0; _i < 2; ++_i) \
;         __builtin_amdgcn_global_load_lds((const unsigned*)((const char*)(gbase) + (voff)[_i]), (PG8_LAS unsigned*)(lds + (bufoff) + ldsw + _i * 8192), 16, 0, 0); } while (0)
; #define PG8_LDA(dst, b, h) do { _Pragma("unroll") for (int m = 0; m < 4; ++m) _Pragma("unroll") for (int k = 0; k < 2; ++k) dst[m][k] = *(const PG8_LAS bf16x8*)(lds + PG8_SA(b, h) + aoff + m * 2048 + k * 1024); } while (0)
; #define PG8_LDB(dst, b, h) do { _Pragma("unroll") for (int n = 0; n < 2; ++n) _Pragma("unroll") for (int k = 0; k < 2; ++k) dst[n][k] = *(const PG8_LAS bf16x8*)(lds + PG8_SB(b, h) + boff + n * 2048 + k * 1024); } while (0)
; #define PG8_MMA(ai, bj, At, Bt) do { __builtin_amdgcn_s_setprio(1); _Pragma("unroll") for (int m = 0; m < 4; ++m) _Pragma("unroll") for (int n = 0; n < 2; ++n) _Pragma("unroll") for (int k = 0; k < 2; ++k) \
;         acc[ai][bj][m][n] = __builtin_amdgcn_mfma_f32_16x16x32_bf16(Bt[n][k], At[m][k], acc[ai][bj][m][n], 0, 0, 0); __builtin_amdgcn_s_setprio(0); } while (0)
; #define PG8_WAIT_V(n) asm volatile("s_waitcnt vmcnt(" #n ")" ::: "memory")
; #define PG8_WAIT_VN(n) asm volatile("s_waitcnt vmcnt(%0)" :: "n"(n) : "memory")
; template <class Epi, class Sched, bool ALIGN_EPI = false, bool SP2 = false>
; __device__ __forceinline__ void gemm_phase(PG8_LAS unsigned char* lds, const Gemm g, const Sched& S, const Epi& E, const int wave_id) {
;     ...
;             const char* a2 = last ? nA : cA + (size_t)(t + 2) * kstep; const char* b2 = last ? nB : cB + (size_t)(t + 2) * kstep;
;     ...
;             int tz_ = __builtin_amdgcn_readfirstlane(t | (ui > 0 ? 0 : 1)); asm volatile("" : "+s"(tz_));
;             const bool strict = !(Epi::NS > 0 && tz_ == 0);
;             PG8_LDB(B0, 0, 0); PG8_LDB(B1, 0, 1); PG8_SCHED; PG8_LDA(At, 0, 0); PG8_STAGE(PG8_SA(1, 1), a1 + hstep, voffA);
;             PG8_WAIT_VN(8 + Epi::NS); if (strict) PG8_WAIT_V(8); PG8_WAIT_L(0); PG8_BAR; PG8_MMA(0, 0, At, B0); PG8_MMA(0, 1, At, B1); PG8_BAR; PG8_SCHED;
;             PG8_LDA(At, 0, 1); PG8_STAGE(PG8_SB(0, 0), b2, voffB); PG8_STAGE(PG8_SB(0, 1), b2 + hstep, voffB); PG8_STAGE(PG8_SA(0, 0), a2, voffA);
;             PG8_WAIT_VN(8 + Epi::NS); if (strict) PG8_WAIT_V(8); PG8_WAIT_L(0); PG8_BAR; PG8_MMA(1, 0, At, B0); PG8_MMA(1, 1, At, B1); PG8_BAR; PG8_SCHED;
.LBB0_1537:
	s_add_u32 s12, s8, s10
	s_addc_u32 s13, s9, s11
	s_add_u32 s12, s12, 0x100
	s_addc_u32 s13, s13, 0
	s_add_u32 s53, s67, s10
	s_addc_u32 s76, s68, s11
	s_add_i32 s69, s69, 2
	s_add_i32 s78, 0, 0x10000
	v_add_u32_e32 v147, s69, v146
	s_cmpk_eq_i32 s10, 0x700
	s_cselect_b32 s26, s57, s12
	v_readfirstlane_b32 s12, v147
	s_cselect_b32 s27, s56, s13
	v_add_u32_e32 v147, s78, v163
	s_cselect_b32 s13, s62, s76
	s_cselect_b32 s12, s63, s53
	s_add_i32 s53, 0, 0x14000
	ds_read_b128 v[148:151], v147
	ds_read_b128 v[152:155], v147 offset:1024
	ds_read_b128 v[156:159], v147 offset:2048
	ds_read_b128 v[166:169], v147 offset:3072
	v_add_u32_e32 v147, s53, v163
	ds_read_b128 v[170:173], v147
	ds_read_b128 v[174:177], v147 offset:1024
	ds_read_b128 v[178:181], v147 offset:2048
	ds_read_b128 v[182:185], v147 offset:3072
	v_lshl_add_u64 v[160:161], v[144:145], 0, s[10:11]
	s_add_i32 m0, s17, 0xc000
	ds_read_b128 v[186:189], v164
	ds_read_b128 v[190:193], v164 offset:1024
	ds_read_b128 v[194:197], v164 offset:2048
	ds_read_b128 v[198:201], v164 offset:3072
	ds_read_b128 v[202:205], v164 offset:4096
	ds_read_b128 v[206:209], v164 offset:5120
	ds_read_b128 v[210:213], v164 offset:6144
	ds_read_b128 v[214:217], v164 offset:7168
	global_load_lds_dwordx4 v[160:161], off
	v_lshl_add_u64 v[160:161], v[142:143], 0, s[10:11]
	s_add_i32 m0, s17, 0xe000
	s_nop 0
	global_load_lds_dwordx4 v[160:161], off
	s_waitcnt vmcnt(8)
	s_waitcnt vmcnt(8)
	s_waitcnt lgkmcnt(0)
	s_barrier
	s_setprio 1
	s_waitcnt lgkmcnt(0)
	v_mfma_f32_16x16x32_bf16 v[126:129], v[148:151], v[186:189], v[126:129]
	v_mfma_f32_16x16x32_bf16 v[122:125], v[156:159], v[186:189], v[122:125]
	v_mfma_f32_16x16x32_bf16 v[118:121], v[148:151], v[194:197], v[118:121]
	v_mfma_f32_16x16x32_bf16 v[114:117], v[156:159], v[194:197], v[114:117]
	v_mfma_f32_16x16x32_bf16 v[110:113], v[148:151], v[202:205], v[110:113]
	v_mfma_f32_16x16x32_bf16 v[106:109], v[156:159], v[202:205], v[106:109]
	v_mfma_f32_16x16x32_bf16 v[102:105], v[148:151], v[210:213], v[102:105]
	v_mfma_f32_16x16x32_bf16 v[98:101], v[156:159], v[210:213], v[98:101]
	v_mfma_f32_16x16x32_bf16 v[126:129], v[152:155], v[190:193], v[126:129]
	v_mfma_f32_16x16x32_bf16 v[122:125], v[166:169], v[190:193], v[122:125]
	v_mfma_f32_16x16x32_bf16 v[118:121], v[152:155], v[198:201], v[118:121]
	v_mfma_f32_16x16x32_bf16 v[114:117], v[166:169], v[198:201], v[114:117]
	v_mfma_f32_16x16x32_bf16 v[110:113], v[152:155], v[206:209], v[110:113]
	v_mfma_f32_16x16x32_bf16 v[106:109], v[166:169], v[206:209], v[106:109]
	v_mfma_f32_16x16x32_bf16 v[102:105], v[152:155], v[214:217], v[102:105]
	v_mfma_f32_16x16x32_bf16 v[98:101], v[166:169], v[214:217], v[98:101]
	s_setprio 0
	s_setprio 1
	v_mfma_f32_16x16x32_bf16 v[94:97], v[170:173], v[186:189], v[94:97]
	v_mfma_f32_16x16x32_bf16 v[90:93], v[178:181], v[186:189], v[90:93]
	v_mfma_f32_16x16x32_bf16 v[86:89], v[170:173], v[194:197], v[86:89]
	v_mfma_f32_16x16x32_bf16 v[82:85], v[178:181], v[194:197], v[82:85]
	v_mfma_f32_16x16x32_bf16 v[78:81], v[170:173], v[202:205], v[78:81]
	v_mfma_f32_16x16x32_bf16 v[74:77], v[178:181], v[202:205], v[74:77]
	v_mfma_f32_16x16x32_bf16 v[70:73], v[170:173], v[210:213], v[70:73]
	v_mfma_f32_16x16x32_bf16 v[66:69], v[178:181], v[210:213], v[66:69]
	v_mfma_f32_16x16x32_bf16 v[94:97], v[174:177], v[190:193], v[94:97]
	v_mfma_f32_16x16x32_bf16 v[90:93], v[182:185], v[190:193], v[90:93]
	v_mfma_f32_16x16x32_bf16 v[86:89], v[174:177], v[198:201], v[86:89]
	v_mfma_f32_16x16x32_bf16 v[82:85], v[182:185], v[198:201], v[82:85]
	v_mfma_f32_16x16x32_bf16 v[78:81], v[174:177], v[206:209], v[78:81]
	v_mfma_f32_16x16x32_bf16 v[74:77], v[182:185], v[206:209], v[74:77]
	v_mfma_f32_16x16x32_bf16 v[70:73], v[174:177], v[214:217], v[70:73]
	v_mfma_f32_16x16x32_bf16 v[66:69], v[182:185], v[214:217], v[66:69]
	s_setprio 0
	s_barrier
	ds_read_b128 v[186:189], v164 offset:16384
	ds_read_b128 v[190:193], v164 offset:17408
	ds_read_b128 v[194:197], v164 offset:18432
	ds_read_b128 v[198:201], v164 offset:19456
	ds_read_b128 v[202:205], v164 offset:20480
	ds_read_b128 v[206:209], v164 offset:21504
	ds_read_b128 v[210:213], v164 offset:22528
	ds_read_b128 v[214:217], v164 offset:23552
	s_add_i32 s76, s78, s35
	v_lshl_add_u64 v[160:161], s[12:13], 0, v[132:133]
	s_mov_b32 m0, s76
	s_nop 0
	global_load_lds_dwordx4 v[160:161], off
	s_add_i32 m0, s76, 0x2000
	s_add_u32 s90, s12, 0x40000
	v_lshl_add_u64 v[218:219], s[12:13], 0, v[136:137]
	s_addc_u32 s91, s13, 0
	s_add_i32 s53, s53, s35
	global_load_lds_dwordx4 v[218:219], off
	v_lshl_add_u64 v[220:221], s[90:91], 0, v[132:133]
	s_mov_b32 m0, s53
	v_lshl_add_u64 v[222:223], s[26:27], 0, v[134:135]
	global_load_lds_dwordx4 v[220:221], off
	v_lshl_add_u64 v[220:221], s[90:91], 0, v[136:137]
	s_add_i32 m0, s53, 0x2000
	s_nop 0
	global_load_lds_dwordx4 v[220:221], off
	v_lshl_add_u64 v[220:221], s[26:27], 0, v[130:131]
	s_mov_b32 m0, s17
	s_nop 0
	global_load_lds_dwordx4 v[220:221], off
	s_mov_b32 m0, s37
	s_nop 0
	global_load_lds_dwordx4 v[222:223], off
	s_waitcnt vmcnt(8)
	s_waitcnt vmcnt(8)
	s_waitcnt lgkmcnt(0)
	s_barrier
; #define PG8_STAGE(bufoff, gbase, voff) do { _Pragma("unroll") for (int _i = 0; _i < 2; ++_i) \
;         __builtin_amdgcn_global_load_lds((const unsigned*)((const char*)(gbase) + (voff)[_i]), (PG8_LAS unsigned*)(lds + (bufoff) + ldsw + _i * 8192), 16, 0, 0); } while (0)
; #define PG8_LDA(dst, b, h) do { _Pragma("unroll") for (int m = 0; m < 4; ++m) _Pragma("unroll") for (int k = 0; k < 2; ++k) dst[m][k] = *(const PG8_LAS bf16x8*)(lds + PG8_SA(b, h) + aoff + m * 2048 + k * 1024); } while (0)
; #define PG8_LDB(dst, b, h) do { _Pragma("unroll") for (int n = 0; n < 2; ++n) _Pragma("unroll") for (int k = 0; k < 2; ++k) dst[n][k] = *(const PG8_LAS bf16x8*)(lds + PG8_SB(b, h) + boff + n * 2048 + k * 1024); } while (0)
; #define PG8_MMA(ai, bj, At, Bt) do { __builtin_amdgcn_s_setprio(1); _Pragma("unroll") for (int m = 0; m < 4; ++m) _Pragma("unroll") for (int n = 0; n < 2; ++n) _Pragma("unroll") for (int k = 0; k < 2; ++k) \
;         acc[ai][bj][m][n] = __builtin_amdgcn_mfma_f32_16x16x32_bf16(Bt[n][k], At[m][k], acc[ai][bj][m][n], 0, 0, 0); __builtin_amdgcn_s_setprio(0); } while (0)
; #define PG8_WAIT_V(n) asm volatile("s_waitcnt vmcnt(" #n ")" ::: "memory")
; #define PG8_WAIT_L(n) asm volatile("s_waitcnt lgkmcnt(" #n ")" ::: "memory")
; #define PG8_BAR __builtin_amdgcn_s_barrier()
; #define PG8_SCHED __builtin_amdgcn_sched_barrier(0)
; template <class Epi, class Sched, bool ALIGN_EPI = false, bool SP2 = false>
; __device__ __forceinline__ void gemm_phase(PG8_LAS unsigned char* lds, const Gemm g, const Sched& S, const Epi& E, const int wave_id) {
;     ...
;             PG8_LDB(B0, 1, 0); PG8_LDB(B1, 1, 1); PG8_SCHED; PG8_LDA(At, 1, 0); PG8_STAGE(PG8_SA(0, 1), a2 + hstep, voffA);
;             PG8_WAIT_V(8); PG8_WAIT_L(0); PG8_BAR; PG8_MMA(0, 0, At, B0); PG8_MMA(0, 1, At, B1); PG8_BAR; PG8_SCHED;
	s_setprio 1
	s_waitcnt lgkmcnt(0)
	v_mfma_f32_16x16x32_bf16 v[62:65], v[148:151], v[186:189], v[62:65]
	v_mfma_f32_16x16x32_bf16 v[58:61], v[156:159], v[186:189], v[58:61]
	v_mfma_f32_16x16x32_bf16 v[54:57], v[148:151], v[194:197], v[54:57]
	v_mfma_f32_16x16x32_bf16 v[50:53], v[156:159], v[194:197], v[50:53]
	v_mfma_f32_16x16x32_bf16 v[46:49], v[148:151], v[202:205], v[46:49]
	v_mfma_f32_16x16x32_bf16 v[42:45], v[156:159], v[202:205], v[42:45]
	v_mfma_f32_16x16x32_bf16 v[38:41], v[148:151], v[210:213], v[38:41]
	v_mfma_f32_16x16x32_bf16 v[34:37], v[156:159], v[210:213], v[34:37]
	v_mfma_f32_16x16x32_bf16 v[62:65], v[152:155], v[190:193], v[62:65]
	v_mfma_f32_16x16x32_bf16 v[58:61], v[166:169], v[190:193], v[58:61]
	v_mfma_f32_16x16x32_bf16 v[54:57], v[152:155], v[198:201], v[54:57]
	v_mfma_f32_16x16x32_bf16 v[50:53], v[166:169], v[198:201], v[50:53]
	v_mfma_f32_16x16x32_bf16 v[46:49], v[152:155], v[206:209], v[46:49]
	v_mfma_f32_16x16x32_bf16 v[42:45], v[166:169], v[206:209], v[42:45]
	v_mfma_f32_16x16x32_bf16 v[38:41], v[152:155], v[214:217], v[38:41]
	v_mfma_f32_16x16x32_bf16 v[34:37], v[166:169], v[214:217], v[34:37]
	s_setprio 0
	s_setprio 1
	v_mfma_f32_16x16x32_bf16 v[30:33], v[170:173], v[186:189], v[30:33]
	v_mfma_f32_16x16x32_bf16 v[26:29], v[178:181], v[186:189], v[26:29]
	v_mfma_f32_16x16x32_bf16 v[22:25], v[170:173], v[194:197], v[22:25]
	v_mfma_f32_16x16x32_bf16 v[18:21], v[178:181], v[194:197], v[18:21]
	v_mfma_f32_16x16x32_bf16 v[14:17], v[170:173], v[202:205], v[14:17]
	v_mfma_f32_16x16x32_bf16 v[10:13], v[178:181], v[202:205], v[10:13]
	v_mfma_f32_16x16x32_bf16 v[6:9], v[170:173], v[210:213], v[6:9]
	v_mfma_f32_16x16x32_bf16 v[2:5], v[178:181], v[210:213], v[2:5]
	v_mfma_f32_16x16x32_bf16 v[30:33], v[174:177], v[190:193], v[30:33]
	v_mfma_f32_16x16x32_bf16 v[26:29], v[182:185], v[190:193], v[26:29]
	v_mfma_f32_16x16x32_bf16 v[22:25], v[174:177], v[198:201], v[22:25]
	v_mfma_f32_16x16x32_bf16 v[18:21], v[182:185], v[198:201], v[18:21]
	v_mfma_f32_16x16x32_bf16 v[14:17], v[174:177], v[206:209], v[14:17]
	v_mfma_f32_16x16x32_bf16 v[10:13], v[182:185], v[206:209], v[10:13]
	v_mfma_f32_16x16x32_bf16 v[6:9], v[174:177], v[214:217], v[6:9]
	v_mfma_f32_16x16x32_bf16 v[2:5], v[182:185], v[214:217], v[2:5]
	s_setprio 0
	s_barrier
	ds_read_b128 v[186:189], v164 offset:32768
	ds_read_b128 v[190:193], v164 offset:33792
	ds_read_b128 v[194:197], v164 offset:34816
	ds_read_b128 v[198:201], v164 offset:35840
	ds_read_b128 v[202:205], v164 offset:36864
	ds_read_b128 v[206:209], v164 offset:37888
	ds_read_b128 v[210:213], v164 offset:38912
	ds_read_b128 v[214:217], v164 offset:39936
	s_add_i32 s53, 0, 0x18000
	v_add_u32_e32 v147, s53, v163
	s_add_i32 s76, 0, 0x1c000
	ds_read_b128 v[148:151], v147
	ds_read_b128 v[152:155], v147 offset:1024
	ds_read_b128 v[156:159], v147 offset:2048
	ds_read_b128 v[166:169], v147 offset:3072
	v_add_u32_e32 v147, s76, v163
	ds_read_b128 v[170:173], v147
	ds_read_b128 v[174:177], v147 offset:1024
	ds_read_b128 v[178:181], v147 offset:2048
	ds_read_b128 v[182:185], v147 offset:3072
	s_add_u32 s26, s26, 0x40000
	s_addc_u32 s27, s27, 0
	s_mov_b32 m0, s38
	v_lshl_add_u64 v[224:225], s[26:27], 0, v[130:131]
	global_load_lds_dwordx4 v[224:225], off
	v_lshl_add_u64 v[224:225], s[26:27], 0, v[134:135]
	s_mov_b32 m0, s39
	s_nop 0
	global_load_lds_dwordx4 v[224:225], off
	s_waitcnt vmcnt(8)
	s_waitcnt lgkmcnt(0)
	s_barrier
	s_setprio 1
	s_waitcnt lgkmcnt(0)
	v_mfma_f32_16x16x32_bf16 v[126:129], v[148:151], v[186:189], v[126:129]
	v_mfma_f32_16x16x32_bf16 v[122:125], v[156:159], v[186:189], v[122:125]
	v_mfma_f32_16x16x32_bf16 v[118:121], v[148:151], v[194:197], v[118:121]
	v_mfma_f32_16x16x32_bf16 v[114:117], v[156:159], v[194:197], v[114:117]
	v_mfma_f32_16x16x32_bf16 v[110:113], v[148:151], v[202:205], v[110:113]
	v_mfma_f32_16x16x32_bf16 v[106:109], v[156:159], v[202:205], v[106:109]
	v_mfma_f32_16x16x32_bf16 v[102:105], v[148:151], v[210:213], v[102:105]
	v_mfma_f32_16x16x32_bf16 v[98:101], v[156:159], v[210:213], v[98:101]
	v_mfma_f32_16x16x32_bf16 v[126:129], v[152:155], v[190:193], v[126:129]
	v_mfma_f32_16x16x32_bf16 v[122:125], v[166:169], v[190:193], v[122:125]
	v_mfma_f32_16x16x32_bf16 v[118:121], v[152:155], v[198:201], v[118:121]
	v_mfma_f32_16x16x32_bf16 v[114:117], v[166:169], v[198:201], v[114:117]
	v_mfma_f32_16x16x32_bf16 v[110:113], v[152:155], v[206:209], v[110:113]
	v_mfma_f32_16x16x32_bf16 v[106:109], v[166:169], v[206:209], v[106:109]
	v_mfma_f32_16x16x32_bf16 v[102:105], v[152:155], v[214:217], v[102:105]
	v_mfma_f32_16x16x32_bf16 v[98:101], v[166:169], v[214:217], v[98:101]
	s_setprio 0
	s_setprio 1
	v_mfma_f32_16x16x32_bf16 v[94:97], v[170:173], v[186:189], v[94:97]
	v_mfma_f32_16x16x32_bf16 v[90:93], v[178:181], v[186:189], v[90:93]
	v_mfma_f32_16x16x32_bf16 v[86:89], v[170:173], v[194:197], v[86:89]
	v_mfma_f32_16x16x32_bf16 v[82:85], v[178:181], v[194:197], v[82:85]
	v_mfma_f32_16x16x32_bf16 v[78:81], v[170:173], v[202:205], v[78:81]
	v_mfma_f32_16x16x32_bf16 v[74:77], v[178:181], v[202:205], v[74:77]
	v_mfma_f32_16x16x32_bf16 v[70:73], v[170:173], v[210:213], v[70:73]
	v_mfma_f32_16x16x32_bf16 v[66:69], v[178:181], v[210:213], v[66:69]
	v_mfma_f32_16x16x32_bf16 v[94:97], v[174:177], v[190:193], v[94:97]
	v_mfma_f32_16x16x32_bf16 v[90:93], v[182:185], v[190:193], v[90:93]
	v_mfma_f32_16x16x32_bf16 v[86:89], v[174:177], v[198:201], v[86:89]
	v_mfma_f32_16x16x32_bf16 v[82:85], v[182:185], v[198:201], v[82:85]
	v_mfma_f32_16x16x32_bf16 v[78:81], v[174:177], v[206:209], v[78:81]
	v_mfma_f32_16x16x32_bf16 v[74:77], v[182:185], v[206:209], v[74:77]
	v_mfma_f32_16x16x32_bf16 v[70:73], v[174:177], v[214:217], v[70:73]
	v_mfma_f32_16x16x32_bf16 v[66:69], v[182:185], v[214:217], v[66:69]
	s_setprio 0
	s_barrier
; #define PG8_STAGE(bufoff, gbase, voff) do { _Pragma("unroll") for (int _i = 0; _i < 2; ++_i) \
;         __builtin_amdgcn_global_load_lds((const unsigned*)((const char*)(gbase) + (voff)[_i]), (PG8_LAS unsigned*)(lds + (bufoff) + ldsw + _i * 8192), 16, 0, 0); } while (0)
; #define PG8_LDA(dst, b, h) do { _Pragma("unroll") for (int m = 0; m < 4; ++m) _Pragma("unroll") for (int k = 0; k < 2; ++k) dst[m][k] = *(const PG8_LAS bf16x8*)(lds + PG8_SA(b, h) + aoff + m * 2048 + k * 1024); } while (0)
; #define PG8_MMA(ai, bj, At, Bt) do { __builtin_amdgcn_s_setprio(1); _Pragma("unroll") for (int m = 0; m < 4; ++m) _Pragma("unroll") for (int n = 0; n < 2; ++n) _Pragma("unroll") for (int k = 0; k < 2; ++k) \
;         acc[ai][bj][m][n] = __builtin_amdgcn_mfma_f32_16x16x32_bf16(Bt[n][k], At[m][k], acc[ai][bj][m][n], 0, 0, 0); __builtin_amdgcn_s_setprio(0); } while (0)
; #define PG8_WAIT_V(n) asm volatile("s_waitcnt vmcnt(" #n ")" ::: "memory")
; #define PG8_WAIT_L(n) asm volatile("s_waitcnt lgkmcnt(" #n ")" ::: "memory")
; #define PG8_BAR __builtin_amdgcn_s_barrier()
; #define PG8_SCHED __builtin_amdgcn_sched_barrier(0)
; template <class Epi, class Sched, bool ALIGN_EPI = false, bool SP2 = false>
; __device__ __forceinline__ void gemm_phase(PG8_LAS unsigned char* lds, const Gemm g, const Sched& S, const Epi& E, const int wave_id) {
;     ...
;         for (int t = 0; t < nt; t += 2) {
;     ...
;             PG8_LDA(At, 1, 1); PG8_STAGE(PG8_SB(1, 0), b3, voffB); PG8_STAGE(PG8_SB(1, 1), b3 + hstep, voffB); PG8_STAGE(PG8_SA(1, 0), a3, voffA);
;             PG8_WAIT_V(8); PG8_WAIT_L(0); PG8_BAR; PG8_MMA(1, 0, At, B0); PG8_MMA(1, 1, At, B1); PG8_BAR; PG8_SCHED;
;     ...
;         if constexpr (ALIGN_EPI) { if (wr == 0) PG8_BAR; }
	ds_read_b128 v[186:189], v164 offset:49152
	ds_read_b128 v[190:193], v164 offset:50176
	ds_read_b128 v[194:197], v164 offset:51200
	ds_read_b128 v[198:201], v164 offset:52224
	ds_read_b128 v[202:205], v164 offset:53248
	ds_read_b128 v[206:209], v164 offset:54272
	ds_read_b128 v[210:213], v164 offset:55296
	ds_read_b128 v[214:217], v164 offset:56320
	s_add_i32 s26, s53, s35
	v_lshl_add_u64 v[160:161], v[160:161], 0, s[64:65]
	s_mov_b32 m0, s26
	s_nop 0
	global_load_lds_dwordx4 v[160:161], off
	s_add_i32 m0, s26, 0x2000
	s_add_u32 s12, s12, 0x40080
	v_lshl_add_u64 v[160:161], v[218:219], 0, s[64:65]
	s_addc_u32 s13, s13, 0
	s_add_i32 s26, s76, s35
	global_load_lds_dwordx4 v[160:161], off
	v_lshl_add_u64 v[160:161], s[12:13], 0, v[132:133]
	s_mov_b32 m0, s26
	s_nop 0
	global_load_lds_dwordx4 v[160:161], off
	v_lshl_add_u64 v[160:161], s[12:13], 0, v[136:137]
	s_add_i32 m0, s26, 0x2000
	s_nop 0
	global_load_lds_dwordx4 v[160:161], off
	v_lshl_add_u64 v[160:161], v[220:221], 0, s[64:65]
	s_mov_b32 m0, s41
	s_nop 0
	global_load_lds_dwordx4 v[160:161], off
	v_lshl_add_u64 v[160:161], v[222:223], 0, s[64:65]
	s_mov_b32 m0, s42
	s_nop 0
	global_load_lds_dwordx4 v[160:161], off
	s_waitcnt vmcnt(8)
	s_waitcnt lgkmcnt(0)
	s_barrier
	s_setprio 1
	s_waitcnt lgkmcnt(0)
	v_mfma_f32_16x16x32_bf16 v[62:65], v[148:151], v[186:189], v[62:65]
	v_mfma_f32_16x16x32_bf16 v[58:61], v[156:159], v[186:189], v[58:61]
	v_mfma_f32_16x16x32_bf16 v[54:57], v[148:151], v[194:197], v[54:57]
	v_mfma_f32_16x16x32_bf16 v[50:53], v[156:159], v[194:197], v[50:53]
	v_mfma_f32_16x16x32_bf16 v[46:49], v[148:151], v[202:205], v[46:49]
	v_mfma_f32_16x16x32_bf16 v[42:45], v[156:159], v[202:205], v[42:45]
	v_mfma_f32_16x16x32_bf16 v[38:41], v[148:151], v[210:213], v[38:41]
	v_mfma_f32_16x16x32_bf16 v[34:37], v[156:159], v[210:213], v[34:37]
	v_mfma_f32_16x16x32_bf16 v[62:65], v[152:155], v[190:193], v[62:65]
	v_mfma_f32_16x16x32_bf16 v[58:61], v[166:169], v[190:193], v[58:61]
	v_mfma_f32_16x16x32_bf16 v[54:57], v[152:155], v[198:201], v[54:57]
	v_mfma_f32_16x16x32_bf16 v[50:53], v[166:169], v[198:201], v[50:53]
	v_mfma_f32_16x16x32_bf16 v[46:49], v[152:155], v[206:209], v[46:49]
	v_mfma_f32_16x16x32_bf16 v[42:45], v[166:169], v[206:209], v[42:45]
	v_mfma_f32_16x16x32_bf16 v[38:41], v[152:155], v[214:217], v[38:41]
	v_mfma_f32_16x16x32_bf16 v[34:37], v[166:169], v[214:217], v[34:37]
	s_setprio 0
	s_setprio 1
	v_mfma_f32_16x16x32_bf16 v[30:33], v[170:173], v[186:189], v[30:33]
	v_mfma_f32_16x16x32_bf16 v[26:29], v[178:181], v[186:189], v[26:29]
	v_mfma_f32_16x16x32_bf16 v[22:25], v[170:173], v[194:197], v[22:25]
	v_mfma_f32_16x16x32_bf16 v[18:21], v[178:181], v[194:197], v[18:21]
	v_mfma_f32_16x16x32_bf16 v[14:17], v[170:173], v[202:205], v[14:17]
	v_mfma_f32_16x16x32_bf16 v[10:13], v[178:181], v[202:205], v[10:13]
	v_mfma_f32_16x16x32_bf16 v[6:9], v[170:173], v[210:213], v[6:9]
	v_mfma_f32_16x16x32_bf16 v[2:5], v[178:181], v[210:213], v[2:5]
	v_mfma_f32_16x16x32_bf16 v[30:33], v[174:177], v[190:193], v[30:33]
	v_mfma_f32_16x16x32_bf16 v[26:29], v[182:185], v[190:193], v[26:29]
	v_mfma_f32_16x16x32_bf16 v[22:25], v[174:177], v[198:201], v[22:25]
	v_mfma_f32_16x16x32_bf16 v[18:21], v[182:185], v[198:201], v[18:21]
	v_mfma_f32_16x16x32_bf16 v[14:17], v[174:177], v[206:209], v[14:17]
	v_mfma_f32_16x16x32_bf16 v[10:13], v[182:185], v[206:209], v[10:13]
	v_mfma_f32_16x16x32_bf16 v[6:9], v[174:177], v[214:217], v[6:9]
	v_mfma_f32_16x16x32_bf16 v[2:5], v[182:185], v[214:217], v[2:5]
	s_setprio 0
	s_barrier
	s_add_u32 s10, s10, 0x100
	s_addc_u32 s11, s11, 0
	s_cmp_gt_u32 s69, 13
	s_cbranch_scc0 .LBB0_1537
	s_and_b64 vcc, exec, s[24:25]
	s_cbranch_vccz .LBB0_1540
	s_barrier

; #define PG8_STAGE(bufoff, gbase, voff) do { _Pragma("unroll") for (int _i = 0; _i < 2; ++_i) \
;         __builtin_amdgcn_global_load_lds((const unsigned*)((const char*)(gbase) + (voff)[_i]), (PG8_LAS unsigned*)(lds + (bufoff) + ldsw + _i * 8192), 16, 0, 0); } while (0)
; #define PG8_LDA(dst, b, h) do { _Pragma("unroll") for (int m = 0; m < 4; ++m) _Pragma("unroll") for (int k = 0; k < 2; ++k) dst[m][k] = *(const PG8_LAS bf16x8*)(lds + PG8_SA(b, h) + aoff + m * 2048 + k * 1024); } while (0)
; #define PG8_LDB(dst, b, h) do { _Pragma("unroll") for (int n = 0; n < 2; ++n) _Pragma("unroll") for (int k = 0; k < 2; ++k) dst[n][k] = *(const PG8_LAS bf16x8*)(lds + PG8_SB(b, h) + boff + n * 2048 + k * 1024); } while (0)
; #define PG8_MMA(ai, bj, At, Bt) do { __builtin_amdgcn_s_setprio(1); _Pragma("unroll") for (int m = 0; m < 4; ++m) _Pragma("unroll") for (int n = 0; n < 2; ++n) _Pragma("unroll") for (int k = 0; k < 2; ++k) \
;         acc[ai][bj][m][n] = __builtin_amdgcn_mfma_f32_16x16x32_bf16(Bt[n][k], At[m][k], acc[ai][bj][m][n], 0, 0, 0); __builtin_amdgcn_s_setprio(0); } while (0)
; #define PG8_WAIT_V(n) asm volatile("s_waitcnt vmcnt(" #n ")" ::: "memory")
; #define PG8_WAIT_VN(n) asm volatile("s_waitcnt vmcnt(%0)" :: "n"(n) : "memory")
; template <class Epi, class Sched, bool ALIGN_EPI = false, bool SP2 = false>
; __device__ __forceinline__ void gemm_phase(PG8_LAS unsigned char* lds, const Gemm g, const Sched& S, const Epi& E, const int wave_id) {
;     ...
;             const char* a2 = last ? nA : cA + (size_t)(t + 2) * kstep; const char* b2 = last ? nB : cB + (size_t)(t + 2) * kstep;
;     ...
;             int tz_ = __builtin_amdgcn_readfirstlane(t | (ui > 0 ? 0 : 1)); asm volatile("" : "+s"(tz_));
;             const bool strict = !(Epi::NS > 0 && tz_ == 0);
;             PG8_LDB(B0, 0, 0); PG8_LDB(B1, 0, 1); PG8_SCHED; PG8_LDA(At, 0, 0); PG8_STAGE(PG8_SA(1, 1), a1 + hstep, voffA);
;             PG8_WAIT_VN(8 + Epi::NS); if (strict) PG8_WAIT_V(8); PG8_WAIT_L(0); PG8_BAR; PG8_MMA(0, 0, At, B0); PG8_MMA(0, 1, At, B1); PG8_BAR; PG8_SCHED;
;             PG8_LDA(At, 0, 1); PG8_STAGE(PG8_SB(0, 0), b2, voffB); PG8_STAGE(PG8_SB(0, 1), b2 + hstep, voffB); PG8_STAGE(PG8_SA(0, 0), a2, voffA);
;             PG8_WAIT_VN(8 + Epi::NS); if (strict) PG8_WAIT_V(8); PG8_WAIT_L(0); PG8_BAR; PG8_MMA(1, 0, At, B0); PG8_MMA(1, 1, At, B1); PG8_BAR; PG8_SCHED;
.LBB0_1685:
	s_add_u32 s24, s20, s22
	s_addc_u32 s25, s21, s23
	s_add_u32 s24, s24, 0x100
	s_addc_u32 s25, s25, 0
	s_add_u32 s53, s52, s22
	s_addc_u32 s57, s54, s23
	s_add_i32 s56, s56, 2
	s_add_i32 s62, 0, 0x10000
	v_add_u32_e32 v147, s56, v146
	s_cmpk_eq_i32 s22, 0x700
	s_cselect_b32 s26, s11, s24
	v_readfirstlane_b32 s24, v147
	s_cselect_b32 s27, s9, s25
	v_add_u32_e32 v147, s62, v163
	s_cselect_b32 s25, s13, s57
	s_cselect_b32 s24, s15, s53
	s_add_i32 s53, 0, 0x14000
	ds_read_b128 v[148:151], v147
	ds_read_b128 v[152:155], v147 offset:1024
	ds_read_b128 v[156:159], v147 offset:2048
	ds_read_b128 v[166:169], v147 offset:3072
	v_add_u32_e32 v147, s53, v163
	ds_read_b128 v[170:173], v147
	ds_read_b128 v[174:177], v147 offset:1024
	ds_read_b128 v[178:181], v147 offset:2048
	ds_read_b128 v[182:185], v147 offset:3072
	v_lshl_add_u64 v[160:161], v[144:145], 0, s[22:23]
	s_add_i32 m0, s38, 0xc000
	ds_read_b128 v[186:189], v164
	ds_read_b128 v[190:193], v164 offset:1024
	ds_read_b128 v[194:197], v164 offset:2048
	ds_read_b128 v[198:201], v164 offset:3072
	ds_read_b128 v[202:205], v164 offset:4096
	ds_read_b128 v[206:209], v164 offset:5120
	ds_read_b128 v[210:213], v164 offset:6144
	ds_read_b128 v[214:217], v164 offset:7168
	global_load_lds_dwordx4 v[160:161], off
	v_lshl_add_u64 v[160:161], v[142:143], 0, s[22:23]
	s_add_i32 m0, s38, 0xe000
	s_nop 0
	global_load_lds_dwordx4 v[160:161], off
	s_waitcnt vmcnt(8)
	s_waitcnt vmcnt(8)
	s_waitcnt lgkmcnt(0)
	s_barrier
	s_setprio 1
	s_waitcnt lgkmcnt(0)
	v_mfma_f32_16x16x32_bf16 v[126:129], v[148:151], v[186:189], v[126:129]
	v_mfma_f32_16x16x32_bf16 v[122:125], v[156:159], v[186:189], v[122:125]
	v_mfma_f32_16x16x32_bf16 v[118:121], v[148:151], v[194:197], v[118:121]
	v_mfma_f32_16x16x32_bf16 v[114:117], v[156:159], v[194:197], v[114:117]
	v_mfma_f32_16x16x32_bf16 v[110:113], v[148:151], v[202:205], v[110:113]
	v_mfma_f32_16x16x32_bf16 v[106:109], v[156:159], v[202:205], v[106:109]
	v_mfma_f32_16x16x32_bf16 v[102:105], v[148:151], v[210:213], v[102:105]
	v_mfma_f32_16x16x32_bf16 v[98:101], v[156:159], v[210:213], v[98:101]
	v_mfma_f32_16x16x32_bf16 v[126:129], v[152:155], v[190:193], v[126:129]
	v_mfma_f32_16x16x32_bf16 v[122:125], v[166:169], v[190:193], v[122:125]
	v_mfma_f32_16x16x32_bf16 v[118:121], v[152:155], v[198:201], v[118:121]
	v_mfma_f32_16x16x32_bf16 v[114:117], v[166:169], v[198:201], v[114:117]
	v_mfma_f32_16x16x32_bf16 v[110:113], v[152:155], v[206:209], v[110:113]
	v_mfma_f32_16x16x32_bf16 v[106:109], v[166:169], v[206:209], v[106:109]
	v_mfma_f32_16x16x32_bf16 v[102:105], v[152:155], v[214:217], v[102:105]
	v_mfma_f32_16x16x32_bf16 v[98:101], v[166:169], v[214:217], v[98:101]
	s_setprio 0
	s_setprio 1
	v_mfma_f32_16x16x32_bf16 v[94:97], v[170:173], v[186:189], v[94:97]
	v_mfma_f32_16x16x32_bf16 v[90:93], v[178:181], v[186:189], v[90:93]
	v_mfma_f32_16x16x32_bf16 v[86:89], v[170:173], v[194:197], v[86:89]
	v_mfma_f32_16x16x32_bf16 v[82:85], v[178:181], v[194:197], v[82:85]
	v_mfma_f32_16x16x32_bf16 v[78:81], v[170:173], v[202:205], v[78:81]
	v_mfma_f32_16x16x32_bf16 v[74:77], v[178:181], v[202:205], v[74:77]
	v_mfma_f32_16x16x32_bf16 v[70:73], v[170:173], v[210:213], v[70:73]
	v_mfma_f32_16x16x32_bf16 v[66:69], v[178:181], v[210:213], v[66:69]
	v_mfma_f32_16x16x32_bf16 v[94:97], v[174:177], v[190:193], v[94:97]
	v_mfma_f32_16x16x32_bf16 v[90:93], v[182:185], v[190:193], v[90:93]
	v_mfma_f32_16x16x32_bf16 v[86:89], v[174:177], v[198:201], v[86:89]
	v_mfma_f32_16x16x32_bf16 v[82:85], v[182:185], v[198:201], v[82:85]
	v_mfma_f32_16x16x32_bf16 v[78:81], v[174:177], v[206:209], v[78:81]
	v_mfma_f32_16x16x32_bf16 v[74:77], v[182:185], v[206:209], v[74:77]
	v_mfma_f32_16x16x32_bf16 v[70:73], v[174:177], v[214:217], v[70:73]
	v_mfma_f32_16x16x32_bf16 v[66:69], v[182:185], v[214:217], v[66:69]
	s_setprio 0
	s_barrier
	ds_read_b128 v[186:189], v164 offset:16384
	ds_read_b128 v[190:193], v164 offset:17408
	ds_read_b128 v[194:197], v164 offset:18432
	ds_read_b128 v[198:201], v164 offset:19456
	ds_read_b128 v[202:205], v164 offset:20480
	ds_read_b128 v[206:209], v164 offset:21504
	ds_read_b128 v[210:213], v164 offset:22528
	ds_read_b128 v[214:217], v164 offset:23552
	s_add_i32 s57, s62, s37
	v_lshl_add_u64 v[160:161], s[24:25], 0, v[132:133]
	s_mov_b32 m0, s57
	s_nop 0
	global_load_lds_dwordx4 v[160:161], off
	s_add_i32 m0, s57, 0x2000
	s_add_u32 s62, s24, 0x40000
	v_lshl_add_u64 v[218:219], s[24:25], 0, v[136:137]
	s_addc_u32 s63, s25, 0
	s_add_i32 s53, s53, s37
	global_load_lds_dwordx4 v[218:219], off
	v_lshl_add_u64 v[220:221], s[62:63], 0, v[132:133]
	s_mov_b32 m0, s53
	v_lshl_add_u64 v[222:223], s[26:27], 0, v[134:135]
	global_load_lds_dwordx4 v[220:221], off
	v_lshl_add_u64 v[220:221], s[62:63], 0, v[136:137]
	s_add_i32 m0, s53, 0x2000
	s_nop 0
	global_load_lds_dwordx4 v[220:221], off
	v_lshl_add_u64 v[220:221], s[26:27], 0, v[130:131]
	s_mov_b32 m0, s38
	s_nop 0
	global_load_lds_dwordx4 v[220:221], off
	s_mov_b32 m0, s39
	s_nop 0
	global_load_lds_dwordx4 v[222:223], off
	s_waitcnt vmcnt(8)
	s_waitcnt vmcnt(8)
	s_waitcnt lgkmcnt(0)
	s_barrier
; #define PG8_STAGE(bufoff, gbase, voff) do { _Pragma("unroll") for (int _i = 0; _i < 2; ++_i) \
;         __builtin_amdgcn_global_load_lds((const unsigned*)((const char*)(gbase) + (voff)[_i]), (PG8_LAS unsigned*)(lds + (bufoff) + ldsw + _i * 8192), 16, 0, 0); } while (0)
; #define PG8_LDA(dst, b, h) do { _Pragma("unroll") for (int m = 0; m < 4; ++m) _Pragma("unroll") for (int k = 0; k < 2; ++k) dst[m][k] = *(const PG8_LAS bf16x8*)(lds + PG8_SA(b, h) + aoff + m * 2048 + k * 1024); } while (0)
; #define PG8_LDB(dst, b, h) do { _Pragma("unroll") for (int n = 0; n < 2; ++n) _Pragma("unroll") for (int k = 0; k < 2; ++k) dst[n][k] = *(const PG8_LAS bf16x8*)(lds + PG8_SB(b, h) + boff + n * 2048 + k * 1024); } while (0)
; #define PG8_MMA(ai, bj, At, Bt) do { __builtin_amdgcn_s_setprio(1); _Pragma("unroll") for (int m = 0; m < 4; ++m) _Pragma("unroll") for (int n = 0; n < 2; ++n) _Pragma("unroll") for (int k = 0; k < 2; ++k) \
;         acc[ai][bj][m][n] = __builtin_amdgcn_mfma_f32_16x16x32_bf16(Bt[n][k], At[m][k], acc[ai][bj][m][n], 0, 0, 0); __builtin_amdgcn_s_setprio(0); } while (0)
; #define PG8_WAIT_V(n) asm volatile("s_waitcnt vmcnt(" #n ")" ::: "memory")
; #define PG8_WAIT_L(n) asm volatile("s_waitcnt lgkmcnt(" #n ")" ::: "memory")
; #define PG8_BAR __builtin_amdgcn_s_barrier()
; #define PG8_SCHED __builtin_amdgcn_sched_barrier(0)
; template <class Epi, class Sched, bool ALIGN_EPI = false, bool SP2 = false>
; __device__ __forceinline__ void gemm_phase(PG8_LAS unsigned char* lds, const Gemm g, const Sched& S, const Epi& E, const int wave_id) {
;     ...
;             PG8_LDB(B0, 1, 0); PG8_LDB(B1, 1, 1); PG8_SCHED; PG8_LDA(At, 1, 0); PG8_STAGE(PG8_SA(0, 1), a2 + hstep, voffA);
;             PG8_WAIT_V(8); PG8_WAIT_L(0); PG8_BAR; PG8_MMA(0, 0, At, B0); PG8_MMA(0, 1, At, B1); PG8_BAR; PG8_SCHED;
	s_setprio 1
	s_waitcnt lgkmcnt(0)
	v_mfma_f32_16x16x32_bf16 v[62:65], v[148:151], v[186:189], v[62:65]
	v_mfma_f32_16x16x32_bf16 v[58:61], v[156:159], v[186:189], v[58:61]
	v_mfma_f32_16x16x32_bf16 v[54:57], v[148:151], v[194:197], v[54:57]
	v_mfma_f32_16x16x32_bf16 v[50:53], v[156:159], v[194:197], v[50:53]
	v_mfma_f32_16x16x32_bf16 v[46:49], v[148:151], v[202:205], v[46:49]
	v_mfma_f32_16x16x32_bf16 v[42:45], v[156:159], v[202:205], v[42:45]
	v_mfma_f32_16x16x32_bf16 v[38:41], v[148:151], v[210:213], v[38:41]
	v_mfma_f32_16x16x32_bf16 v[34:37], v[156:159], v[210:213], v[34:37]
	v_mfma_f32_16x16x32_bf16 v[62:65], v[152:155], v[190:193], v[62:65]
	v_mfma_f32_16x16x32_bf16 v[58:61], v[166:169], v[190:193], v[58:61]
	v_mfma_f32_16x16x32_bf16 v[54:57], v[152:155], v[198:201], v[54:57]
	v_mfma_f32_16x16x32_bf16 v[50:53], v[166:169], v[198:201], v[50:53]
	v_mfma_f32_16x16x32_bf16 v[46:49], v[152:155], v[206:209], v[46:49]
	v_mfma_f32_16x16x32_bf16 v[42:45], v[166:169], v[206:209], v[42:45]
	v_mfma_f32_16x16x32_bf16 v[38:41], v[152:155], v[214:217], v[38:41]
	v_mfma_f32_16x16x32_bf16 v[34:37], v[166:169], v[214:217], v[34:37]
	s_setprio 0
	s_setprio 1
	v_mfma_f32_16x16x32_bf16 v[30:33], v[170:173], v[186:189], v[30:33]
	v_mfma_f32_16x16x32_bf16 v[26:29], v[178:181], v[186:189], v[26:29]
	v_mfma_f32_16x16x32_bf16 v[22:25], v[170:173], v[194:197], v[22:25]
	v_mfma_f32_16x16x32_bf16 v[18:21], v[178:181], v[194:197], v[18:21]
	v_mfma_f32_16x16x32_bf16 v[14:17], v[170:173], v[202:205], v[14:17]
	v_mfma_f32_16x16x32_bf16 v[10:13], v[178:181], v[202:205], v[10:13]
	v_mfma_f32_16x16x32_bf16 v[6:9], v[170:173], v[210:213], v[6:9]
	v_mfma_f32_16x16x32_bf16 v[2:5], v[178:181], v[210:213], v[2:5]
	v_mfma_f32_16x16x32_bf16 v[30:33], v[174:177], v[190:193], v[30:33]
	v_mfma_f32_16x16x32_bf16 v[26:29], v[182:185], v[190:193], v[26:29]
	v_mfma_f32_16x16x32_bf16 v[22:25], v[174:177], v[198:201], v[22:25]
	v_mfma_f32_16x16x32_bf16 v[18:21], v[182:185], v[198:201], v[18:21]
	v_mfma_f32_16x16x32_bf16 v[14:17], v[174:177], v[206:209], v[14:17]
	v_mfma_f32_16x16x32_bf16 v[10:13], v[182:185], v[206:209], v[10:13]
	v_mfma_f32_16x16x32_bf16 v[6:9], v[174:177], v[214:217], v[6:9]
	v_mfma_f32_16x16x32_bf16 v[2:5], v[182:185], v[214:217], v[2:5]
	s_setprio 0
	s_barrier
	ds_read_b128 v[186:189], v164 offset:32768
	ds_read_b128 v[190:193], v164 offset:33792
	ds_read_b128 v[194:197], v164 offset:34816
	ds_read_b128 v[198:201], v164 offset:35840
	ds_read_b128 v[202:205], v164 offset:36864
	ds_read_b128 v[206:209], v164 offset:37888
	ds_read_b128 v[210:213], v164 offset:38912
	ds_read_b128 v[214:217], v164 offset:39936
	s_add_i32 s53, 0, 0x18000
	v_add_u32_e32 v147, s53, v163
	s_add_i32 s57, 0, 0x1c000
	ds_read_b128 v[148:151], v147
	ds_read_b128 v[152:155], v147 offset:1024
	ds_read_b128 v[156:159], v147 offset:2048
	ds_read_b128 v[166:169], v147 offset:3072
	v_add_u32_e32 v147, s57, v163
	ds_read_b128 v[170:173], v147
	ds_read_b128 v[174:177], v147 offset:1024
	ds_read_b128 v[178:181], v147 offset:2048
	ds_read_b128 v[182:185], v147 offset:3072
	s_add_u32 s26, s26, 0x40000
	s_addc_u32 s27, s27, 0
	s_mov_b32 m0, s40
	v_lshl_add_u64 v[224:225], s[26:27], 0, v[130:131]
	global_load_lds_dwordx4 v[224:225], off
	v_lshl_add_u64 v[224:225], s[26:27], 0, v[134:135]
	s_mov_b32 m0, s41
	s_nop 0
	global_load_lds_dwordx4 v[224:225], off
	s_waitcnt vmcnt(8)
	s_waitcnt lgkmcnt(0)
	s_barrier
	s_setprio 1
	s_waitcnt lgkmcnt(0)
	v_mfma_f32_16x16x32_bf16 v[126:129], v[148:151], v[186:189], v[126:129]
	v_mfma_f32_16x16x32_bf16 v[122:125], v[156:159], v[186:189], v[122:125]
	v_mfma_f32_16x16x32_bf16 v[118:121], v[148:151], v[194:197], v[118:121]
	v_mfma_f32_16x16x32_bf16 v[114:117], v[156:159], v[194:197], v[114:117]
	v_mfma_f32_16x16x32_bf16 v[110:113], v[148:151], v[202:205], v[110:113]
	v_mfma_f32_16x16x32_bf16 v[106:109], v[156:159], v[202:205], v[106:109]
	v_mfma_f32_16x16x32_bf16 v[102:105], v[148:151], v[210:213], v[102:105]
	v_mfma_f32_16x16x32_bf16 v[98:101], v[156:159], v[210:213], v[98:101]
	v_mfma_f32_16x16x32_bf16 v[126:129], v[152:155], v[190:193], v[126:129]
	v_mfma_f32_16x16x32_bf16 v[122:125], v[166:169], v[190:193], v[122:125]
	v_mfma_f32_16x16x32_bf16 v[118:121], v[152:155], v[198:201], v[118:121]
	v_mfma_f32_16x16x32_bf16 v[114:117], v[166:169], v[198:201], v[114:117]
	v_mfma_f32_16x16x32_bf16 v[110:113], v[152:155], v[206:209], v[110:113]
	v_mfma_f32_16x16x32_bf16 v[106:109], v[166:169], v[206:209], v[106:109]
	v_mfma_f32_16x16x32_bf16 v[102:105], v[152:155], v[214:217], v[102:105]
	v_mfma_f32_16x16x32_bf16 v[98:101], v[166:169], v[214:217], v[98:101]
	s_setprio 0
	s_setprio 1
	v_mfma_f32_16x16x32_bf16 v[94:97], v[170:173], v[186:189], v[94:97]
	v_mfma_f32_16x16x32_bf16 v[90:93], v[178:181], v[186:189], v[90:93]
	v_mfma_f32_16x16x32_bf16 v[86:89], v[170:173], v[194:197], v[86:89]
	v_mfma_f32_16x16x32_bf16 v[82:85], v[178:181], v[194:197], v[82:85]
	v_mfma_f32_16x16x32_bf16 v[78:81], v[170:173], v[202:205], v[78:81]
	v_mfma_f32_16x16x32_bf16 v[74:77], v[178:181], v[202:205], v[74:77]
	v_mfma_f32_16x16x32_bf16 v[70:73], v[170:173], v[210:213], v[70:73]
	v_mfma_f32_16x16x32_bf16 v[66:69], v[178:181], v[210:213], v[66:69]
	v_mfma_f32_16x16x32_bf16 v[94:97], v[174:177], v[190:193], v[94:97]
	v_mfma_f32_16x16x32_bf16 v[90:93], v[182:185], v[190:193], v[90:93]
	v_mfma_f32_16x16x32_bf16 v[86:89], v[174:177], v[198:201], v[86:89]
	v_mfma_f32_16x16x32_bf16 v[82:85], v[182:185], v[198:201], v[82:85]
	v_mfma_f32_16x16x32_bf16 v[78:81], v[174:177], v[206:209], v[78:81]
	v_mfma_f32_16x16x32_bf16 v[74:77], v[182:185], v[206:209], v[74:77]
	v_mfma_f32_16x16x32_bf16 v[70:73], v[174:177], v[214:217], v[70:73]
	v_mfma_f32_16x16x32_bf16 v[66:69], v[182:185], v[214:217], v[66:69]
	s_setprio 0
	s_barrier
; #define PG8_STAGE(bufoff, gbase, voff) do { _Pragma("unroll") for (int _i = 0; _i < 2; ++_i) \
;         __builtin_amdgcn_global_load_lds((const unsigned*)((const char*)(gbase) + (voff)[_i]), (PG8_LAS unsigned*)(lds + (bufoff) + ldsw + _i * 8192), 16, 0, 0); } while (0)
; #define PG8_LDA(dst, b, h) do { _Pragma("unroll") for (int m = 0; m < 4; ++m) _Pragma("unroll") for (int k = 0; k < 2; ++k) dst[m][k] = *(const PG8_LAS bf16x8*)(lds + PG8_SA(b, h) + aoff + m * 2048 + k * 1024); } while (0)
; #define PG8_MMA(ai, bj, At, Bt) do { __builtin_amdgcn_s_setprio(1); _Pragma("unroll") for (int m = 0; m < 4; ++m) _Pragma("unroll") for (int n = 0; n < 2; ++n) _Pragma("unroll") for (int k = 0; k < 2; ++k) \
;         acc[ai][bj][m][n] = __builtin_amdgcn_mfma_f32_16x16x32_bf16(Bt[n][k], At[m][k], acc[ai][bj][m][n], 0, 0, 0); __builtin_amdgcn_s_setprio(0); } while (0)
; #define PG8_WAIT_V(n) asm volatile("s_waitcnt vmcnt(" #n ")" ::: "memory")
; #define PG8_WAIT_L(n) asm volatile("s_waitcnt lgkmcnt(" #n ")" ::: "memory")
; #define PG8_BAR __builtin_amdgcn_s_barrier()
; #define PG8_SCHED __builtin_amdgcn_sched_barrier(0)
; template <class Epi, class Sched, bool ALIGN_EPI = false, bool SP2 = false>
; __device__ __forceinline__ void gemm_phase(PG8_LAS unsigned char* lds, const Gemm g, const Sched& S, const Epi& E, const int wave_id) {
;     ...
;         for (int t = 0; t < nt; t += 2) {
;     ...
;             PG8_LDA(At, 1, 1); PG8_STAGE(PG8_SB(1, 0), b3, voffB); PG8_STAGE(PG8_SB(1, 1), b3 + hstep, voffB); PG8_STAGE(PG8_SA(1, 0), a3, voffA);
;             PG8_WAIT_V(8); PG8_WAIT_L(0); PG8_BAR; PG8_MMA(1, 0, At, B0); PG8_MMA(1, 1, At, B1); PG8_BAR; PG8_SCHED;
	ds_read_b128 v[186:189], v164 offset:49152
	ds_read_b128 v[190:193], v164 offset:50176
	ds_read_b128 v[194:197], v164 offset:51200
	ds_read_b128 v[198:201], v164 offset:52224
	ds_read_b128 v[202:205], v164 offset:53248
	ds_read_b128 v[206:209], v164 offset:54272
	ds_read_b128 v[210:213], v164 offset:55296
	ds_read_b128 v[214:217], v164 offset:56320
	s_add_i32 s26, s53, s37
	v_lshl_add_u64 v[160:161], v[160:161], 0, s[64:65]
	s_mov_b32 m0, s26
	s_nop 0
	global_load_lds_dwordx4 v[160:161], off
	s_add_i32 m0, s26, 0x2000
	s_add_u32 s24, s24, 0x40080
	v_lshl_add_u64 v[160:161], v[218:219], 0, s[64:65]
	s_addc_u32 s25, s25, 0
	s_add_i32 s26, s57, s37
	global_load_lds_dwordx4 v[160:161], off
	v_lshl_add_u64 v[160:161], s[24:25], 0, v[132:133]
	s_mov_b32 m0, s26
	s_nop 0
	global_load_lds_dwordx4 v[160:161], off
	v_lshl_add_u64 v[160:161], s[24:25], 0, v[136:137]
	s_add_i32 m0, s26, 0x2000
	s_nop 0
	global_load_lds_dwordx4 v[160:161], off
	v_lshl_add_u64 v[160:161], v[220:221], 0, s[64:65]
	s_mov_b32 m0, s43
	s_nop 0
	global_load_lds_dwordx4 v[160:161], off
	v_lshl_add_u64 v[160:161], v[222:223], 0, s[64:65]
	s_mov_b32 m0, s49
	s_nop 0
	global_load_lds_dwordx4 v[160:161], off
	s_waitcnt vmcnt(8)
	s_waitcnt lgkmcnt(0)
	s_barrier
	s_setprio 1
	s_waitcnt lgkmcnt(0)
	v_mfma_f32_16x16x32_bf16 v[62:65], v[148:151], v[186:189], v[62:65]
	v_mfma_f32_16x16x32_bf16 v[58:61], v[156:159], v[186:189], v[58:61]
	v_mfma_f32_16x16x32_bf16 v[54:57], v[148:151], v[194:197], v[54:57]
	v_mfma_f32_16x16x32_bf16 v[50:53], v[156:159], v[194:197], v[50:53]
	v_mfma_f32_16x16x32_bf16 v[46:49], v[148:151], v[202:205], v[46:49]
	v_mfma_f32_16x16x32_bf16 v[42:45], v[156:159], v[202:205], v[42:45]
	v_mfma_f32_16x16x32_bf16 v[38:41], v[148:151], v[210:213], v[38:41]
	v_mfma_f32_16x16x32_bf16 v[34:37], v[156:159], v[210:213], v[34:37]
	v_mfma_f32_16x16x32_bf16 v[62:65], v[152:155], v[190:193], v[62:65]
	v_mfma_f32_16x16x32_bf16 v[58:61], v[166:169], v[190:193], v[58:61]
	v_mfma_f32_16x16x32_bf16 v[54:57], v[152:155], v[198:201], v[54:57]
	v_mfma_f32_16x16x32_bf16 v[50:53], v[166:169], v[198:201], v[50:53]
	v_mfma_f32_16x16x32_bf16 v[46:49], v[152:155], v[206:209], v[46:49]
	v_mfma_f32_16x16x32_bf16 v[42:45], v[166:169], v[206:209], v[42:45]
	v_mfma_f32_16x16x32_bf16 v[38:41], v[152:155], v[214:217], v[38:41]
	v_mfma_f32_16x16x32_bf16 v[34:37], v[166:169], v[214:217], v[34:37]
	s_setprio 0
	s_setprio 1
	v_mfma_f32_16x16x32_bf16 v[30:33], v[170:173], v[186:189], v[30:33]
	v_mfma_f32_16x16x32_bf16 v[26:29], v[178:181], v[186:189], v[26:29]
	v_mfma_f32_16x16x32_bf16 v[22:25], v[170:173], v[194:197], v[22:25]
	v_mfma_f32_16x16x32_bf16 v[18:21], v[178:181], v[194:197], v[18:21]
	v_mfma_f32_16x16x32_bf16 v[14:17], v[170:173], v[202:205], v[14:17]
	v_mfma_f32_16x16x32_bf16 v[10:13], v[178:181], v[202:205], v[10:13]
	v_mfma_f32_16x16x32_bf16 v[6:9], v[170:173], v[210:213], v[6:9]
	v_mfma_f32_16x16x32_bf16 v[2:5], v[178:181], v[210:213], v[2:5]
	v_mfma_f32_16x16x32_bf16 v[30:33], v[174:177], v[190:193], v[30:33]
	v_mfma_f32_16x16x32_bf16 v[26:29], v[182:185], v[190:193], v[26:29]
	v_mfma_f32_16x16x32_bf16 v[22:25], v[174:177], v[198:201], v[22:25]
	v_mfma_f32_16x16x32_bf16 v[18:21], v[182:185], v[198:201], v[18:21]
	v_mfma_f32_16x16x32_bf16 v[14:17], v[174:177], v[206:209], v[14:17]
	v_mfma_f32_16x16x32_bf16 v[10:13], v[182:185], v[206:209], v[10:13]
	v_mfma_f32_16x16x32_bf16 v[6:9], v[174:177], v[214:217], v[6:9]
	v_mfma_f32_16x16x32_bf16 v[2:5], v[182:185], v[214:217], v[2:5]
	s_setprio 0
	s_barrier
	s_add_u32 s22, s22, 0x100
	s_addc_u32 s23, s23, 0
	s_cmp_gt_u32 s56, 13
	s_cbranch_scc0 .LBB0_1685
	s_and_b64 vcc, exec, s[4:5]
	s_cbranch_vccz .LBB0_1688
	s_barrier

; #define PG8_STAGE(bufoff, gbase, voff) do { _Pragma("unroll") for (int _i = 0; _i < 2; ++_i) \
;         __builtin_amdgcn_global_load_lds((const unsigned*)((const char*)(gbase) + (voff)[_i]), (PG8_LAS unsigned*)(lds + (bufoff) + ldsw + _i * 8192), 16, 0, 0); } while (0)
; #define PG8_LDA(dst, b, h) do { _Pragma("unroll") for (int m = 0; m < 4; ++m) _Pragma("unroll") for (int k = 0; k < 2; ++k) dst[m][k] = *(const PG8_LAS bf16x8*)(lds + PG8_SA(b, h) + aoff + m * 2048 + k * 1024); } while (0)
; #define PG8_LDB(dst, b, h) do { _Pragma("unroll") for (int n = 0; n < 2; ++n) _Pragma("unroll") for (int k = 0; k < 2; ++k) dst[n][k] = *(const PG8_LAS bf16x8*)(lds + PG8_SB(b, h) + boff + n * 2048 + k * 1024); } while (0)
; #define PG8_MMA(ai, bj, At, Bt) do { __builtin_amdgcn_s_setprio(1); _Pragma("unroll") for (int m = 0; m < 4; ++m) _Pragma("unroll") for (int n = 0; n < 2; ++n) _Pragma("unroll") for (int k = 0; k < 2; ++k) \
;         acc[ai][bj][m][n] = __builtin_amdgcn_mfma_f32_16x16x32_bf16(Bt[n][k], At[m][k], acc[ai][bj][m][n], 0, 0, 0); __builtin_amdgcn_s_setprio(0); } while (0)
; #define PG8_WAIT_V(n) asm volatile("s_waitcnt vmcnt(" #n ")" ::: "memory")
; #define PG8_WAIT_VN(n) asm volatile("s_waitcnt vmcnt(%0)" :: "n"(n) : "memory")
; #define PG8_WAIT_L(n) asm volatile("s_waitcnt lgkmcnt(" #n ")" ::: "memory")
; #define PG8_BAR __builtin_amdgcn_s_barrier()
; #define PG8_SCHED __builtin_amdgcn_sched_barrier(0)
; template <class Epi, class Sched, bool ALIGN_EPI = false, bool SP2 = false>
; __device__ __forceinline__ void gemm_phase(PG8_LAS unsigned char* lds, const Gemm g, const Sched& S, const Epi& E, const int wave_id) {
;     ...
;             PG8_WAIT_VN(8 + Epi::NS); if (strict) PG8_WAIT_V(8); PG8_WAIT_L(0); PG8_BAR; PG8_MMA(1, 0, At, B0); PG8_MMA(1, 1, At, B1); PG8_BAR; PG8_SCHED;
;             PG8_LDB(B0, 1, 0); PG8_LDB(B1, 1, 1); PG8_SCHED; PG8_LDA(At, 1, 0); PG8_STAGE(PG8_SA(0, 1), a2 + hstep, voffA);
.LBB0_1821:
	s_waitcnt lgkmcnt(0)
	s_barrier
	s_setprio 1
	s_waitcnt lgkmcnt(0)
	v_mfma_f32_16x16x32_bf16 v[62:65], v[146:149], v[186:189], v[62:65]
	v_mfma_f32_16x16x32_bf16 v[58:61], v[154:157], v[186:189], v[58:61]
	v_mfma_f32_16x16x32_bf16 v[46:49], v[146:149], v[178:181], v[46:49]
	v_mfma_f32_16x16x32_bf16 v[42:45], v[154:157], v[178:181], v[42:45]
	v_mfma_f32_16x16x32_bf16 v[30:33], v[146:149], v[170:173], v[30:33]
	v_mfma_f32_16x16x32_bf16 v[26:29], v[154:157], v[170:173], v[26:29]
	v_mfma_f32_16x16x32_bf16 v[14:17], v[146:149], v[162:165], v[14:17]
	v_mfma_f32_16x16x32_bf16 v[10:13], v[154:157], v[162:165], v[10:13]
	v_mfma_f32_16x16x32_bf16 v[62:65], v[150:153], v[190:193], v[62:65]
	v_mfma_f32_16x16x32_bf16 v[58:61], v[158:161], v[190:193], v[58:61]
	v_mfma_f32_16x16x32_bf16 v[46:49], v[150:153], v[182:185], v[46:49]
	v_mfma_f32_16x16x32_bf16 v[42:45], v[158:161], v[182:185], v[42:45]
	v_mfma_f32_16x16x32_bf16 v[30:33], v[150:153], v[174:177], v[30:33]
	v_mfma_f32_16x16x32_bf16 v[26:29], v[158:161], v[174:177], v[26:29]
	v_mfma_f32_16x16x32_bf16 v[14:17], v[150:153], v[166:169], v[14:17]
	v_mfma_f32_16x16x32_bf16 v[10:13], v[158:161], v[166:169], v[10:13]
	s_setprio 0
	s_setprio 1
	v_mfma_f32_16x16x32_bf16 v[54:57], v[130:133], v[186:189], v[54:57]
	v_mfma_f32_16x16x32_bf16 v[50:53], v[138:141], v[186:189], v[50:53]
	v_mfma_f32_16x16x32_bf16 v[38:41], v[130:133], v[178:181], v[38:41]
	v_mfma_f32_16x16x32_bf16 v[34:37], v[138:141], v[178:181], v[34:37]
	v_mfma_f32_16x16x32_bf16 v[22:25], v[130:133], v[170:173], v[22:25]
	v_mfma_f32_16x16x32_bf16 v[18:21], v[138:141], v[170:173], v[18:21]
	v_mfma_f32_16x16x32_bf16 v[6:9], v[130:133], v[162:165], v[6:9]
	v_mfma_f32_16x16x32_bf16 v[2:5], v[138:141], v[162:165], v[2:5]
	v_mfma_f32_16x16x32_bf16 v[54:57], v[134:137], v[190:193], v[54:57]
	v_mfma_f32_16x16x32_bf16 v[50:53], v[142:145], v[190:193], v[50:53]
	v_mfma_f32_16x16x32_bf16 v[38:41], v[134:137], v[182:185], v[38:41]
	v_mfma_f32_16x16x32_bf16 v[34:37], v[142:145], v[182:185], v[34:37]
	v_mfma_f32_16x16x32_bf16 v[22:25], v[134:137], v[174:177], v[22:25]
	v_mfma_f32_16x16x32_bf16 v[18:21], v[142:145], v[174:177], v[18:21]
	v_mfma_f32_16x16x32_bf16 v[6:9], v[134:137], v[166:169], v[6:9]
	v_mfma_f32_16x16x32_bf16 v[2:5], v[142:145], v[166:169], v[2:5]
	s_setprio 0
	s_barrier
	ds_read_b128 v[162:165], v247 offset:32768
	ds_read_b128 v[166:169], v247 offset:33792
	ds_read_b128 v[170:173], v247 offset:34816
	ds_read_b128 v[174:177], v247 offset:35840
	ds_read_b128 v[178:181], v247 offset:36864
	ds_read_b128 v[182:185], v247 offset:37888
	ds_read_b128 v[186:189], v247 offset:38912
	ds_read_b128 v[190:193], v247 offset:39936
	s_add_i32 s26, 0, 0x18000
	s_add_i32 s27, 0, 0x1c000
	v_add_u32_e32 v142, s26, v246
	v_add_u32_e32 v158, s27, v246
	ds_read_b128 v[130:133], v142
	ds_read_b128 v[134:137], v142 offset:1024
	ds_read_b128 v[138:141], v142 offset:2048
	ds_read_b128 v[142:145], v142 offset:3072
	ds_read_b128 v[146:149], v158
	ds_read_b128 v[150:153], v158 offset:1024
	ds_read_b128 v[154:157], v158 offset:2048
	ds_read_b128 v[158:161], v158 offset:3072
	s_add_u32 s24, s24, 0x40000
	s_addc_u32 s25, s25, 0
	s_mov_b32 m0, s50
	v_lshl_add_u64 v[194:195], s[24:25], 0, v[210:211]
	global_load_lds_dwordx4 v[194:195], off
	v_lshl_add_u64 v[194:195], s[24:25], 0, v[214:215]
	s_mov_b32 m0, s51
	s_nop 0
	global_load_lds_dwordx4 v[194:195], off
	s_waitcnt vmcnt(26)
	s_cmp_eq_u32 s100, 0
	s_cbranch_scc1 .Lthird_wait_relaxed_3
	s_waitcnt vmcnt(8)
; #define PG8_STAGE(bufoff, gbase, voff) do { _Pragma("unroll") for (int _i = 0; _i < 2; ++_i) \
;         __builtin_amdgcn_global_load_lds((const unsigned*)((const char*)(gbase) + (voff)[_i]), (PG8_LAS unsigned*)(lds + (bufoff) + ldsw + _i * 8192), 16, 0, 0); } while (0)
; #define PG8_LDA(dst, b, h) do { _Pragma("unroll") for (int m = 0; m < 4; ++m) _Pragma("unroll") for (int k = 0; k < 2; ++k) dst[m][k] = *(const PG8_LAS bf16x8*)(lds + PG8_SA(b, h) + aoff + m * 2048 + k * 1024); } while (0)
; #define PG8_LDB(dst, b, h) do { _Pragma("unroll") for (int n = 0; n < 2; ++n) _Pragma("unroll") for (int k = 0; k < 2; ++k) dst[n][k] = *(const PG8_LAS bf16x8*)(lds + PG8_SB(b, h) + boff + n * 2048 + k * 1024); } while (0)
; #define PG8_MMA(ai, bj, At, Bt) do { __builtin_amdgcn_s_setprio(1); _Pragma("unroll") for (int m = 0; m < 4; ++m) _Pragma("unroll") for (int n = 0; n < 2; ++n) _Pragma("unroll") for (int k = 0; k < 2; ++k) \
;         acc[ai][bj][m][n] = __builtin_amdgcn_mfma_f32_16x16x32_bf16(Bt[n][k], At[m][k], acc[ai][bj][m][n], 0, 0, 0); __builtin_amdgcn_s_setprio(0); } while (0)
; #define PG8_WAIT_V(n) asm volatile("s_waitcnt vmcnt(" #n ")" ::: "memory")
; #define PG8_WAIT_L(n) asm volatile("s_waitcnt lgkmcnt(" #n ")" ::: "memory")
; #define PG8_BAR __builtin_amdgcn_s_barrier()
; #define PG8_SCHED __builtin_amdgcn_sched_barrier(0)
; template <class Epi, class Sched, bool ALIGN_EPI = false, bool SP2 = false>
; __device__ __forceinline__ void gemm_phase(PG8_LAS unsigned char* lds, const Gemm g, const Sched& S, const Epi& E, const int wave_id) {
;     ...
;         for (int t = 0; t < nt; t += 2) {
;     ...
;             PG8_LDB(B0, 1, 0); PG8_LDB(B1, 1, 1); PG8_SCHED; PG8_LDA(At, 1, 0); PG8_STAGE(PG8_SA(0, 1), a2 + hstep, voffA);
;             PG8_WAIT_V(8); PG8_WAIT_L(0); PG8_BAR; PG8_MMA(0, 0, At, B0); PG8_MMA(0, 1, At, B1); PG8_BAR; PG8_SCHED;
;             PG8_LDA(At, 1, 1); PG8_STAGE(PG8_SB(1, 0), b3, voffB); PG8_STAGE(PG8_SB(1, 1), b3 + hstep, voffB); PG8_STAGE(PG8_SA(1, 0), a3, voffA);
;             PG8_WAIT_V(8); PG8_WAIT_L(0); PG8_BAR; PG8_MMA(1, 0, At, B0); PG8_MMA(1, 1, At, B1); PG8_BAR; PG8_SCHED;
.Lthird_wait_relaxed_3:
	s_waitcnt lgkmcnt(0)
	s_barrier
	s_setprio 1
	s_waitcnt lgkmcnt(0)
	v_mfma_f32_16x16x32_bf16 v[126:129], v[130:133], v[162:165], v[126:129]
	v_mfma_f32_16x16x32_bf16 v[122:125], v[138:141], v[162:165], v[122:125]
	v_mfma_f32_16x16x32_bf16 v[110:113], v[130:133], v[170:173], v[110:113]
	v_mfma_f32_16x16x32_bf16 v[106:109], v[138:141], v[170:173], v[106:109]
	v_mfma_f32_16x16x32_bf16 v[94:97], v[130:133], v[178:181], v[94:97]
	v_mfma_f32_16x16x32_bf16 v[90:93], v[138:141], v[178:181], v[90:93]
	v_mfma_f32_16x16x32_bf16 v[78:81], v[130:133], v[186:189], v[78:81]
	v_mfma_f32_16x16x32_bf16 v[74:77], v[138:141], v[186:189], v[74:77]
	v_mfma_f32_16x16x32_bf16 v[126:129], v[134:137], v[166:169], v[126:129]
	v_mfma_f32_16x16x32_bf16 v[122:125], v[142:145], v[166:169], v[122:125]
	v_mfma_f32_16x16x32_bf16 v[110:113], v[134:137], v[174:177], v[110:113]
	v_mfma_f32_16x16x32_bf16 v[106:109], v[142:145], v[174:177], v[106:109]
	v_mfma_f32_16x16x32_bf16 v[94:97], v[134:137], v[182:185], v[94:97]
	v_mfma_f32_16x16x32_bf16 v[90:93], v[142:145], v[182:185], v[90:93]
	v_mfma_f32_16x16x32_bf16 v[78:81], v[134:137], v[190:193], v[78:81]
	v_mfma_f32_16x16x32_bf16 v[74:77], v[142:145], v[190:193], v[74:77]
	s_setprio 0
	s_setprio 1
	v_mfma_f32_16x16x32_bf16 v[118:121], v[146:149], v[162:165], v[118:121]
	v_mfma_f32_16x16x32_bf16 v[114:117], v[154:157], v[162:165], v[114:117]
	v_mfma_f32_16x16x32_bf16 v[102:105], v[146:149], v[170:173], v[102:105]
	v_mfma_f32_16x16x32_bf16 v[98:101], v[154:157], v[170:173], v[98:101]
	v_mfma_f32_16x16x32_bf16 v[86:89], v[146:149], v[178:181], v[86:89]
	v_mfma_f32_16x16x32_bf16 v[82:85], v[154:157], v[178:181], v[82:85]
	v_mfma_f32_16x16x32_bf16 v[70:73], v[146:149], v[186:189], v[70:73]
	v_mfma_f32_16x16x32_bf16 v[66:69], v[154:157], v[186:189], v[66:69]
	v_mfma_f32_16x16x32_bf16 v[118:121], v[150:153], v[166:169], v[118:121]
	v_mfma_f32_16x16x32_bf16 v[114:117], v[158:161], v[166:169], v[114:117]
	v_mfma_f32_16x16x32_bf16 v[102:105], v[150:153], v[174:177], v[102:105]
	v_mfma_f32_16x16x32_bf16 v[98:101], v[158:161], v[174:177], v[98:101]
	v_mfma_f32_16x16x32_bf16 v[86:89], v[150:153], v[182:185], v[86:89]
	v_mfma_f32_16x16x32_bf16 v[82:85], v[158:161], v[182:185], v[82:85]
	v_mfma_f32_16x16x32_bf16 v[70:73], v[150:153], v[190:193], v[70:73]
	v_mfma_f32_16x16x32_bf16 v[66:69], v[158:161], v[190:193], v[66:69]
	s_setprio 0
	s_barrier
	ds_read_b128 v[162:165], v247 offset:49152
	ds_read_b128 v[166:169], v247 offset:50176
	ds_read_b128 v[170:173], v247 offset:51200
	ds_read_b128 v[174:177], v247 offset:52224
	ds_read_b128 v[178:181], v247 offset:53248
	ds_read_b128 v[182:185], v247 offset:54272
	ds_read_b128 v[186:189], v247 offset:55296
	ds_read_b128 v[190:193], v247 offset:56320
	s_add_i32 s24, s26, s38
	v_lshl_add_u64 v[194:195], v[232:233], 0, s[64:65]
	s_mov_b32 m0, s24
	s_nop 0
	global_load_lds_dwordx4 v[194:195], off
	s_add_i32 m0, s24, 0x2000
	s_add_u32 s22, s22, 0x40080
	v_lshl_add_u64 v[194:195], v[230:231], 0, s[64:65]
	s_addc_u32 s23, s23, 0
	s_add_i32 s24, s27, s38
	global_load_lds_dwordx4 v[194:195], off
	v_lshl_add_u64 v[194:195], s[22:23], 0, v[212:213]
	s_mov_b32 m0, s24
	s_nop 0
	global_load_lds_dwordx4 v[194:195], off
	v_lshl_add_u64 v[194:195], s[22:23], 0, v[216:217]
	s_add_i32 m0, s24, 0x2000
	s_nop 0
	global_load_lds_dwordx4 v[194:195], off
	v_lshl_add_u64 v[194:195], v[226:227], 0, s[64:65]
	s_mov_b32 m0, s54
	s_nop 0
	global_load_lds_dwordx4 v[194:195], off
	v_lshl_add_u64 v[194:195], v[228:229], 0, s[64:65]
	s_mov_b32 m0, s56
	s_nop 0
	global_load_lds_dwordx4 v[194:195], off
	s_waitcnt vmcnt(8)
	s_waitcnt lgkmcnt(0)
	s_barrier
	s_setprio 1
	s_waitcnt lgkmcnt(0)
	v_mfma_f32_16x16x32_bf16 v[62:65], v[130:133], v[162:165], v[62:65]
	v_mfma_f32_16x16x32_bf16 v[58:61], v[138:141], v[162:165], v[58:61]
	v_mfma_f32_16x16x32_bf16 v[46:49], v[130:133], v[170:173], v[46:49]
	v_mfma_f32_16x16x32_bf16 v[42:45], v[138:141], v[170:173], v[42:45]
	v_mfma_f32_16x16x32_bf16 v[30:33], v[130:133], v[178:181], v[30:33]
	v_mfma_f32_16x16x32_bf16 v[26:29], v[138:141], v[178:181], v[26:29]
	v_mfma_f32_16x16x32_bf16 v[14:17], v[130:133], v[186:189], v[14:17]
	v_mfma_f32_16x16x32_bf16 v[10:13], v[138:141], v[186:189], v[10:13]
	v_mfma_f32_16x16x32_bf16 v[62:65], v[134:137], v[166:169], v[62:65]
	v_mfma_f32_16x16x32_bf16 v[58:61], v[142:145], v[166:169], v[58:61]
	v_mfma_f32_16x16x32_bf16 v[46:49], v[134:137], v[174:177], v[46:49]
	v_mfma_f32_16x16x32_bf16 v[42:45], v[142:145], v[174:177], v[42:45]
	v_mfma_f32_16x16x32_bf16 v[30:33], v[134:137], v[182:185], v[30:33]
	v_mfma_f32_16x16x32_bf16 v[26:29], v[142:145], v[182:185], v[26:29]
	v_mfma_f32_16x16x32_bf16 v[14:17], v[134:137], v[190:193], v[14:17]
	v_mfma_f32_16x16x32_bf16 v[10:13], v[142:145], v[190:193], v[10:13]
	s_setprio 0
	s_setprio 1
	v_mfma_f32_16x16x32_bf16 v[54:57], v[146:149], v[162:165], v[54:57]
	v_mfma_f32_16x16x32_bf16 v[50:53], v[154:157], v[162:165], v[50:53]
	v_mfma_f32_16x16x32_bf16 v[38:41], v[146:149], v[170:173], v[38:41]
	v_mfma_f32_16x16x32_bf16 v[34:37], v[154:157], v[170:173], v[34:37]
	v_mfma_f32_16x16x32_bf16 v[22:25], v[146:149], v[178:181], v[22:25]
	v_mfma_f32_16x16x32_bf16 v[18:21], v[154:157], v[178:181], v[18:21]
	v_mfma_f32_16x16x32_bf16 v[6:9], v[146:149], v[186:189], v[6:9]
	v_mfma_f32_16x16x32_bf16 v[2:5], v[154:157], v[186:189], v[2:5]
	v_mfma_f32_16x16x32_bf16 v[54:57], v[150:153], v[166:169], v[54:57]
	v_mfma_f32_16x16x32_bf16 v[50:53], v[158:161], v[166:169], v[50:53]
	v_mfma_f32_16x16x32_bf16 v[38:41], v[150:153], v[174:177], v[38:41]
	v_mfma_f32_16x16x32_bf16 v[34:37], v[158:161], v[174:177], v[34:37]
	v_mfma_f32_16x16x32_bf16 v[22:25], v[150:153], v[182:185], v[22:25]
	v_mfma_f32_16x16x32_bf16 v[18:21], v[158:161], v[182:185], v[18:21]
	v_mfma_f32_16x16x32_bf16 v[6:9], v[150:153], v[190:193], v[6:9]
	v_mfma_f32_16x16x32_bf16 v[2:5], v[158:161], v[190:193], v[2:5]
	s_setprio 0
	s_add_i32 s74, s74, 2
	s_add_u32 s20, s20, 0x100
	s_addc_u32 s21, s21, 0
	s_cmp_gt_u32 s74, 13
	s_barrier
	s_cbranch_scc1 .LBB0_1826

; #define PG8_STAGE(bufoff, gbase, voff) do { _Pragma("unroll") for (int _i = 0; _i < 2; ++_i) \
;         __builtin_amdgcn_global_load_lds((const unsigned*)((const char*)(gbase) + (voff)[_i]), (PG8_LAS unsigned*)(lds + (bufoff) + ldsw + _i * 8192), 16, 0, 0); } while (0)
; #define PG8_LDA(dst, b, h) do { _Pragma("unroll") for (int m = 0; m < 4; ++m) _Pragma("unroll") for (int k = 0; k < 2; ++k) dst[m][k] = *(const PG8_LAS bf16x8*)(lds + PG8_SA(b, h) + aoff + m * 2048 + k * 1024); } while (0)
; #define PG8_LDB(dst, b, h) do { _Pragma("unroll") for (int n = 0; n < 2; ++n) _Pragma("unroll") for (int k = 0; k < 2; ++k) dst[n][k] = *(const PG8_LAS bf16x8*)(lds + PG8_SB(b, h) + boff + n * 2048 + k * 1024); } while (0)
; #define PG8_MMA(ai, bj, At, Bt) do { __builtin_amdgcn_s_setprio(1); _Pragma("unroll") for (int m = 0; m < 4; ++m) _Pragma("unroll") for (int n = 0; n < 2; ++n) _Pragma("unroll") for (int k = 0; k < 2; ++k) \
;         acc[ai][bj][m][n] = __builtin_amdgcn_mfma_f32_16x16x32_bf16(Bt[n][k], At[m][k], acc[ai][bj][m][n], 0, 0, 0); __builtin_amdgcn_s_setprio(0); } while (0)
; #define PG8_WAIT_V(n) asm volatile("s_waitcnt vmcnt(" #n ")" ::: "memory")
; #define PG8_WAIT_VN(n) asm volatile("s_waitcnt vmcnt(%0)" :: "n"(n) : "memory")
; template <class Epi, class Sched, bool ALIGN_EPI = false, bool SP2 = false>
; __device__ __forceinline__ void gemm_phase(PG8_LAS unsigned char* lds, const Gemm g, const Sched& S, const Epi& E, const int wave_id) {
;     ...
;             const bool last = (t == nt - 2);
;             const char* a1 = cA + (size_t)(t + 1) * kstep;
;             const char* a2 = last ? nA : cA + (size_t)(t + 2) * kstep; const char* b2 = last ? nB : cB + (size_t)(t + 2) * kstep;
;             const char* a3 = a2 + kstep; const char* b3 = b2 + kstep;
;     ...
;             PG8_LDB(B0, 0, 0); PG8_LDB(B1, 0, 1); PG8_SCHED; PG8_LDA(At, 0, 0); PG8_STAGE(PG8_SA(1, 1), a1 + hstep, voffA);
;             PG8_WAIT_VN(8 + Epi::NS); if (strict) PG8_WAIT_V(8); PG8_WAIT_L(0); PG8_BAR; PG8_MMA(0, 0, At, B0); PG8_MMA(0, 1, At, B1); PG8_BAR; PG8_SCHED;
;             PG8_LDA(At, 0, 1); PG8_STAGE(PG8_SB(0, 0), b2, voffB); PG8_STAGE(PG8_SB(0, 1), b2 + hstep, voffB); PG8_STAGE(PG8_SA(0, 0), a2, voffA);
;             PG8_WAIT_VN(8 + Epi::NS); if (strict) PG8_WAIT_V(8); PG8_WAIT_L(0); PG8_BAR; PG8_MMA(1, 0, At, B0); PG8_MMA(1, 1, At, B1); PG8_BAR; PG8_SCHED;
.LBB0_1824:
	s_add_u32 s22, s18, s20
	s_addc_u32 s23, s19, s21
	s_add_u32 s22, s22, 0x100
	s_addc_u32 s23, s23, 0
	s_add_u32 s53, s68, s20
	s_addc_u32 s75, s69, s21
	s_waitcnt lgkmcnt(0)
	s_cmpk_eq_i32 s20, 0x700
	s_cselect_b32 s25, s11, s23
	s_cselect_b32 s24, s63, s22
	s_cselect_b32 s23, s9, s75
	s_cselect_b32 s22, s67, s53
	s_barrier
	s_setprio 1
	s_waitcnt lgkmcnt(0)
	v_mfma_f32_16x16x32_bf16 v[126:129], v[146:149], v[186:189], v[126:129]
	v_mfma_f32_16x16x32_bf16 v[122:125], v[154:157], v[186:189], v[122:125]
	v_mfma_f32_16x16x32_bf16 v[110:113], v[146:149], v[178:181], v[110:113]
	v_mfma_f32_16x16x32_bf16 v[106:109], v[154:157], v[178:181], v[106:109]
	v_mfma_f32_16x16x32_bf16 v[94:97], v[146:149], v[170:173], v[94:97]
	v_mfma_f32_16x16x32_bf16 v[90:93], v[154:157], v[170:173], v[90:93]
	v_mfma_f32_16x16x32_bf16 v[78:81], v[146:149], v[162:165], v[78:81]
	v_mfma_f32_16x16x32_bf16 v[74:77], v[154:157], v[162:165], v[74:77]
	v_mfma_f32_16x16x32_bf16 v[126:129], v[150:153], v[190:193], v[126:129]
	v_mfma_f32_16x16x32_bf16 v[122:125], v[158:161], v[190:193], v[122:125]
	v_mfma_f32_16x16x32_bf16 v[110:113], v[150:153], v[182:185], v[110:113]
	v_mfma_f32_16x16x32_bf16 v[106:109], v[158:161], v[182:185], v[106:109]
	v_mfma_f32_16x16x32_bf16 v[94:97], v[150:153], v[174:177], v[94:97]
	v_mfma_f32_16x16x32_bf16 v[90:93], v[158:161], v[174:177], v[90:93]
	v_mfma_f32_16x16x32_bf16 v[78:81], v[150:153], v[166:169], v[78:81]
	v_mfma_f32_16x16x32_bf16 v[74:77], v[158:161], v[166:169], v[74:77]
	s_setprio 0
	s_setprio 1
	v_mfma_f32_16x16x32_bf16 v[118:121], v[130:133], v[186:189], v[118:121]
	v_mfma_f32_16x16x32_bf16 v[114:117], v[138:141], v[186:189], v[114:117]
	v_mfma_f32_16x16x32_bf16 v[102:105], v[130:133], v[178:181], v[102:105]
	v_mfma_f32_16x16x32_bf16 v[98:101], v[138:141], v[178:181], v[98:101]
	v_mfma_f32_16x16x32_bf16 v[86:89], v[130:133], v[170:173], v[86:89]
	v_mfma_f32_16x16x32_bf16 v[82:85], v[138:141], v[170:173], v[82:85]
	v_mfma_f32_16x16x32_bf16 v[70:73], v[130:133], v[162:165], v[70:73]
	v_mfma_f32_16x16x32_bf16 v[66:69], v[138:141], v[162:165], v[66:69]
	v_mfma_f32_16x16x32_bf16 v[118:121], v[134:137], v[190:193], v[118:121]
	v_mfma_f32_16x16x32_bf16 v[114:117], v[142:145], v[190:193], v[114:117]
	v_mfma_f32_16x16x32_bf16 v[102:105], v[134:137], v[182:185], v[102:105]
	v_mfma_f32_16x16x32_bf16 v[98:101], v[142:145], v[182:185], v[98:101]
	v_mfma_f32_16x16x32_bf16 v[86:89], v[134:137], v[174:177], v[86:89]
	v_mfma_f32_16x16x32_bf16 v[82:85], v[142:145], v[174:177], v[82:85]
	v_mfma_f32_16x16x32_bf16 v[70:73], v[134:137], v[166:169], v[70:73]
	v_mfma_f32_16x16x32_bf16 v[66:69], v[142:145], v[166:169], v[66:69]
	s_setprio 0
	s_barrier
	ds_read_b128 v[186:189], v247 offset:16384
	ds_read_b128 v[190:193], v247 offset:17408
	ds_read_b128 v[178:181], v247 offset:18432
	ds_read_b128 v[182:185], v247 offset:19456
	ds_read_b128 v[170:173], v247 offset:20480
	ds_read_b128 v[174:177], v247 offset:21504
	ds_read_b128 v[162:165], v247 offset:22528
	ds_read_b128 v[166:169], v247 offset:23552
	s_mov_b32 m0, s40
	v_lshl_add_u64 v[232:233], s[22:23], 0, v[212:213]
	s_add_u32 s90, s22, 0x40000
	global_load_lds_dwordx4 v[232:233], off
	v_lshl_add_u64 v[230:231], s[22:23], 0, v[216:217]
	s_mov_b32 m0, s41
	s_addc_u32 s91, s23, 0
	global_load_lds_dwordx4 v[230:231], off
	v_lshl_add_u64 v[194:195], s[90:91], 0, v[212:213]
	s_mov_b32 m0, s42
	v_lshl_add_u64 v[226:227], s[24:25], 0, v[210:211]
	global_load_lds_dwordx4 v[194:195], off
	v_lshl_add_u64 v[194:195], s[90:91], 0, v[216:217]
	s_mov_b32 m0, s43
	v_lshl_add_u64 v[228:229], s[24:25], 0, v[214:215]
	global_load_lds_dwordx4 v[194:195], off
	s_mov_b32 m0, s39
	s_andn2_b64 vcc, exec, s[26:27]
	global_load_lds_dwordx4 v[226:227], off
	s_mov_b32 m0, s49
	s_nop 0
	global_load_lds_dwordx4 v[228:229], off
	s_waitcnt vmcnt(24)
	s_cbranch_vccnz .LBB0_1821
	s_waitcnt vmcnt(8)
	s_branch .LBB0_1821

; #define PG8_STAGE(bufoff, gbase, voff) do { _Pragma("unroll") for (int _i = 0; _i < 2; ++_i) \
;         __builtin_amdgcn_global_load_lds((const unsigned*)((const char*)(gbase) + (voff)[_i]), (PG8_LAS unsigned*)(lds + (bufoff) + ldsw + _i * 8192), 16, 0, 0); } while (0)
; #define PG8_LDA(dst, b, h) do { _Pragma("unroll") for (int m = 0; m < 4; ++m) _Pragma("unroll") for (int k = 0; k < 2; ++k) dst[m][k] = *(const PG8_LAS bf16x8*)(lds + PG8_SA(b, h) + aoff + m * 2048 + k * 1024); } while (0)
; #define PG8_LDB(dst, b, h) do { _Pragma("unroll") for (int n = 0; n < 2; ++n) _Pragma("unroll") for (int k = 0; k < 2; ++k) dst[n][k] = *(const PG8_LAS bf16x8*)(lds + PG8_SB(b, h) + boff + n * 2048 + k * 1024); } while (0)
; #define PG8_MMA(ai, bj, At, Bt) do { __builtin_amdgcn_s_setprio(1); _Pragma("unroll") for (int m = 0; m < 4; ++m) _Pragma("unroll") for (int n = 0; n < 2; ++n) _Pragma("unroll") for (int k = 0; k < 2; ++k) \
;         acc[ai][bj][m][n] = __builtin_amdgcn_mfma_f32_16x16x32_bf16(Bt[n][k], At[m][k], acc[ai][bj][m][n], 0, 0, 0); __builtin_amdgcn_s_setprio(0); } while (0)
; #define PG8_WAIT_V(n) asm volatile("s_waitcnt vmcnt(" #n ")" ::: "memory")
; #define PG8_WAIT_L(n) asm volatile("s_waitcnt lgkmcnt(" #n ")" ::: "memory")
; #define PG8_BAR __builtin_amdgcn_s_barrier()
; #define PG8_SCHED __builtin_amdgcn_sched_barrier(0)
; template <class Epi, class Sched, bool ALIGN_EPI = false, bool SP2 = false>
; __device__ __forceinline__ void gemm_phase(PG8_LAS unsigned char* lds, const Gemm g, const Sched& S, const Epi& E, const int wave_id) {
;     ...
;             PG8_LDB(B0, 1, 0); PG8_LDB(B1, 1, 1); PG8_SCHED; PG8_LDA(At, 1, 0); PG8_STAGE(PG8_SA(0, 1), a2 + hstep, voffA);
;             PG8_WAIT_V(8); PG8_WAIT_L(0); PG8_BAR; PG8_MMA(0, 0, At, B0); PG8_MMA(0, 1, At, B1); PG8_BAR; PG8_SCHED;
.LBB0_1889:
	s_waitcnt lgkmcnt(0)
	s_barrier
	s_setprio 1
	s_waitcnt lgkmcnt(0)
	v_mfma_f32_16x16x32_bf16 v[62:65], v[146:149], v[186:189], v[62:65]
	v_mfma_f32_16x16x32_bf16 v[58:61], v[154:157], v[186:189], v[58:61]
	v_mfma_f32_16x16x32_bf16 v[54:57], v[146:149], v[178:181], v[54:57]
	v_mfma_f32_16x16x32_bf16 v[50:53], v[154:157], v[178:181], v[50:53]
	v_mfma_f32_16x16x32_bf16 v[30:33], v[146:149], v[170:173], v[30:33]
	v_mfma_f32_16x16x32_bf16 v[26:29], v[154:157], v[170:173], v[26:29]
	v_mfma_f32_16x16x32_bf16 v[22:25], v[146:149], v[162:165], v[22:25]
	v_mfma_f32_16x16x32_bf16 v[18:21], v[154:157], v[162:165], v[18:21]
	v_mfma_f32_16x16x32_bf16 v[62:65], v[150:153], v[190:193], v[62:65]
	v_mfma_f32_16x16x32_bf16 v[58:61], v[158:161], v[190:193], v[58:61]
	v_mfma_f32_16x16x32_bf16 v[54:57], v[150:153], v[182:185], v[54:57]
	v_mfma_f32_16x16x32_bf16 v[50:53], v[158:161], v[182:185], v[50:53]
	v_mfma_f32_16x16x32_bf16 v[30:33], v[150:153], v[174:177], v[30:33]
	v_mfma_f32_16x16x32_bf16 v[26:29], v[158:161], v[174:177], v[26:29]
	v_mfma_f32_16x16x32_bf16 v[22:25], v[150:153], v[166:169], v[22:25]
	v_mfma_f32_16x16x32_bf16 v[18:21], v[158:161], v[166:169], v[18:21]
	s_setprio 0
	s_setprio 1
	v_mfma_f32_16x16x32_bf16 v[46:49], v[130:133], v[186:189], v[46:49]
	v_mfma_f32_16x16x32_bf16 v[42:45], v[138:141], v[186:189], v[42:45]
	v_mfma_f32_16x16x32_bf16 v[38:41], v[130:133], v[178:181], v[38:41]
	v_mfma_f32_16x16x32_bf16 v[34:37], v[138:141], v[178:181], v[34:37]
	v_mfma_f32_16x16x32_bf16 v[14:17], v[130:133], v[170:173], v[14:17]
	v_mfma_f32_16x16x32_bf16 v[10:13], v[138:141], v[170:173], v[10:13]
	v_mfma_f32_16x16x32_bf16 v[6:9], v[130:133], v[162:165], v[6:9]
	v_mfma_f32_16x16x32_bf16 v[2:5], v[138:141], v[162:165], v[2:5]
	v_mfma_f32_16x16x32_bf16 v[46:49], v[134:137], v[190:193], v[46:49]
	v_mfma_f32_16x16x32_bf16 v[42:45], v[142:145], v[190:193], v[42:45]
	v_mfma_f32_16x16x32_bf16 v[38:41], v[134:137], v[182:185], v[38:41]
	v_mfma_f32_16x16x32_bf16 v[34:37], v[142:145], v[182:185], v[34:37]
	v_mfma_f32_16x16x32_bf16 v[14:17], v[134:137], v[174:177], v[14:17]
	v_mfma_f32_16x16x32_bf16 v[10:13], v[142:145], v[174:177], v[10:13]
	v_mfma_f32_16x16x32_bf16 v[6:9], v[134:137], v[166:169], v[6:9]
	v_mfma_f32_16x16x32_bf16 v[2:5], v[142:145], v[166:169], v[2:5]
	s_setprio 0
	s_barrier
	ds_read_b128 v[162:165], v232 offset:32768
	ds_read_b128 v[166:169], v232 offset:33792
	ds_read_b128 v[170:173], v232 offset:34816
	ds_read_b128 v[174:177], v232 offset:35840
	ds_read_b128 v[178:181], v232 offset:36864
	ds_read_b128 v[182:185], v232 offset:37888
	ds_read_b128 v[186:189], v232 offset:38912
	ds_read_b128 v[190:193], v232 offset:39936
	s_add_i32 s16, 0, 0x18000
	s_add_i32 s17, 0, 0x1c000
	v_add_u32_e32 v142, s16, v231
	v_add_u32_e32 v158, s17, v231
	ds_read_b128 v[130:133], v142
	ds_read_b128 v[134:137], v142 offset:1024
	ds_read_b128 v[138:141], v142 offset:2048
	ds_read_b128 v[142:145], v142 offset:3072
	ds_read_b128 v[146:149], v158
	ds_read_b128 v[150:153], v158 offset:1024
	ds_read_b128 v[154:157], v158 offset:2048
	ds_read_b128 v[158:161], v158 offset:3072
	s_add_u32 s14, s14, 0x40000
	s_addc_u32 s15, s15, 0
	s_mov_b32 m0, s28
	v_lshl_add_u64 v[194:195], s[14:15], 0, v[210:211]
	global_load_lds_dwordx4 v[194:195], off
	v_lshl_add_u64 v[194:195], s[14:15], 0, v[214:215]
	s_mov_b32 m0, s29
	s_nop 0
	global_load_lds_dwordx4 v[194:195], off
	s_waitcnt vmcnt(8)
	s_waitcnt lgkmcnt(0)
	s_barrier
	s_setprio 1
	s_waitcnt lgkmcnt(0)
	v_mfma_f32_16x16x32_bf16 v[126:129], v[130:133], v[162:165], v[126:129]
	v_mfma_f32_16x16x32_bf16 v[122:125], v[138:141], v[162:165], v[122:125]
	v_mfma_f32_16x16x32_bf16 v[118:121], v[130:133], v[170:173], v[118:121]
	v_mfma_f32_16x16x32_bf16 v[114:117], v[138:141], v[170:173], v[114:117]
	v_mfma_f32_16x16x32_bf16 v[94:97], v[130:133], v[178:181], v[94:97]
	v_mfma_f32_16x16x32_bf16 v[90:93], v[138:141], v[178:181], v[90:93]
	v_mfma_f32_16x16x32_bf16 v[86:89], v[130:133], v[186:189], v[86:89]
	v_mfma_f32_16x16x32_bf16 v[82:85], v[138:141], v[186:189], v[82:85]
	v_mfma_f32_16x16x32_bf16 v[126:129], v[134:137], v[166:169], v[126:129]
	v_mfma_f32_16x16x32_bf16 v[122:125], v[142:145], v[166:169], v[122:125]
	v_mfma_f32_16x16x32_bf16 v[118:121], v[134:137], v[174:177], v[118:121]
	v_mfma_f32_16x16x32_bf16 v[114:117], v[142:145], v[174:177], v[114:117]
	v_mfma_f32_16x16x32_bf16 v[94:97], v[134:137], v[182:185], v[94:97]
	v_mfma_f32_16x16x32_bf16 v[90:93], v[142:145], v[182:185], v[90:93]
	v_mfma_f32_16x16x32_bf16 v[86:89], v[134:137], v[190:193], v[86:89]
	v_mfma_f32_16x16x32_bf16 v[82:85], v[142:145], v[190:193], v[82:85]
	s_setprio 0
	s_setprio 1
	v_mfma_f32_16x16x32_bf16 v[110:113], v[146:149], v[162:165], v[110:113]
	v_mfma_f32_16x16x32_bf16 v[106:109], v[154:157], v[162:165], v[106:109]
	v_mfma_f32_16x16x32_bf16 v[102:105], v[146:149], v[170:173], v[102:105]
	v_mfma_f32_16x16x32_bf16 v[98:101], v[154:157], v[170:173], v[98:101]
	v_mfma_f32_16x16x32_bf16 v[78:81], v[146:149], v[178:181], v[78:81]
	v_mfma_f32_16x16x32_bf16 v[74:77], v[154:157], v[178:181], v[74:77]
	v_mfma_f32_16x16x32_bf16 v[70:73], v[146:149], v[186:189], v[70:73]
	v_mfma_f32_16x16x32_bf16 v[66:69], v[154:157], v[186:189], v[66:69]
	v_mfma_f32_16x16x32_bf16 v[110:113], v[150:153], v[166:169], v[110:113]
	v_mfma_f32_16x16x32_bf16 v[106:109], v[158:161], v[166:169], v[106:109]
	v_mfma_f32_16x16x32_bf16 v[102:105], v[150:153], v[174:177], v[102:105]
	v_mfma_f32_16x16x32_bf16 v[98:101], v[158:161], v[174:177], v[98:101]
	v_mfma_f32_16x16x32_bf16 v[78:81], v[150:153], v[182:185], v[78:81]
	v_mfma_f32_16x16x32_bf16 v[74:77], v[158:161], v[182:185], v[74:77]
	v_mfma_f32_16x16x32_bf16 v[70:73], v[150:153], v[190:193], v[70:73]
	v_mfma_f32_16x16x32_bf16 v[66:69], v[158:161], v[190:193], v[66:69]
	s_setprio 0
	s_barrier
; #define PG8_STAGE(bufoff, gbase, voff) do { _Pragma("unroll") for (int _i = 0; _i < 2; ++_i) \
;         __builtin_amdgcn_global_load_lds((const unsigned*)((const char*)(gbase) + (voff)[_i]), (PG8_LAS unsigned*)(lds + (bufoff) + ldsw + _i * 8192), 16, 0, 0); } while (0)
; #define PG8_LDA(dst, b, h) do { _Pragma("unroll") for (int m = 0; m < 4; ++m) _Pragma("unroll") for (int k = 0; k < 2; ++k) dst[m][k] = *(const PG8_LAS bf16x8*)(lds + PG8_SA(b, h) + aoff + m * 2048 + k * 1024); } while (0)
; #define PG8_MMA(ai, bj, At, Bt) do { __builtin_amdgcn_s_setprio(1); _Pragma("unroll") for (int m = 0; m < 4; ++m) _Pragma("unroll") for (int n = 0; n < 2; ++n) _Pragma("unroll") for (int k = 0; k < 2; ++k) \
;         acc[ai][bj][m][n] = __builtin_amdgcn_mfma_f32_16x16x32_bf16(Bt[n][k], At[m][k], acc[ai][bj][m][n], 0, 0, 0); __builtin_amdgcn_s_setprio(0); } while (0)
; #define PG8_WAIT_V(n) asm volatile("s_waitcnt vmcnt(" #n ")" ::: "memory")
; #define PG8_WAIT_L(n) asm volatile("s_waitcnt lgkmcnt(" #n ")" ::: "memory")
; #define PG8_BAR __builtin_amdgcn_s_barrier()
; #define PG8_SCHED __builtin_amdgcn_sched_barrier(0)
; template <class Epi, class Sched, bool ALIGN_EPI = false, bool SP2 = false>
; __device__ __forceinline__ void gemm_phase(PG8_LAS unsigned char* lds, const Gemm g, const Sched& S, const Epi& E, const int wave_id) {
;     ...
;         for (int t = 0; t < nt; t += 2) {
;     ...
;             PG8_LDA(At, 1, 1); PG8_STAGE(PG8_SB(1, 0), b3, voffB); PG8_STAGE(PG8_SB(1, 1), b3 + hstep, voffB); PG8_STAGE(PG8_SA(1, 0), a3, voffA);
;             PG8_WAIT_V(8); PG8_WAIT_L(0); PG8_BAR; PG8_MMA(1, 0, At, B0); PG8_MMA(1, 1, At, B1); PG8_BAR; PG8_SCHED;
	ds_read_b128 v[162:165], v232 offset:49152
	ds_read_b128 v[166:169], v232 offset:50176
	ds_read_b128 v[170:173], v232 offset:51200
	ds_read_b128 v[174:177], v232 offset:52224
	ds_read_b128 v[178:181], v232 offset:53248
	ds_read_b128 v[182:185], v232 offset:54272
	ds_read_b128 v[186:189], v232 offset:55296
	ds_read_b128 v[190:193], v232 offset:56320
	s_add_i32 s14, s16, s21
	v_lshl_add_u64 v[194:195], v[228:229], 0, s[64:65]
	s_mov_b32 m0, s14
	s_nop 0
	global_load_lds_dwordx4 v[194:195], off
	s_add_i32 m0, s14, 0x2000
	s_add_u32 s12, s12, 0x40080
	v_lshl_add_u64 v[194:195], v[226:227], 0, s[64:65]
	s_addc_u32 s13, s13, 0
	s_add_i32 s14, s17, s21
	global_load_lds_dwordx4 v[194:195], off
	v_lshl_add_u64 v[194:195], s[12:13], 0, v[212:213]
	s_mov_b32 m0, s14
	s_nop 0
	global_load_lds_dwordx4 v[194:195], off
	v_lshl_add_u64 v[194:195], s[12:13], 0, v[216:217]
	s_add_i32 m0, s14, 0x2000
	s_nop 0
	global_load_lds_dwordx4 v[194:195], off
	v_lshl_add_u64 v[194:195], v[222:223], 0, s[64:65]
	s_mov_b32 m0, s30
	s_nop 0
	global_load_lds_dwordx4 v[194:195], off
	v_lshl_add_u64 v[194:195], v[224:225], 0, s[64:65]
	s_mov_b32 m0, s31
	s_nop 0
	global_load_lds_dwordx4 v[194:195], off
	s_waitcnt vmcnt(8)
	s_waitcnt lgkmcnt(0)
	s_barrier
	s_setprio 1
	s_waitcnt lgkmcnt(0)
	v_mfma_f32_16x16x32_bf16 v[62:65], v[130:133], v[162:165], v[62:65]
	v_mfma_f32_16x16x32_bf16 v[58:61], v[138:141], v[162:165], v[58:61]
	v_mfma_f32_16x16x32_bf16 v[54:57], v[130:133], v[170:173], v[54:57]
	v_mfma_f32_16x16x32_bf16 v[50:53], v[138:141], v[170:173], v[50:53]
	v_mfma_f32_16x16x32_bf16 v[30:33], v[130:133], v[178:181], v[30:33]
	v_mfma_f32_16x16x32_bf16 v[26:29], v[138:141], v[178:181], v[26:29]
	v_mfma_f32_16x16x32_bf16 v[22:25], v[130:133], v[186:189], v[22:25]
	v_mfma_f32_16x16x32_bf16 v[18:21], v[138:141], v[186:189], v[18:21]
	v_mfma_f32_16x16x32_bf16 v[62:65], v[134:137], v[166:169], v[62:65]
	v_mfma_f32_16x16x32_bf16 v[58:61], v[142:145], v[166:169], v[58:61]
	v_mfma_f32_16x16x32_bf16 v[54:57], v[134:137], v[174:177], v[54:57]
	v_mfma_f32_16x16x32_bf16 v[50:53], v[142:145], v[174:177], v[50:53]
	v_mfma_f32_16x16x32_bf16 v[30:33], v[134:137], v[182:185], v[30:33]
	v_mfma_f32_16x16x32_bf16 v[26:29], v[142:145], v[182:185], v[26:29]
	v_mfma_f32_16x16x32_bf16 v[22:25], v[134:137], v[190:193], v[22:25]
	v_mfma_f32_16x16x32_bf16 v[18:21], v[142:145], v[190:193], v[18:21]
	s_setprio 0
	s_setprio 1
	v_mfma_f32_16x16x32_bf16 v[46:49], v[146:149], v[162:165], v[46:49]
	v_mfma_f32_16x16x32_bf16 v[42:45], v[154:157], v[162:165], v[42:45]
	v_mfma_f32_16x16x32_bf16 v[38:41], v[146:149], v[170:173], v[38:41]
	v_mfma_f32_16x16x32_bf16 v[34:37], v[154:157], v[170:173], v[34:37]
	v_mfma_f32_16x16x32_bf16 v[14:17], v[146:149], v[178:181], v[14:17]
	v_mfma_f32_16x16x32_bf16 v[10:13], v[154:157], v[178:181], v[10:13]
	v_mfma_f32_16x16x32_bf16 v[6:9], v[146:149], v[186:189], v[6:9]
	v_mfma_f32_16x16x32_bf16 v[2:5], v[154:157], v[186:189], v[2:5]
	v_mfma_f32_16x16x32_bf16 v[46:49], v[150:153], v[166:169], v[46:49]
	v_mfma_f32_16x16x32_bf16 v[42:45], v[158:161], v[166:169], v[42:45]
	v_mfma_f32_16x16x32_bf16 v[38:41], v[150:153], v[174:177], v[38:41]
	v_mfma_f32_16x16x32_bf16 v[34:37], v[158:161], v[174:177], v[34:37]
	v_mfma_f32_16x16x32_bf16 v[14:17], v[150:153], v[182:185], v[14:17]
	v_mfma_f32_16x16x32_bf16 v[10:13], v[158:161], v[182:185], v[10:13]
	v_mfma_f32_16x16x32_bf16 v[6:9], v[150:153], v[190:193], v[6:9]
	v_mfma_f32_16x16x32_bf16 v[2:5], v[158:161], v[190:193], v[2:5]
	s_setprio 0
	s_barrier
	s_add_u32 s10, s10, 0x100
	s_addc_u32 s11, s11, 0
	s_cmp_gt_u32 s38, 13
	v_readlane_b32 s40, v254, 55
	s_cbranch_scc1 .LBB0_1894

; #define PG8_STAGE(bufoff, gbase, voff) do { _Pragma("unroll") for (int _i = 0; _i < 2; ++_i) \
;         __builtin_amdgcn_global_load_lds((const unsigned*)((const char*)(gbase) + (voff)[_i]), (PG8_LAS unsigned*)(lds + (bufoff) + ldsw + _i * 8192), 16, 0, 0); } while (0)
; #define PG8_LDA(dst, b, h) do { _Pragma("unroll") for (int m = 0; m < 4; ++m) _Pragma("unroll") for (int k = 0; k < 2; ++k) dst[m][k] = *(const PG8_LAS bf16x8*)(lds + PG8_SA(b, h) + aoff + m * 2048 + k * 1024); } while (0)
; #define PG8_LDB(dst, b, h) do { _Pragma("unroll") for (int n = 0; n < 2; ++n) _Pragma("unroll") for (int k = 0; k < 2; ++k) dst[n][k] = *(const PG8_LAS bf16x8*)(lds + PG8_SB(b, h) + boff + n * 2048 + k * 1024); } while (0)
; #define PG8_MMA(ai, bj, At, Bt) do { __builtin_amdgcn_s_setprio(1); _Pragma("unroll") for (int m = 0; m < 4; ++m) _Pragma("unroll") for (int n = 0; n < 2; ++n) _Pragma("unroll") for (int k = 0; k < 2; ++k) \
;         acc[ai][bj][m][n] = __builtin_amdgcn_mfma_f32_16x16x32_bf16(Bt[n][k], At[m][k], acc[ai][bj][m][n], 0, 0, 0); __builtin_amdgcn_s_setprio(0); } while (0)
; #define PG8_WAIT_V(n) asm volatile("s_waitcnt vmcnt(" #n ")" ::: "memory")
; #define PG8_WAIT_VN(n) asm volatile("s_waitcnt vmcnt(%0)" :: "n"(n) : "memory")
; template <class Epi, class Sched, bool ALIGN_EPI = false, bool SP2 = false>
; __device__ __forceinline__ void gemm_phase(PG8_LAS unsigned char* lds, const Gemm g, const Sched& S, const Epi& E, const int wave_id) {
;     ...
;             const bool last = (t == nt - 2);
;             const char* a1 = cA + (size_t)(t + 1) * kstep;
;             const char* a2 = last ? nA : cA + (size_t)(t + 2) * kstep; const char* b2 = last ? nB : cB + (size_t)(t + 2) * kstep;
;             const char* a3 = a2 + kstep; const char* b3 = b2 + kstep;
;     ...
;             PG8_LDB(B0, 0, 0); PG8_LDB(B1, 0, 1); PG8_SCHED; PG8_LDA(At, 0, 0); PG8_STAGE(PG8_SA(1, 1), a1 + hstep, voffA);
;             PG8_WAIT_VN(8 + Epi::NS); if (strict) PG8_WAIT_V(8); PG8_WAIT_L(0); PG8_BAR; PG8_MMA(0, 0, At, B0); PG8_MMA(0, 1, At, B1); PG8_BAR; PG8_SCHED;
;             PG8_LDA(At, 0, 1); PG8_STAGE(PG8_SB(0, 0), b2, voffB); PG8_STAGE(PG8_SB(0, 1), b2 + hstep, voffB); PG8_STAGE(PG8_SA(0, 0), a2, voffA);
;             PG8_WAIT_VN(8 + Epi::NS); if (strict) PG8_WAIT_V(8); PG8_WAIT_L(0); PG8_BAR; PG8_MMA(1, 0, At, B0); PG8_MMA(1, 1, At, B1); PG8_BAR; PG8_SCHED;
.LBB0_1892:
	s_add_u32 s12, s36, s10
	s_addc_u32 s13, s37, s11
	s_add_u32 s12, s12, 0x8200100
	s_addc_u32 s13, s13, 0
	s_add_u32 s39, s34, s10
	s_addc_u32 s40, s35, s11
	s_waitcnt lgkmcnt(0)
	s_cmpk_eq_i32 s10, 0x700
	s_cselect_b32 s15, s9, s13
	s_cselect_b32 s14, s8, s12
	s_cselect_b32 s13, s7, s40
	s_cselect_b32 s12, s6, s39
	s_barrier
	s_setprio 1
	s_waitcnt lgkmcnt(0)
	v_mfma_f32_16x16x32_bf16 v[126:129], v[146:149], v[186:189], v[126:129]
	v_mfma_f32_16x16x32_bf16 v[122:125], v[154:157], v[186:189], v[122:125]
	v_mfma_f32_16x16x32_bf16 v[118:121], v[146:149], v[178:181], v[118:121]
	v_mfma_f32_16x16x32_bf16 v[114:117], v[154:157], v[178:181], v[114:117]
	v_mfma_f32_16x16x32_bf16 v[94:97], v[146:149], v[170:173], v[94:97]
	v_mfma_f32_16x16x32_bf16 v[90:93], v[154:157], v[170:173], v[90:93]
	v_mfma_f32_16x16x32_bf16 v[86:89], v[146:149], v[162:165], v[86:89]
	v_mfma_f32_16x16x32_bf16 v[82:85], v[154:157], v[162:165], v[82:85]
	v_mfma_f32_16x16x32_bf16 v[126:129], v[150:153], v[190:193], v[126:129]
	v_mfma_f32_16x16x32_bf16 v[122:125], v[158:161], v[190:193], v[122:125]
	v_mfma_f32_16x16x32_bf16 v[118:121], v[150:153], v[182:185], v[118:121]
	v_mfma_f32_16x16x32_bf16 v[114:117], v[158:161], v[182:185], v[114:117]
	v_mfma_f32_16x16x32_bf16 v[94:97], v[150:153], v[174:177], v[94:97]
	v_mfma_f32_16x16x32_bf16 v[90:93], v[158:161], v[174:177], v[90:93]
	v_mfma_f32_16x16x32_bf16 v[86:89], v[150:153], v[166:169], v[86:89]
	v_mfma_f32_16x16x32_bf16 v[82:85], v[158:161], v[166:169], v[82:85]
	s_setprio 0
	s_setprio 1
	v_mfma_f32_16x16x32_bf16 v[110:113], v[130:133], v[186:189], v[110:113]
	v_mfma_f32_16x16x32_bf16 v[106:109], v[138:141], v[186:189], v[106:109]
	v_mfma_f32_16x16x32_bf16 v[102:105], v[130:133], v[178:181], v[102:105]
	v_mfma_f32_16x16x32_bf16 v[98:101], v[138:141], v[178:181], v[98:101]
	v_mfma_f32_16x16x32_bf16 v[78:81], v[130:133], v[170:173], v[78:81]
	v_mfma_f32_16x16x32_bf16 v[74:77], v[138:141], v[170:173], v[74:77]
	v_mfma_f32_16x16x32_bf16 v[70:73], v[130:133], v[162:165], v[70:73]
	v_mfma_f32_16x16x32_bf16 v[66:69], v[138:141], v[162:165], v[66:69]
	v_mfma_f32_16x16x32_bf16 v[110:113], v[134:137], v[190:193], v[110:113]
	v_mfma_f32_16x16x32_bf16 v[106:109], v[142:145], v[190:193], v[106:109]
	v_mfma_f32_16x16x32_bf16 v[102:105], v[134:137], v[182:185], v[102:105]
	v_mfma_f32_16x16x32_bf16 v[98:101], v[142:145], v[182:185], v[98:101]
	v_mfma_f32_16x16x32_bf16 v[78:81], v[134:137], v[174:177], v[78:81]
	v_mfma_f32_16x16x32_bf16 v[74:77], v[142:145], v[174:177], v[74:77]
	v_mfma_f32_16x16x32_bf16 v[70:73], v[134:137], v[166:169], v[70:73]
	v_mfma_f32_16x16x32_bf16 v[66:69], v[142:145], v[166:169], v[66:69]
	s_setprio 0
	s_barrier
	ds_read_b128 v[186:189], v232 offset:16384
	ds_read_b128 v[190:193], v232 offset:17408
	ds_read_b128 v[178:181], v232 offset:18432
	ds_read_b128 v[182:185], v232 offset:19456
	ds_read_b128 v[170:173], v232 offset:20480
	ds_read_b128 v[174:177], v232 offset:21504
	ds_read_b128 v[162:165], v232 offset:22528
	ds_read_b128 v[166:169], v232 offset:23552
	s_mov_b32 m0, s22
	v_lshl_add_u64 v[228:229], s[12:13], 0, v[212:213]
	s_add_u32 s40, s12, 0x40000
	global_load_lds_dwordx4 v[228:229], off
	v_lshl_add_u64 v[226:227], s[12:13], 0, v[216:217]
	s_mov_b32 m0, s23
	s_addc_u32 s41, s13, 0
	global_load_lds_dwordx4 v[226:227], off
	v_lshl_add_u64 v[194:195], s[40:41], 0, v[212:213]
	s_mov_b32 m0, s24
	v_lshl_add_u64 v[222:223], s[14:15], 0, v[210:211]
	global_load_lds_dwordx4 v[194:195], off
	v_lshl_add_u64 v[194:195], s[40:41], 0, v[216:217]
	s_mov_b32 m0, s25
	v_lshl_add_u64 v[224:225], s[14:15], 0, v[214:215]
	global_load_lds_dwordx4 v[194:195], off
	s_mov_b32 m0, s5
	s_andn2_b64 vcc, exec, s[16:17]
	global_load_lds_dwordx4 v[222:223], off
	s_mov_b32 m0, s26
	s_nop 0
	global_load_lds_dwordx4 v[224:225], off
	s_waitcnt vmcnt(16)
	s_cbranch_vccnz .LBB0_1889
	s_waitcnt vmcnt(8)
	s_branch .LBB0_1889

; #define PG8_STAGE(bufoff, gbase, voff) do { _Pragma("unroll") for (int _i = 0; _i < 2; ++_i) \
;         __builtin_amdgcn_global_load_lds((const unsigned*)((const char*)(gbase) + (voff)[_i]), (PG8_LAS unsigned*)(lds + (bufoff) + ldsw + _i * 8192), 16, 0, 0); } while (0)
; #define PG8_LDA(dst, b, h) do { _Pragma("unroll") for (int m = 0; m < 4; ++m) _Pragma("unroll") for (int k = 0; k < 2; ++k) dst[m][k] = *(const PG8_LAS bf16x8*)(lds + PG8_SA(b, h) + aoff + m * 2048 + k * 1024); } while (0)
; #define PG8_LDB(dst, b, h) do { _Pragma("unroll") for (int n = 0; n < 2; ++n) _Pragma("unroll") for (int k = 0; k < 2; ++k) dst[n][k] = *(const PG8_LAS bf16x8*)(lds + PG8_SB(b, h) + boff + n * 2048 + k * 1024); } while (0)
; #define PG8_MMA(ai, bj, At, Bt) do { __builtin_amdgcn_s_setprio(1); _Pragma("unroll") for (int m = 0; m < 4; ++m) _Pragma("unroll") for (int n = 0; n < 2; ++n) _Pragma("unroll") for (int k = 0; k < 2; ++k) \
;         acc[ai][bj][m][n] = __builtin_amdgcn_mfma_f32_16x16x32_bf16(Bt[n][k], At[m][k], acc[ai][bj][m][n], 0, 0, 0); __builtin_amdgcn_s_setprio(0); } while (0)
; #define PG8_WAIT_V(n) asm volatile("s_waitcnt vmcnt(" #n ")" ::: "memory")
; #define PG8_WAIT_VN(n) asm volatile("s_waitcnt vmcnt(%0)" :: "n"(n) : "memory")
; #define PG8_WAIT_L(n) asm volatile("s_waitcnt lgkmcnt(" #n ")" ::: "memory")
; #define PG8_BAR __builtin_amdgcn_s_barrier()
; #define PG8_SCHED __builtin_amdgcn_sched_barrier(0)
; template <class Epi, class Sched, bool ALIGN_EPI = false, bool SP2 = false>
; __device__ __forceinline__ void gemm_phase(PG8_LAS unsigned char* lds, const Gemm g, const Sched& S, const Epi& E, const int wave_id) {
;     ...
;             PG8_WAIT_VN(8 + Epi::NS); if (strict) PG8_WAIT_V(8); PG8_WAIT_L(0); PG8_BAR; PG8_MMA(1, 0, At, B0); PG8_MMA(1, 1, At, B1); PG8_BAR; PG8_SCHED;
;             PG8_LDB(B0, 1, 0); PG8_LDB(B1, 1, 1); PG8_SCHED; PG8_LDA(At, 1, 0); PG8_STAGE(PG8_SA(0, 1), a2 + hstep, voffA);
;             PG8_WAIT_V(8); PG8_WAIT_L(0); PG8_BAR; PG8_MMA(0, 0, At, B0); PG8_MMA(0, 1, At, B1); PG8_BAR; PG8_SCHED;
.LBB0_1952:
	s_waitcnt lgkmcnt(0)
	s_barrier
	s_setprio 1
	s_waitcnt lgkmcnt(0)
	v_mfma_f32_16x16x32_bf16 v[62:65], v[146:149], v[186:189], v[62:65]
	v_mfma_f32_16x16x32_bf16 v[58:61], v[154:157], v[186:189], v[58:61]
	v_mfma_f32_16x16x32_bf16 v[54:57], v[146:149], v[178:181], v[54:57]
	v_mfma_f32_16x16x32_bf16 v[50:53], v[154:157], v[178:181], v[50:53]
	v_mfma_f32_16x16x32_bf16 v[30:33], v[146:149], v[170:173], v[30:33]
	v_mfma_f32_16x16x32_bf16 v[26:29], v[154:157], v[170:173], v[26:29]
	v_mfma_f32_16x16x32_bf16 v[22:25], v[146:149], v[162:165], v[22:25]
	v_mfma_f32_16x16x32_bf16 v[18:21], v[154:157], v[162:165], v[18:21]
	v_mfma_f32_16x16x32_bf16 v[62:65], v[150:153], v[190:193], v[62:65]
	v_mfma_f32_16x16x32_bf16 v[58:61], v[158:161], v[190:193], v[58:61]
	v_mfma_f32_16x16x32_bf16 v[54:57], v[150:153], v[182:185], v[54:57]
	v_mfma_f32_16x16x32_bf16 v[50:53], v[158:161], v[182:185], v[50:53]
	v_mfma_f32_16x16x32_bf16 v[30:33], v[150:153], v[174:177], v[30:33]
	v_mfma_f32_16x16x32_bf16 v[26:29], v[158:161], v[174:177], v[26:29]
	v_mfma_f32_16x16x32_bf16 v[22:25], v[150:153], v[166:169], v[22:25]
	v_mfma_f32_16x16x32_bf16 v[18:21], v[158:161], v[166:169], v[18:21]
	s_setprio 0
	s_setprio 1
	v_mfma_f32_16x16x32_bf16 v[46:49], v[130:133], v[186:189], v[46:49]
	v_mfma_f32_16x16x32_bf16 v[42:45], v[138:141], v[186:189], v[42:45]
	v_mfma_f32_16x16x32_bf16 v[38:41], v[130:133], v[178:181], v[38:41]
	v_mfma_f32_16x16x32_bf16 v[34:37], v[138:141], v[178:181], v[34:37]
	v_mfma_f32_16x16x32_bf16 v[14:17], v[130:133], v[170:173], v[14:17]
	v_mfma_f32_16x16x32_bf16 v[10:13], v[138:141], v[170:173], v[10:13]
	v_mfma_f32_16x16x32_bf16 v[6:9], v[130:133], v[162:165], v[6:9]
	v_mfma_f32_16x16x32_bf16 v[2:5], v[138:141], v[162:165], v[2:5]
	v_mfma_f32_16x16x32_bf16 v[46:49], v[134:137], v[190:193], v[46:49]
	v_mfma_f32_16x16x32_bf16 v[42:45], v[142:145], v[190:193], v[42:45]
	v_mfma_f32_16x16x32_bf16 v[38:41], v[134:137], v[182:185], v[38:41]
	v_mfma_f32_16x16x32_bf16 v[34:37], v[142:145], v[182:185], v[34:37]
	v_mfma_f32_16x16x32_bf16 v[14:17], v[134:137], v[174:177], v[14:17]
	v_mfma_f32_16x16x32_bf16 v[10:13], v[142:145], v[174:177], v[10:13]
	v_mfma_f32_16x16x32_bf16 v[6:9], v[134:137], v[166:169], v[6:9]
	v_mfma_f32_16x16x32_bf16 v[2:5], v[142:145], v[166:169], v[2:5]
	s_setprio 0
	s_barrier
	ds_read_b128 v[162:165], v247 offset:32768
	ds_read_b128 v[166:169], v247 offset:33792
	ds_read_b128 v[170:173], v247 offset:34816
	ds_read_b128 v[174:177], v247 offset:35840
	ds_read_b128 v[178:181], v247 offset:36864
	ds_read_b128 v[182:185], v247 offset:37888
	ds_read_b128 v[186:189], v247 offset:38912
	ds_read_b128 v[190:193], v247 offset:39936
	s_add_i32 s28, 0, 0x18000
	s_add_i32 s29, 0, 0x1c000
	v_add_u32_e32 v142, s28, v246
	v_add_u32_e32 v158, s29, v246
	ds_read_b128 v[130:133], v142
	ds_read_b128 v[134:137], v142 offset:1024
	ds_read_b128 v[138:141], v142 offset:2048
	ds_read_b128 v[142:145], v142 offset:3072
	ds_read_b128 v[146:149], v158
	ds_read_b128 v[150:153], v158 offset:1024
	ds_read_b128 v[154:157], v158 offset:2048
	ds_read_b128 v[158:161], v158 offset:3072
	s_add_u32 s26, s26, 0x40000
	s_addc_u32 s27, s27, 0
	s_mov_b32 m0, s52
	v_lshl_add_u64 v[194:195], s[26:27], 0, v[216:217]
	global_load_lds_dwordx4 v[194:195], off
	v_lshl_add_u64 v[194:195], s[26:27], 0, v[212:213]
	s_mov_b32 m0, s54
	s_nop 0
	global_load_lds_dwordx4 v[194:195], off
	s_waitcnt vmcnt(18)
	s_cmp_eq_u32 s100, 0
	s_cbranch_scc1 .Lthird_wait_relaxed_2
	s_waitcnt vmcnt(8)
; #define PG8_STAGE(bufoff, gbase, voff) do { _Pragma("unroll") for (int _i = 0; _i < 2; ++_i) \
;         __builtin_amdgcn_global_load_lds((const unsigned*)((const char*)(gbase) + (voff)[_i]), (PG8_LAS unsigned*)(lds + (bufoff) + ldsw + _i * 8192), 16, 0, 0); } while (0)
; #define PG8_LDA(dst, b, h) do { _Pragma("unroll") for (int m = 0; m < 4; ++m) _Pragma("unroll") for (int k = 0; k < 2; ++k) dst[m][k] = *(const PG8_LAS bf16x8*)(lds + PG8_SA(b, h) + aoff + m * 2048 + k * 1024); } while (0)
; #define PG8_MMA(ai, bj, At, Bt) do { __builtin_amdgcn_s_setprio(1); _Pragma("unroll") for (int m = 0; m < 4; ++m) _Pragma("unroll") for (int n = 0; n < 2; ++n) _Pragma("unroll") for (int k = 0; k < 2; ++k) \
;         acc[ai][bj][m][n] = __builtin_amdgcn_mfma_f32_16x16x32_bf16(Bt[n][k], At[m][k], acc[ai][bj][m][n], 0, 0, 0); __builtin_amdgcn_s_setprio(0); } while (0)
; #define PG8_WAIT_V(n) asm volatile("s_waitcnt vmcnt(" #n ")" ::: "memory")
; #define PG8_WAIT_L(n) asm volatile("s_waitcnt lgkmcnt(" #n ")" ::: "memory")
; #define PG8_BAR __builtin_amdgcn_s_barrier()
; #define PG8_SCHED __builtin_amdgcn_sched_barrier(0)
; template <class Epi, class Sched, bool ALIGN_EPI = false, bool SP2 = false>
; __device__ __forceinline__ void gemm_phase(PG8_LAS unsigned char* lds, const Gemm g, const Sched& S, const Epi& E, const int wave_id) {
;     ...
;             PG8_WAIT_V(8); PG8_WAIT_L(0); PG8_BAR; PG8_MMA(0, 0, At, B0); PG8_MMA(0, 1, At, B1); PG8_BAR; PG8_SCHED;
;             PG8_LDA(At, 1, 1); PG8_STAGE(PG8_SB(1, 0), b3, voffB); PG8_STAGE(PG8_SB(1, 1), b3 + hstep, voffB); PG8_STAGE(PG8_SA(1, 0), a3, voffA);
;             PG8_WAIT_V(8); PG8_WAIT_L(0); PG8_BAR; PG8_MMA(1, 0, At, B0); PG8_MMA(1, 1, At, B1); PG8_BAR; PG8_SCHED;
.Lthird_wait_relaxed_2:
	s_waitcnt lgkmcnt(0)
	s_barrier
	s_setprio 1
	s_waitcnt lgkmcnt(0)
	v_mfma_f32_16x16x32_bf16 v[126:129], v[130:133], v[162:165], v[126:129]
	v_mfma_f32_16x16x32_bf16 v[122:125], v[138:141], v[162:165], v[122:125]
	v_mfma_f32_16x16x32_bf16 v[118:121], v[130:133], v[170:173], v[118:121]
	v_mfma_f32_16x16x32_bf16 v[114:117], v[138:141], v[170:173], v[114:117]
	v_mfma_f32_16x16x32_bf16 v[94:97], v[130:133], v[178:181], v[94:97]
	v_mfma_f32_16x16x32_bf16 v[90:93], v[138:141], v[178:181], v[90:93]
	v_mfma_f32_16x16x32_bf16 v[86:89], v[130:133], v[186:189], v[86:89]
	v_mfma_f32_16x16x32_bf16 v[82:85], v[138:141], v[186:189], v[82:85]
	v_mfma_f32_16x16x32_bf16 v[126:129], v[134:137], v[166:169], v[126:129]
	v_mfma_f32_16x16x32_bf16 v[122:125], v[142:145], v[166:169], v[122:125]
	v_mfma_f32_16x16x32_bf16 v[118:121], v[134:137], v[174:177], v[118:121]
	v_mfma_f32_16x16x32_bf16 v[114:117], v[142:145], v[174:177], v[114:117]
	v_mfma_f32_16x16x32_bf16 v[94:97], v[134:137], v[182:185], v[94:97]
	v_mfma_f32_16x16x32_bf16 v[90:93], v[142:145], v[182:185], v[90:93]
	v_mfma_f32_16x16x32_bf16 v[86:89], v[134:137], v[190:193], v[86:89]
	v_mfma_f32_16x16x32_bf16 v[82:85], v[142:145], v[190:193], v[82:85]
	s_setprio 0
	s_setprio 1
	v_mfma_f32_16x16x32_bf16 v[110:113], v[146:149], v[162:165], v[110:113]
	v_mfma_f32_16x16x32_bf16 v[106:109], v[154:157], v[162:165], v[106:109]
	v_mfma_f32_16x16x32_bf16 v[102:105], v[146:149], v[170:173], v[102:105]
	v_mfma_f32_16x16x32_bf16 v[98:101], v[154:157], v[170:173], v[98:101]
	v_mfma_f32_16x16x32_bf16 v[78:81], v[146:149], v[178:181], v[78:81]
	v_mfma_f32_16x16x32_bf16 v[74:77], v[154:157], v[178:181], v[74:77]
	v_mfma_f32_16x16x32_bf16 v[70:73], v[146:149], v[186:189], v[70:73]
	v_mfma_f32_16x16x32_bf16 v[66:69], v[154:157], v[186:189], v[66:69]
	v_mfma_f32_16x16x32_bf16 v[110:113], v[150:153], v[166:169], v[110:113]
	v_mfma_f32_16x16x32_bf16 v[106:109], v[158:161], v[166:169], v[106:109]
	v_mfma_f32_16x16x32_bf16 v[102:105], v[150:153], v[174:177], v[102:105]
	v_mfma_f32_16x16x32_bf16 v[98:101], v[158:161], v[174:177], v[98:101]
	v_mfma_f32_16x16x32_bf16 v[78:81], v[150:153], v[182:185], v[78:81]
	v_mfma_f32_16x16x32_bf16 v[74:77], v[158:161], v[182:185], v[74:77]
	v_mfma_f32_16x16x32_bf16 v[70:73], v[150:153], v[190:193], v[70:73]
	v_mfma_f32_16x16x32_bf16 v[66:69], v[158:161], v[190:193], v[66:69]
	s_setprio 0
	s_barrier
	ds_read_b128 v[162:165], v247 offset:49152
	ds_read_b128 v[166:169], v247 offset:50176
	ds_read_b128 v[170:173], v247 offset:51200
	ds_read_b128 v[174:177], v247 offset:52224
	ds_read_b128 v[178:181], v247 offset:53248
	ds_read_b128 v[182:185], v247 offset:54272
	ds_read_b128 v[186:189], v247 offset:55296
	ds_read_b128 v[190:193], v247 offset:56320
	s_add_i32 s26, s28, s39
	v_lshl_add_u64 v[194:195], v[232:233], 0, s[64:65]
	s_mov_b32 m0, s26
	s_nop 0
	global_load_lds_dwordx4 v[194:195], off
	s_add_i32 m0, s26, 0x2000
	s_add_u32 s24, s24, 0x40080
	v_lshl_add_u64 v[194:195], v[230:231], 0, s[64:65]
	s_addc_u32 s25, s25, 0
	s_add_i32 s26, s29, s39
	global_load_lds_dwordx4 v[194:195], off
	v_lshl_add_u64 v[194:195], s[24:25], 0, v[214:215]
	s_mov_b32 m0, s26
	s_nop 0
	global_load_lds_dwordx4 v[194:195], off
	v_lshl_add_u64 v[194:195], s[24:25], 0, v[210:211]
	s_add_i32 m0, s26, 0x2000
	s_nop 0
	global_load_lds_dwordx4 v[194:195], off
	v_lshl_add_u64 v[194:195], v[226:227], 0, s[64:65]
	s_mov_b32 m0, s57
	s_nop 0
	global_load_lds_dwordx4 v[194:195], off
	v_lshl_add_u64 v[194:195], v[228:229], 0, s[64:65]
	s_mov_b32 m0, s62
	s_nop 0
	global_load_lds_dwordx4 v[194:195], off
	s_waitcnt vmcnt(8)
	s_waitcnt lgkmcnt(0)
	s_barrier
	s_setprio 1
	s_waitcnt lgkmcnt(0)
	v_mfma_f32_16x16x32_bf16 v[62:65], v[130:133], v[162:165], v[62:65]
	v_mfma_f32_16x16x32_bf16 v[58:61], v[138:141], v[162:165], v[58:61]
	v_mfma_f32_16x16x32_bf16 v[54:57], v[130:133], v[170:173], v[54:57]
	v_mfma_f32_16x16x32_bf16 v[50:53], v[138:141], v[170:173], v[50:53]
	v_mfma_f32_16x16x32_bf16 v[30:33], v[130:133], v[178:181], v[30:33]
	v_mfma_f32_16x16x32_bf16 v[26:29], v[138:141], v[178:181], v[26:29]
	v_mfma_f32_16x16x32_bf16 v[22:25], v[130:133], v[186:189], v[22:25]
	v_mfma_f32_16x16x32_bf16 v[18:21], v[138:141], v[186:189], v[18:21]
	v_mfma_f32_16x16x32_bf16 v[62:65], v[134:137], v[166:169], v[62:65]
	v_mfma_f32_16x16x32_bf16 v[58:61], v[142:145], v[166:169], v[58:61]
	v_mfma_f32_16x16x32_bf16 v[54:57], v[134:137], v[174:177], v[54:57]
	v_mfma_f32_16x16x32_bf16 v[50:53], v[142:145], v[174:177], v[50:53]
	v_mfma_f32_16x16x32_bf16 v[30:33], v[134:137], v[182:185], v[30:33]
	v_mfma_f32_16x16x32_bf16 v[26:29], v[142:145], v[182:185], v[26:29]
	v_mfma_f32_16x16x32_bf16 v[22:25], v[134:137], v[190:193], v[22:25]
	v_mfma_f32_16x16x32_bf16 v[18:21], v[142:145], v[190:193], v[18:21]
	s_setprio 0
	s_setprio 1
	v_mfma_f32_16x16x32_bf16 v[46:49], v[146:149], v[162:165], v[46:49]
	v_mfma_f32_16x16x32_bf16 v[42:45], v[154:157], v[162:165], v[42:45]
	v_mfma_f32_16x16x32_bf16 v[38:41], v[146:149], v[170:173], v[38:41]
	v_mfma_f32_16x16x32_bf16 v[34:37], v[154:157], v[170:173], v[34:37]
	v_mfma_f32_16x16x32_bf16 v[14:17], v[146:149], v[178:181], v[14:17]
	v_mfma_f32_16x16x32_bf16 v[10:13], v[154:157], v[178:181], v[10:13]
	v_mfma_f32_16x16x32_bf16 v[6:9], v[146:149], v[186:189], v[6:9]
	v_mfma_f32_16x16x32_bf16 v[2:5], v[154:157], v[186:189], v[2:5]
	v_mfma_f32_16x16x32_bf16 v[46:49], v[150:153], v[166:169], v[46:49]
	v_mfma_f32_16x16x32_bf16 v[42:45], v[158:161], v[166:169], v[42:45]
	v_mfma_f32_16x16x32_bf16 v[38:41], v[150:153], v[174:177], v[38:41]
	v_mfma_f32_16x16x32_bf16 v[34:37], v[158:161], v[174:177], v[34:37]
	v_mfma_f32_16x16x32_bf16 v[14:17], v[150:153], v[182:185], v[14:17]
	v_mfma_f32_16x16x32_bf16 v[10:13], v[158:161], v[182:185], v[10:13]
	v_mfma_f32_16x16x32_bf16 v[6:9], v[150:153], v[190:193], v[6:9]
	v_mfma_f32_16x16x32_bf16 v[2:5], v[158:161], v[190:193], v[2:5]
	s_setprio 0
	s_add_i32 s76, s76, 2
	s_add_u32 s22, s22, 0x100
	s_addc_u32 s23, s23, 0
	s_cmp_gt_u32 s76, 13
	s_barrier
	s_cbranch_scc1 .LBB0_1957

; #define PG8_STAGE(bufoff, gbase, voff) do { _Pragma("unroll") for (int _i = 0; _i < 2; ++_i) \
;         __builtin_amdgcn_global_load_lds((const unsigned*)((const char*)(gbase) + (voff)[_i]), (PG8_LAS unsigned*)(lds + (bufoff) + ldsw + _i * 8192), 16, 0, 0); } while (0)
; #define PG8_LDA(dst, b, h) do { _Pragma("unroll") for (int m = 0; m < 4; ++m) _Pragma("unroll") for (int k = 0; k < 2; ++k) dst[m][k] = *(const PG8_LAS bf16x8*)(lds + PG8_SA(b, h) + aoff + m * 2048 + k * 1024); } while (0)
; #define PG8_MMA(ai, bj, At, Bt) do { __builtin_amdgcn_s_setprio(1); _Pragma("unroll") for (int m = 0; m < 4; ++m) _Pragma("unroll") for (int n = 0; n < 2; ++n) _Pragma("unroll") for (int k = 0; k < 2; ++k) \
;         acc[ai][bj][m][n] = __builtin_amdgcn_mfma_f32_16x16x32_bf16(Bt[n][k], At[m][k], acc[ai][bj][m][n], 0, 0, 0); __builtin_amdgcn_s_setprio(0); } while (0)
; #define PG8_WAIT_V(n) asm volatile("s_waitcnt vmcnt(" #n ")" ::: "memory")
; #define PG8_WAIT_VN(n) asm volatile("s_waitcnt vmcnt(%0)" :: "n"(n) : "memory")
; #define PG8_WAIT_L(n) asm volatile("s_waitcnt lgkmcnt(" #n ")" ::: "memory")
; #define PG8_BAR __builtin_amdgcn_s_barrier()
; #define PG8_SCHED __builtin_amdgcn_sched_barrier(0)
; template <class Epi, class Sched, bool ALIGN_EPI = false, bool SP2 = false>
; __device__ __forceinline__ void gemm_phase(PG8_LAS unsigned char* lds, const Gemm g, const Sched& S, const Epi& E, const int wave_id) {
;     ...
;             const char* a1 = cA + (size_t)(t + 1) * kstep;
;             const char* a2 = last ? nA : cA + (size_t)(t + 2) * kstep; const char* b2 = last ? nB : cB + (size_t)(t + 2) * kstep;
;     ...
;             PG8_WAIT_VN(8 + Epi::NS); if (strict) PG8_WAIT_V(8); PG8_WAIT_L(0); PG8_BAR; PG8_MMA(0, 0, At, B0); PG8_MMA(0, 1, At, B1); PG8_BAR; PG8_SCHED;
;             PG8_LDA(At, 0, 1); PG8_STAGE(PG8_SB(0, 0), b2, voffB); PG8_STAGE(PG8_SB(0, 1), b2 + hstep, voffB); PG8_STAGE(PG8_SA(0, 0), a2, voffA);
;             PG8_WAIT_VN(8 + Epi::NS); if (strict) PG8_WAIT_V(8); PG8_WAIT_L(0); PG8_BAR; PG8_MMA(1, 0, At, B0); PG8_MMA(1, 1, At, B1); PG8_BAR; PG8_SCHED;
.LBB0_1955:
	s_add_u32 s24, s20, s22
	s_addc_u32 s25, s21, s23
	s_add_u32 s24, s24, 0x100
	s_addc_u32 s25, s25, 0
	s_add_u32 s53, s74, s22
	s_addc_u32 s78, s75, s23
	s_waitcnt lgkmcnt(0)
	s_cmpk_eq_i32 s22, 0x700
	s_cselect_b32 s27, s13, s25
	s_cselect_b32 s26, s68, s24
	s_cselect_b32 s25, s11, s78
	s_cselect_b32 s24, s69, s53
	s_barrier
	s_setprio 1
	s_waitcnt lgkmcnt(0)
	v_mfma_f32_16x16x32_bf16 v[126:129], v[146:149], v[186:189], v[126:129]
	v_mfma_f32_16x16x32_bf16 v[122:125], v[154:157], v[186:189], v[122:125]
	v_mfma_f32_16x16x32_bf16 v[118:121], v[146:149], v[178:181], v[118:121]
	v_mfma_f32_16x16x32_bf16 v[114:117], v[154:157], v[178:181], v[114:117]
	v_mfma_f32_16x16x32_bf16 v[94:97], v[146:149], v[170:173], v[94:97]
	v_mfma_f32_16x16x32_bf16 v[90:93], v[154:157], v[170:173], v[90:93]
	v_mfma_f32_16x16x32_bf16 v[86:89], v[146:149], v[162:165], v[86:89]
	v_mfma_f32_16x16x32_bf16 v[82:85], v[154:157], v[162:165], v[82:85]
	v_mfma_f32_16x16x32_bf16 v[126:129], v[150:153], v[190:193], v[126:129]
	v_mfma_f32_16x16x32_bf16 v[122:125], v[158:161], v[190:193], v[122:125]
	v_mfma_f32_16x16x32_bf16 v[118:121], v[150:153], v[182:185], v[118:121]
	v_mfma_f32_16x16x32_bf16 v[114:117], v[158:161], v[182:185], v[114:117]
	v_mfma_f32_16x16x32_bf16 v[94:97], v[150:153], v[174:177], v[94:97]
	v_mfma_f32_16x16x32_bf16 v[90:93], v[158:161], v[174:177], v[90:93]
	v_mfma_f32_16x16x32_bf16 v[86:89], v[150:153], v[166:169], v[86:89]
	v_mfma_f32_16x16x32_bf16 v[82:85], v[158:161], v[166:169], v[82:85]
	s_setprio 0
	s_setprio 1
	v_mfma_f32_16x16x32_bf16 v[110:113], v[130:133], v[186:189], v[110:113]
	v_mfma_f32_16x16x32_bf16 v[106:109], v[138:141], v[186:189], v[106:109]
	v_mfma_f32_16x16x32_bf16 v[102:105], v[130:133], v[178:181], v[102:105]
	v_mfma_f32_16x16x32_bf16 v[98:101], v[138:141], v[178:181], v[98:101]
	v_mfma_f32_16x16x32_bf16 v[78:81], v[130:133], v[170:173], v[78:81]
	v_mfma_f32_16x16x32_bf16 v[74:77], v[138:141], v[170:173], v[74:77]
	v_mfma_f32_16x16x32_bf16 v[70:73], v[130:133], v[162:165], v[70:73]
	v_mfma_f32_16x16x32_bf16 v[66:69], v[138:141], v[162:165], v[66:69]
	v_mfma_f32_16x16x32_bf16 v[110:113], v[134:137], v[190:193], v[110:113]
	v_mfma_f32_16x16x32_bf16 v[106:109], v[142:145], v[190:193], v[106:109]
	v_mfma_f32_16x16x32_bf16 v[102:105], v[134:137], v[182:185], v[102:105]
	v_mfma_f32_16x16x32_bf16 v[98:101], v[142:145], v[182:185], v[98:101]
	v_mfma_f32_16x16x32_bf16 v[78:81], v[134:137], v[174:177], v[78:81]
	v_mfma_f32_16x16x32_bf16 v[74:77], v[142:145], v[174:177], v[74:77]
	v_mfma_f32_16x16x32_bf16 v[70:73], v[134:137], v[166:169], v[70:73]
	v_mfma_f32_16x16x32_bf16 v[66:69], v[142:145], v[166:169], v[66:69]
	s_setprio 0
	s_barrier
	ds_read_b128 v[186:189], v247 offset:16384
	ds_read_b128 v[190:193], v247 offset:17408
	ds_read_b128 v[178:181], v247 offset:18432
	ds_read_b128 v[182:185], v247 offset:19456
	ds_read_b128 v[170:173], v247 offset:20480
	ds_read_b128 v[174:177], v247 offset:21504
	ds_read_b128 v[162:165], v247 offset:22528
	ds_read_b128 v[166:169], v247 offset:23552
	s_mov_b32 m0, s42
	v_lshl_add_u64 v[232:233], s[24:25], 0, v[214:215]
	s_add_u32 s90, s24, 0x40000
	global_load_lds_dwordx4 v[232:233], off
	v_lshl_add_u64 v[230:231], s[24:25], 0, v[210:211]
	s_mov_b32 m0, s43
	s_addc_u32 s91, s25, 0
	global_load_lds_dwordx4 v[230:231], off
	v_lshl_add_u64 v[194:195], s[90:91], 0, v[214:215]
	s_mov_b32 m0, s49
	v_lshl_add_u64 v[226:227], s[26:27], 0, v[216:217]
	global_load_lds_dwordx4 v[194:195], off
	v_lshl_add_u64 v[194:195], s[90:91], 0, v[210:211]
	s_mov_b32 m0, s50
	v_lshl_add_u64 v[228:229], s[26:27], 0, v[212:213]
	global_load_lds_dwordx4 v[194:195], off
	s_mov_b32 m0, s41
	s_andn2_b64 vcc, exec, s[28:29]
	global_load_lds_dwordx4 v[226:227], off
	s_mov_b32 m0, s51
	s_nop 0
	global_load_lds_dwordx4 v[228:229], off
	s_waitcnt vmcnt(16)
	s_cbranch_vccnz .LBB0_1952
	s_waitcnt vmcnt(8)
	s_branch .LBB0_1952

; #define PG8_STAGE(bufoff, gbase, voff) do { _Pragma("unroll") for (int _i = 0; _i < 2; ++_i) \
;         __builtin_amdgcn_global_load_lds((const unsigned*)((const char*)(gbase) + (voff)[_i]), (PG8_LAS unsigned*)(lds + (bufoff) + ldsw + _i * 8192), 16, 0, 0); } while (0)
; #define PG8_LDA(dst, b, h) do { _Pragma("unroll") for (int m = 0; m < 4; ++m) _Pragma("unroll") for (int k = 0; k < 2; ++k) dst[m][k] = *(const PG8_LAS bf16x8*)(lds + PG8_SA(b, h) + aoff + m * 2048 + k * 1024); } while (0)
; #define PG8_MMA(ai, bj, At, Bt) do { __builtin_amdgcn_s_setprio(1); _Pragma("unroll") for (int m = 0; m < 4; ++m) _Pragma("unroll") for (int n = 0; n < 2; ++n) _Pragma("unroll") for (int k = 0; k < 2; ++k) \
;         acc[ai][bj][m][n] = __builtin_amdgcn_mfma_f32_16x16x32_bf16(Bt[n][k], At[m][k], acc[ai][bj][m][n], 0, 0, 0); __builtin_amdgcn_s_setprio(0); } while (0)
; #define PG8_WAIT_V(n) asm volatile("s_waitcnt vmcnt(" #n ")" ::: "memory")
; #define PG8_WAIT_VN(n) asm volatile("s_waitcnt vmcnt(%0)" :: "n"(n) : "memory")
; #define PG8_WAIT_L(n) asm volatile("s_waitcnt lgkmcnt(" #n ")" ::: "memory")
; #define PG8_BAR __builtin_amdgcn_s_barrier()
; #define PG8_SCHED __builtin_amdgcn_sched_barrier(0)
; template <class Epi, class Sched, bool ALIGN_EPI = false, bool SP2 = false>
; __device__ __forceinline__ void gemm_phase(PG8_LAS unsigned char* lds, const Gemm g, const Sched& S, const Epi& E, const int wave_id) {
;     ...
;             const char* a1 = cA + (size_t)(t + 1) * kstep;
;             const char* a2 = last ? nA : cA + (size_t)(t + 2) * kstep; const char* b2 = last ? nB : cB + (size_t)(t + 2) * kstep;
;     ...
;             PG8_WAIT_VN(8 + Epi::NS); if (strict) PG8_WAIT_V(8); PG8_WAIT_L(0); PG8_BAR; PG8_MMA(0, 0, At, B0); PG8_MMA(0, 1, At, B1); PG8_BAR; PG8_SCHED;
;             PG8_LDA(At, 0, 1); PG8_STAGE(PG8_SB(0, 0), b2, voffB); PG8_STAGE(PG8_SB(0, 1), b2 + hstep, voffB); PG8_STAGE(PG8_SA(0, 0), a2, voffA);
;             PG8_WAIT_VN(8 + Epi::NS); if (strict) PG8_WAIT_V(8); PG8_WAIT_L(0); PG8_BAR; PG8_MMA(1, 0, At, B0); PG8_MMA(1, 1, At, B1); PG8_BAR; PG8_SCHED;
.LBB0_2033:
	s_add_u32 s16, s12, s14
	s_addc_u32 s17, s13, s15
	s_add_u32 s16, s16, 0x100
	s_addc_u32 s17, s17, 0
	s_add_u32 s53, s57, s14
	s_addc_u32 s67, s62, s15
	s_waitcnt lgkmcnt(0)
	s_cmpk_eq_i32 s14, 0x1500
	s_cselect_b32 s19, s9, s17
	s_cselect_b32 s18, s8, s16
	s_cselect_b32 s17, s11, s67
	s_cselect_b32 s16, s10, s53
	s_barrier
	s_setprio 1
	s_waitcnt lgkmcnt(0)
	v_mfma_f32_16x16x32_bf16 v[126:129], v[146:149], v[186:189], v[126:129]
	v_mfma_f32_16x16x32_bf16 v[122:125], v[154:157], v[186:189], v[122:125]
	v_mfma_f32_16x16x32_bf16 v[110:113], v[146:149], v[178:181], v[110:113]
	v_mfma_f32_16x16x32_bf16 v[106:109], v[154:157], v[178:181], v[106:109]
	v_mfma_f32_16x16x32_bf16 v[94:97], v[146:149], v[170:173], v[94:97]
	v_mfma_f32_16x16x32_bf16 v[90:93], v[154:157], v[170:173], v[90:93]
	v_mfma_f32_16x16x32_bf16 v[78:81], v[146:149], v[162:165], v[78:81]
	v_mfma_f32_16x16x32_bf16 v[74:77], v[154:157], v[162:165], v[74:77]
	v_mfma_f32_16x16x32_bf16 v[126:129], v[150:153], v[190:193], v[126:129]
	v_mfma_f32_16x16x32_bf16 v[122:125], v[158:161], v[190:193], v[122:125]
	v_mfma_f32_16x16x32_bf16 v[110:113], v[150:153], v[182:185], v[110:113]
	v_mfma_f32_16x16x32_bf16 v[106:109], v[158:161], v[182:185], v[106:109]
	v_mfma_f32_16x16x32_bf16 v[94:97], v[150:153], v[174:177], v[94:97]
	v_mfma_f32_16x16x32_bf16 v[90:93], v[158:161], v[174:177], v[90:93]
	v_mfma_f32_16x16x32_bf16 v[78:81], v[150:153], v[166:169], v[78:81]
	v_mfma_f32_16x16x32_bf16 v[74:77], v[158:161], v[166:169], v[74:77]
	s_setprio 0
	s_setprio 1
	v_mfma_f32_16x16x32_bf16 v[118:121], v[130:133], v[186:189], v[118:121]
	v_mfma_f32_16x16x32_bf16 v[114:117], v[138:141], v[186:189], v[114:117]
	v_mfma_f32_16x16x32_bf16 v[102:105], v[130:133], v[178:181], v[102:105]
	v_mfma_f32_16x16x32_bf16 v[98:101], v[138:141], v[178:181], v[98:101]
	v_mfma_f32_16x16x32_bf16 v[86:89], v[130:133], v[170:173], v[86:89]
	v_mfma_f32_16x16x32_bf16 v[82:85], v[138:141], v[170:173], v[82:85]
	v_mfma_f32_16x16x32_bf16 v[70:73], v[130:133], v[162:165], v[70:73]
	v_mfma_f32_16x16x32_bf16 v[66:69], v[138:141], v[162:165], v[66:69]
	v_mfma_f32_16x16x32_bf16 v[118:121], v[134:137], v[190:193], v[118:121]
	v_mfma_f32_16x16x32_bf16 v[114:117], v[142:145], v[190:193], v[114:117]
	v_mfma_f32_16x16x32_bf16 v[102:105], v[134:137], v[182:185], v[102:105]
	v_mfma_f32_16x16x32_bf16 v[98:101], v[142:145], v[182:185], v[98:101]
	v_mfma_f32_16x16x32_bf16 v[86:89], v[134:137], v[174:177], v[86:89]
	v_mfma_f32_16x16x32_bf16 v[82:85], v[142:145], v[174:177], v[82:85]
	v_mfma_f32_16x16x32_bf16 v[70:73], v[134:137], v[166:169], v[70:73]
	v_mfma_f32_16x16x32_bf16 v[66:69], v[142:145], v[166:169], v[66:69]
	s_setprio 0
	s_barrier
	ds_read_b128 v[186:189], v247 offset:16384
	ds_read_b128 v[190:193], v247 offset:17408
	ds_read_b128 v[178:181], v247 offset:18432
	ds_read_b128 v[182:185], v247 offset:19456
	ds_read_b128 v[170:173], v247 offset:20480
	ds_read_b128 v[174:177], v247 offset:21504
	ds_read_b128 v[162:165], v247 offset:22528
	ds_read_b128 v[166:169], v247 offset:23552
	s_mov_b32 m0, s34
	v_lshl_add_u64 v[232:233], s[16:17], 0, v[212:213]
	s_add_u32 s68, s16, 0xb0000
	global_load_lds_dwordx4 v[232:233], off
	v_lshl_add_u64 v[230:231], s[16:17], 0, v[216:217]
	s_mov_b32 m0, s35
	s_addc_u32 s69, s17, 0
	global_load_lds_dwordx4 v[230:231], off
	v_lshl_add_u64 v[194:195], s[68:69], 0, v[212:213]
	s_mov_b32 m0, s36
	v_lshl_add_u64 v[226:227], s[18:19], 0, v[210:211]
	global_load_lds_dwordx4 v[194:195], off
	v_lshl_add_u64 v[194:195], s[68:69], 0, v[216:217]
	s_mov_b32 m0, s37
	v_lshl_add_u64 v[228:229], s[18:19], 0, v[214:215]
	global_load_lds_dwordx4 v[194:195], off
	s_mov_b32 m0, s31
	s_andn2_b64 vcc, exec, s[20:21]
	global_load_lds_dwordx4 v[226:227], off
	s_mov_b32 m0, s38
	s_nop 0
	global_load_lds_dwordx4 v[228:229], off
	s_waitcnt vmcnt(24)
	s_cbranch_vccnz .LBB0_2030
	s_waitcnt vmcnt(8)
	s_branch .LBB0_2030
